# wave reductions without LDS: norm phases via v_permlane32/16_swap + DPP (row_ror, quad_perm), combine phases via DPP quad_perm + row_half_mirror (bit-identical partner values)
# baseline (speedup 1.0000x reference)
.LBB0_99:
	s_or_b64 exec, exec, s[8:9]
	s_waitcnt vmcnt(7)
	v_mov_b32_e32 v50, v37
	s_waitcnt vmcnt(6)
	v_mov_b32_e32 v51, v33
	v_mov_b32_e32 v48, v36
	v_mov_b32_e32 v49, v32
	v_pk_mul_f32 v[50:51], v[50:51], v[50:51]
	s_waitcnt vmcnt(5)
	v_mov_b32_e32 v52, v29
	v_pk_fma_f32 v[48:49], v[48:49], v[48:49], v[50:51]
	v_mov_b32_e32 v50, v38
	v_mov_b32_e32 v51, v34
	v_pk_fma_f32 v[48:49], v[50:51], v[50:51], v[48:49]
	v_mov_b32_e32 v50, v39
	v_mov_b32_e32 v51, v35
	s_waitcnt vmcnt(4)
	v_mov_b32_e32 v53, v25
	v_pk_fma_f32 v[48:49], v[50:51], v[50:51], v[48:49]
	v_mov_b32_e32 v50, v28
	v_mov_b32_e32 v51, v24
	v_pk_mul_f32 v[52:53], v[52:53], v[52:53]
	v_add_f32_e32 v48, v48, v49
	v_pk_fma_f32 v[50:51], v[50:51], v[50:51], v[52:53]
	v_mov_b32_e32 v52, v30
	v_mov_b32_e32 v53, v26
	v_pk_fma_f32 v[50:51], v[52:53], v[52:53], v[50:51]
	v_mov_b32_e32 v52, v31
	v_mov_b32_e32 v53, v27
	v_pk_fma_f32 v[50:51], v[52:53], v[52:53], v[50:51]
	v_ashrrev_i32_e32 v163, 31, v162
	v_add_f32_e32 v48, v48, v50
	v_add_f32_e32 v48, v48, v51
	v_mov_b32_e32 v49, v48
	v_lshlrev_b64 v[52:53], 11, v[162:163]
	v_lshl_add_u64 v[52:53], v[148:149], 0, v[52:53]
	s_nop 1
	v_permlane32_swap_b32_e32 v49, v48
	s_nop 1
	v_add_f32_e32 v48, v48, v49
	v_mov_b32_e32 v49, v48
	s_nop 1
	v_permlane16_swap_b32_e32 v49, v48
	s_nop 1
	v_add_f32_e32 v48, v48, v49
	s_nop 1
	v_add_f32_dpp v48, v48, v48 row_ror:8 row_mask:0xf bank_mask:0xf
	s_nop 1
	v_add_f32_dpp v48, v48, v48 row_ror:4 row_mask:0xf bank_mask:0xf
	s_nop 1
	v_add_f32_dpp v50, v48, v48 quad_perm:[2,3,0,1] row_mask:0xf bank_mask:0xf
	v_pk_add_f32 v[48:49], v[22:23], 1.0 op_sel_hi:[1,0]
	s_nop 1
	v_add_f32_dpp v50, v50, v50 quad_perm:[1,0,3,2] row_mask:0xf bank_mask:0xf
	v_fmamk_f32 v50, v50, 0x3a800000, v184
	v_mul_f32_e32 v51, 0x4b800000, v50
	v_cmp_gt_f32_e32 vcc, s14, v50
	s_nop 1
	v_cndmask_b32_e32 v50, v50, v51, vcc
	v_rsq_f32_e32 v54, v50
	v_pk_add_f32 v[50:51], v[20:21], 1.0 op_sel_hi:[1,0]
	v_mul_f32_e32 v55, 0x45800000, v54
	v_cndmask_b32_e32 v54, v54, v55, vcc
	v_pk_mul_f32 v[38:39], v[38:39], v[54:55] op_sel_hi:[1,0]
	v_pk_mul_f32 v[36:37], v[36:37], v[54:55] op_sel_hi:[1,0]
	v_pk_mul_f32 v[38:39], v[2:3], v[38:39]
	v_pk_mul_f32 v[36:37], v[0:1], v[36:37]
	v_pk_fma_f32 v[38:39], v[48:49], v[38:39], v[18:19]
	v_pk_fma_f32 v[36:37], v[50:51], v[36:37], v[16:17]
	v_pk_mul_f32 v[34:35], v[34:35], v[54:55] op_sel_hi:[1,0]
	v_cvt_pk_bf16_f32 v36, v36, v37
	v_cvt_pk_bf16_f32 v37, v38, v39
	v_pk_mul_f32 v[32:33], v[32:33], v[54:55] op_sel_hi:[1,0]
	global_store_dwordx2 v[52:53], v[36:37], off
	v_pk_mul_f32 v[32:33], v[4:5], v[32:33]
	v_pk_mul_f32 v[34:35], v[6:7], v[34:35]
	v_pk_add_f32 v[36:37], v[46:47], 1.0 op_sel_hi:[1,0]
	v_pk_add_f32 v[38:39], v[44:45], 1.0 op_sel_hi:[1,0]
	v_pk_fma_f32 v[34:35], v[36:37], v[34:35], v[42:43]
	v_pk_fma_f32 v[32:33], v[38:39], v[32:33], v[40:41]
	v_pk_mul_f32 v[30:31], v[30:31], v[54:55] op_sel_hi:[1,0]
	v_cvt_pk_bf16_f32 v32, v32, v33
	v_cvt_pk_bf16_f32 v33, v34, v35
	v_pk_mul_f32 v[28:29], v[28:29], v[54:55] op_sel_hi:[1,0]
	global_store_dwordx2 v[52:53], v[32:33], off offset:512
	v_pk_mul_f32 v[28:29], v[8:9], v[28:29]
	v_pk_mul_f32 v[30:31], v[10:11], v[30:31]
	v_pk_add_f32 v[32:33], v[70:71], 1.0 op_sel_hi:[1,0]
	v_pk_add_f32 v[34:35], v[68:69], 1.0 op_sel_hi:[1,0]
	v_pk_fma_f32 v[30:31], v[32:33], v[30:31], v[66:67]
	v_pk_fma_f32 v[28:29], v[34:35], v[28:29], v[64:65]
	v_pk_mul_f32 v[26:27], v[26:27], v[54:55] op_sel_hi:[1,0]
	v_cvt_pk_bf16_f32 v28, v28, v29
	v_cvt_pk_bf16_f32 v29, v30, v31
	v_pk_mul_f32 v[24:25], v[24:25], v[54:55] op_sel_hi:[1,0]
	global_store_dwordx2 v[52:53], v[28:29], off offset:1024
	v_pk_mul_f32 v[24:25], v[12:13], v[24:25]
	v_pk_mul_f32 v[26:27], v[14:15], v[26:27]
	v_pk_add_f32 v[28:29], v[94:95], 1.0 op_sel_hi:[1,0]
	v_pk_add_f32 v[30:31], v[92:93], 1.0 op_sel_hi:[1,0]
	v_pk_fma_f32 v[26:27], v[28:29], v[26:27], v[90:91]
	v_pk_fma_f32 v[24:25], v[30:31], v[24:25], v[88:89]
	s_nop 0
	v_cvt_pk_bf16_f32 v24, v24, v25
	v_cvt_pk_bf16_f32 v25, v26, v27
	global_store_dwordx2 v[52:53], v[24:25], off offset:1536

.LBB0_111:
	s_or_b64 exec, exec, s[6:7]
	s_waitcnt vmcnt(23)
	v_mov_b32_e32 v174, v141
	s_waitcnt vmcnt(22)
	v_mov_b32_e32 v175, v137
	v_mov_b32_e32 v172, v140
	v_mov_b32_e32 v173, v136
	v_pk_mul_f32 v[174:175], v[174:175], v[174:175]
	s_waitcnt vmcnt(21)
	v_mov_b32_e32 v186, v133
	v_pk_fma_f32 v[172:173], v[172:173], v[172:173], v[174:175]
	v_mov_b32_e32 v174, v142
	v_mov_b32_e32 v175, v138
	v_pk_fma_f32 v[172:173], v[174:175], v[174:175], v[172:173]
	v_mov_b32_e32 v174, v143
	v_mov_b32_e32 v175, v139
	s_waitcnt vmcnt(20)
	v_mov_b32_e32 v187, v129
	v_pk_fma_f32 v[172:173], v[174:175], v[174:175], v[172:173]
	v_mov_b32_e32 v174, v132
	v_mov_b32_e32 v175, v128
	v_pk_mul_f32 v[186:187], v[186:187], v[186:187]
	v_add_f32_e32 v145, v172, v173
	v_pk_fma_f32 v[174:175], v[174:175], v[174:175], v[186:187]
	v_mov_b32_e32 v186, v134
	v_mov_b32_e32 v187, v130
	v_pk_fma_f32 v[174:175], v[186:187], v[186:187], v[174:175]
	v_mov_b32_e32 v186, v135
	v_mov_b32_e32 v187, v131
	v_pk_fma_f32 v[174:175], v[186:187], v[186:187], v[174:175]
	v_pk_add_f32 v[172:173], v[22:23], 1.0 op_sel_hi:[1,0]
	v_add_f32_e32 v145, v145, v174
	v_add_f32_e32 v145, v145, v175
	v_mov_b32_e32 v163, v145
	v_pk_add_f32 v[174:175], v[20:21], 1.0 op_sel_hi:[1,0]
	s_nop 1
	v_permlane32_swap_b32_e32 v163, v145
	s_nop 1
	v_add_f32_e32 v145, v145, v163
	v_mov_b32_e32 v163, v145
	s_nop 1
	v_permlane16_swap_b32_e32 v163, v145
	s_nop 1
	v_add_f32_e32 v145, v145, v163
	s_nop 1
	v_add_f32_dpp v145, v145, v145 row_ror:8 row_mask:0xf bank_mask:0xf
	s_nop 1
	v_add_f32_dpp v145, v145, v145 row_ror:4 row_mask:0xf bank_mask:0xf
	s_nop 1
	v_add_f32_dpp v163, v145, v145 quad_perm:[2,3,0,1] row_mask:0xf bank_mask:0xf
	v_ashrrev_i32_e32 v145, 31, v144
	v_lshlrev_b64 v[186:187], 11, v[144:145]
	v_lshl_add_u64 v[186:187], v[148:149], 0, v[186:187]
	s_nop 1
	v_add_f32_dpp v163, v163, v163 quad_perm:[1,0,3,2] row_mask:0xf bank_mask:0xf
	v_fmamk_f32 v163, v163, 0x3a800000, v184
	v_mul_f32_e32 v165, 0x4b800000, v163
	v_cmp_gt_f32_e32 vcc, s14, v163
	s_nop 1
	v_cndmask_b32_e32 v163, v163, v165, vcc
	v_rsq_f32_e32 v163, v163
	s_nop 0
	v_mul_f32_e32 v145, 0x45800000, v163
	v_cndmask_b32_e32 v188, v163, v145, vcc
	v_pk_mul_f32 v[142:143], v[142:143], v[188:189] op_sel_hi:[1,0]
	v_pk_mul_f32 v[140:141], v[140:141], v[188:189] op_sel_hi:[1,0]
	v_pk_mul_f32 v[142:143], v[2:3], v[142:143]
	v_pk_mul_f32 v[140:141], v[0:1], v[140:141]
	v_pk_fma_f32 v[142:143], v[172:173], v[142:143], v[18:19]
	v_pk_fma_f32 v[140:141], v[174:175], v[140:141], v[16:17]
	v_pk_mul_f32 v[138:139], v[138:139], v[188:189] op_sel_hi:[1,0]
	v_cvt_pk_bf16_f32 v140, v140, v141
	v_cvt_pk_bf16_f32 v141, v142, v143
	v_pk_mul_f32 v[136:137], v[136:137], v[188:189] op_sel_hi:[1,0]
	global_store_dwordx2 v[186:187], v[140:141], off
	v_pk_mul_f32 v[140:141], v[4:5], v[136:137]
	v_pk_mul_f32 v[142:143], v[6:7], v[138:139]
	v_pk_add_f32 v[136:137], v[46:47], 1.0 op_sel_hi:[1,0]
	v_pk_add_f32 v[138:139], v[44:45], 1.0 op_sel_hi:[1,0]
	v_pk_fma_f32 v[142:143], v[136:137], v[142:143], v[42:43]
	v_pk_fma_f32 v[140:141], v[138:139], v[140:141], v[40:41]
	v_pk_mul_f32 v[134:135], v[134:135], v[188:189] op_sel_hi:[1,0]
	v_cvt_pk_bf16_f32 v140, v140, v141
	v_cvt_pk_bf16_f32 v141, v142, v143
	v_pk_mul_f32 v[132:133], v[132:133], v[188:189] op_sel_hi:[1,0]
	global_store_dwordx2 v[186:187], v[140:141], off offset:512
	v_pk_mul_f32 v[140:141], v[8:9], v[132:133]
	v_pk_mul_f32 v[142:143], v[10:11], v[134:135]
	v_pk_add_f32 v[132:133], v[70:71], 1.0 op_sel_hi:[1,0]
	v_pk_add_f32 v[134:135], v[68:69], 1.0 op_sel_hi:[1,0]
	v_pk_fma_f32 v[142:143], v[132:133], v[142:143], v[66:67]
	v_pk_fma_f32 v[140:141], v[134:135], v[140:141], v[64:65]
	v_pk_mul_f32 v[130:131], v[130:131], v[188:189] op_sel_hi:[1,0]
	v_cvt_pk_bf16_f32 v140, v140, v141
	v_cvt_pk_bf16_f32 v141, v142, v143
	v_pk_mul_f32 v[128:129], v[128:129], v[188:189] op_sel_hi:[1,0]
	global_store_dwordx2 v[186:187], v[140:141], off offset:1024
	v_pk_mul_f32 v[140:141], v[12:13], v[128:129]
	v_pk_mul_f32 v[142:143], v[14:15], v[130:131]
	v_pk_add_f32 v[128:129], v[94:95], 1.0 op_sel_hi:[1,0]
	v_pk_add_f32 v[130:131], v[92:93], 1.0 op_sel_hi:[1,0]
	v_pk_fma_f32 v[142:143], v[128:129], v[142:143], v[90:91]
	v_pk_fma_f32 v[140:141], v[130:131], v[140:141], v[88:89]
	v_cmp_lt_i32_e32 vcc, v170, v176
	v_cvt_pk_bf16_f32 v140, v140, v141
	v_cvt_pk_bf16_f32 v141, v142, v143
	global_store_dwordx2 v[186:187], v[140:141], off offset:1536
	s_and_saveexec_b64 s[6:7], vcc
	s_cbranch_execz .LBB0_136
	v_add_u32_e32 v140, 0xffffe001, v144
	v_ashrrev_i32_e32 v140, 10, v140
	v_add_u32_e32 v140, 1, v140
	v_cmp_lt_i32_e32 vcc, s15, v144
	s_nop 1
	v_cndmask_b32_e32 v140, 0, v140, vcc
	v_cmp_ne_u32_e32 vcc, v140, v185
	s_and_saveexec_b64 s[8:9], vcc
	s_cbranch_execz .LBB0_122
	global_load_dwordx4 v[16:19], v[150:151], off
	global_load_dwordx4 v[20:23], v[152:153], off
	v_mad_i64_i32 v[128:129], s[10:11], v140, s3, v[160:161]
	s_mov_b64 s[10:11], 0

.LBB0_122:
	s_or_b64 exec, exec, s[8:9]
	s_waitcnt vmcnt(23)
	v_mov_b32_e32 v142, v125
	s_waitcnt vmcnt(22)
	v_mov_b32_e32 v143, v121
	v_mov_b32_e32 v140, v124
	v_mov_b32_e32 v141, v120
	v_pk_mul_f32 v[142:143], v[142:143], v[142:143]
	s_waitcnt vmcnt(21)
	v_mov_b32_e32 v186, v117
	v_pk_fma_f32 v[140:141], v[140:141], v[140:141], v[142:143]
	v_mov_b32_e32 v142, v126
	v_mov_b32_e32 v143, v122
	v_pk_fma_f32 v[140:141], v[142:143], v[142:143], v[140:141]
	v_mov_b32_e32 v142, v127
	v_mov_b32_e32 v143, v123
	s_waitcnt vmcnt(20)
	v_mov_b32_e32 v187, v113
	v_pk_fma_f32 v[140:141], v[142:143], v[142:143], v[140:141]
	v_mov_b32_e32 v142, v116
	v_mov_b32_e32 v143, v112
	v_pk_mul_f32 v[186:187], v[186:187], v[186:187]
	v_add_f32_e32 v140, v140, v141
	v_pk_fma_f32 v[142:143], v[142:143], v[142:143], v[186:187]
	v_mov_b32_e32 v186, v118
	v_mov_b32_e32 v187, v114
	v_pk_fma_f32 v[142:143], v[186:187], v[186:187], v[142:143]
	v_mov_b32_e32 v186, v119
	v_mov_b32_e32 v187, v115
	v_pk_fma_f32 v[142:143], v[186:187], v[186:187], v[142:143]
	v_ashrrev_i32_e32 v171, 31, v170
	v_add_f32_e32 v140, v140, v142
	v_add_f32_e32 v140, v140, v143
	v_mov_b32_e32 v141, v140
	s_nop 1
	v_permlane32_swap_b32_e32 v141, v140
	s_nop 1
	v_add_f32_e32 v140, v140, v141
	v_mov_b32_e32 v141, v140
	s_nop 1
	v_permlane16_swap_b32_e32 v141, v140
	s_nop 1
	v_add_f32_e32 v140, v140, v141
	s_nop 1
	v_add_f32_dpp v140, v140, v140 row_ror:8 row_mask:0xf bank_mask:0xf
	s_nop 1
	v_add_f32_dpp v140, v140, v140 row_ror:4 row_mask:0xf bank_mask:0xf
	s_nop 1
	v_add_f32_dpp v140, v140, v140 quad_perm:[2,3,0,1] row_mask:0xf bank_mask:0xf
	s_nop 1
	v_add_f32_dpp v140, v140, v140 quad_perm:[1,0,3,2] row_mask:0xf bank_mask:0xf
	v_fmamk_f32 v140, v140, 0x3a800000, v184
	v_mul_f32_e32 v141, 0x4b800000, v140
	v_cmp_gt_f32_e32 vcc, s14, v140
	s_nop 1
	v_cndmask_b32_e32 v140, v140, v141, vcc
	v_rsq_f32_e32 v142, v140
	v_lshlrev_b64 v[140:141], 11, v[170:171]
	v_lshl_add_u64 v[140:141], v[148:149], 0, v[140:141]
	v_mul_f32_e32 v143, 0x45800000, v142
	v_cndmask_b32_e32 v142, v142, v143, vcc
	v_pk_mul_f32 v[126:127], v[126:127], v[142:143] op_sel_hi:[1,0]
	v_pk_mul_f32 v[124:125], v[124:125], v[142:143] op_sel_hi:[1,0]
	v_pk_mul_f32 v[122:123], v[122:123], v[142:143] op_sel_hi:[1,0]
	v_pk_mul_f32 v[120:121], v[120:121], v[142:143] op_sel_hi:[1,0]
	v_pk_mul_f32 v[118:119], v[118:119], v[142:143] op_sel_hi:[1,0]
	v_pk_mul_f32 v[116:117], v[116:117], v[142:143] op_sel_hi:[1,0]
	v_pk_mul_f32 v[114:115], v[114:115], v[142:143] op_sel_hi:[1,0]
	v_pk_mul_f32 v[112:113], v[112:113], v[142:143] op_sel_hi:[1,0]
	v_pk_mul_f32 v[124:125], v[0:1], v[124:125]
	v_pk_mul_f32 v[126:127], v[2:3], v[126:127]
	v_pk_mul_f32 v[120:121], v[4:5], v[120:121]
	v_pk_mul_f32 v[122:123], v[6:7], v[122:123]
	v_pk_mul_f32 v[116:117], v[8:9], v[116:117]
	v_pk_mul_f32 v[118:119], v[10:11], v[118:119]
	v_pk_mul_f32 v[112:113], v[12:13], v[112:113]
	v_pk_mul_f32 v[114:115], v[14:15], v[114:115]
	v_pk_fma_f32 v[126:127], v[172:173], v[126:127], v[18:19]
	v_pk_fma_f32 v[124:125], v[174:175], v[124:125], v[16:17]
	v_pk_fma_f32 v[122:123], v[136:137], v[122:123], v[42:43]
	v_pk_fma_f32 v[120:121], v[138:139], v[120:121], v[40:41]
	v_pk_fma_f32 v[118:119], v[132:133], v[118:119], v[66:67]
	v_pk_fma_f32 v[116:117], v[134:135], v[116:117], v[64:65]
	v_pk_fma_f32 v[114:115], v[128:129], v[114:115], v[90:91]
	v_pk_fma_f32 v[112:113], v[130:131], v[112:113], v[88:89]
	v_cvt_pk_bf16_f32 v124, v124, v125
	v_cvt_pk_bf16_f32 v125, v126, v127
	v_cvt_pk_bf16_f32 v120, v120, v121
	v_cvt_pk_bf16_f32 v121, v122, v123
	v_cvt_pk_bf16_f32 v116, v116, v117
	v_cvt_pk_bf16_f32 v117, v118, v119
	v_cvt_pk_bf16_f32 v112, v112, v113
	v_cvt_pk_bf16_f32 v113, v114, v115
	global_store_dwordx2 v[140:141], v[124:125], off
	global_store_dwordx2 v[140:141], v[120:121], off offset:512
	global_store_dwordx2 v[140:141], v[116:117], off offset:1024
	global_store_dwordx2 v[140:141], v[112:113], off offset:1536
	s_or_b64 exec, exec, s[6:7]
	v_cmp_lt_i32_e32 vcc, v168, v176
	s_and_saveexec_b64 s[6:7], vcc
	s_cbranch_execnz .LBB0_137

.LBB0_134:
	s_or_b64 exec, exec, s[8:9]
	s_waitcnt vmcnt(15)
	v_mov_b32_e32 v98, v85
	s_waitcnt vmcnt(14)
	v_mov_b32_e32 v99, v81
	v_mov_b32_e32 v96, v84
	v_mov_b32_e32 v97, v80
	v_pk_mul_f32 v[98:99], v[98:99], v[98:99]
	s_waitcnt vmcnt(13)
	v_mov_b32_e32 v100, v77
	v_pk_fma_f32 v[96:97], v[96:97], v[96:97], v[98:99]
	v_mov_b32_e32 v98, v86
	v_mov_b32_e32 v99, v82
	v_pk_fma_f32 v[96:97], v[98:99], v[98:99], v[96:97]
	v_mov_b32_e32 v98, v87
	v_mov_b32_e32 v99, v83
	s_waitcnt vmcnt(12)
	v_mov_b32_e32 v101, v73
	v_pk_fma_f32 v[96:97], v[98:99], v[98:99], v[96:97]
	v_mov_b32_e32 v98, v76
	v_mov_b32_e32 v99, v72
	v_pk_mul_f32 v[100:101], v[100:101], v[100:101]
	v_add_f32_e32 v96, v96, v97
	v_pk_fma_f32 v[98:99], v[98:99], v[98:99], v[100:101]
	v_mov_b32_e32 v100, v78
	v_mov_b32_e32 v101, v74
	v_pk_fma_f32 v[98:99], v[100:101], v[100:101], v[98:99]
	v_mov_b32_e32 v100, v79
	v_mov_b32_e32 v101, v75
	v_pk_fma_f32 v[98:99], v[100:101], v[100:101], v[98:99]
	v_ashrrev_i32_e32 v167, 31, v166
	v_add_f32_e32 v96, v96, v98
	v_add_f32_e32 v96, v96, v99
	v_mov_b32_e32 v97, v96
	v_lshlrev_b64 v[100:101], 11, v[166:167]
	v_lshl_add_u64 v[100:101], v[148:149], 0, v[100:101]
	s_nop 1
	v_permlane32_swap_b32_e32 v97, v96
	s_nop 1
	v_add_f32_e32 v96, v96, v97
	v_mov_b32_e32 v97, v96
	s_nop 1
	v_permlane16_swap_b32_e32 v97, v96
	s_nop 1
	v_add_f32_e32 v96, v96, v97
	s_nop 1
	v_add_f32_dpp v96, v96, v96 row_ror:8 row_mask:0xf bank_mask:0xf
	s_nop 1
	v_add_f32_dpp v96, v96, v96 row_ror:4 row_mask:0xf bank_mask:0xf
	s_nop 1
	v_add_f32_dpp v98, v96, v96 quad_perm:[2,3,0,1] row_mask:0xf bank_mask:0xf
	v_pk_add_f32 v[96:97], v[22:23], 1.0 op_sel_hi:[1,0]
	s_nop 1
	v_add_f32_dpp v98, v98, v98 quad_perm:[1,0,3,2] row_mask:0xf bank_mask:0xf
	v_fmamk_f32 v98, v98, 0x3a800000, v184
	v_mul_f32_e32 v99, 0x4b800000, v98
	v_cmp_gt_f32_e32 vcc, s14, v98
	s_nop 1
	v_cndmask_b32_e32 v98, v98, v99, vcc
	v_rsq_f32_e32 v102, v98
	v_pk_add_f32 v[98:99], v[20:21], 1.0 op_sel_hi:[1,0]
	v_mul_f32_e32 v103, 0x45800000, v102
	v_cndmask_b32_e32 v102, v102, v103, vcc
	v_pk_mul_f32 v[86:87], v[86:87], v[102:103] op_sel_hi:[1,0]
	v_pk_mul_f32 v[84:85], v[84:85], v[102:103] op_sel_hi:[1,0]
	v_pk_mul_f32 v[86:87], v[2:3], v[86:87]
	v_pk_mul_f32 v[84:85], v[0:1], v[84:85]
	v_pk_fma_f32 v[86:87], v[96:97], v[86:87], v[18:19]
	v_pk_fma_f32 v[84:85], v[98:99], v[84:85], v[16:17]
	v_pk_mul_f32 v[82:83], v[82:83], v[102:103] op_sel_hi:[1,0]
	v_cvt_pk_bf16_f32 v84, v84, v85
	v_cvt_pk_bf16_f32 v85, v86, v87
	v_pk_mul_f32 v[80:81], v[80:81], v[102:103] op_sel_hi:[1,0]
	global_store_dwordx2 v[100:101], v[84:85], off
	v_pk_mul_f32 v[80:81], v[4:5], v[80:81]
	v_pk_mul_f32 v[82:83], v[6:7], v[82:83]
	v_pk_add_f32 v[84:85], v[46:47], 1.0 op_sel_hi:[1,0]
	v_pk_add_f32 v[86:87], v[44:45], 1.0 op_sel_hi:[1,0]
	v_pk_fma_f32 v[82:83], v[84:85], v[82:83], v[42:43]
	v_pk_fma_f32 v[80:81], v[86:87], v[80:81], v[40:41]
	v_pk_mul_f32 v[78:79], v[78:79], v[102:103] op_sel_hi:[1,0]
	v_cvt_pk_bf16_f32 v80, v80, v81
	v_cvt_pk_bf16_f32 v81, v82, v83
	v_pk_mul_f32 v[76:77], v[76:77], v[102:103] op_sel_hi:[1,0]
	global_store_dwordx2 v[100:101], v[80:81], off offset:512
	v_pk_mul_f32 v[76:77], v[8:9], v[76:77]
	v_pk_mul_f32 v[78:79], v[10:11], v[78:79]
	v_pk_add_f32 v[80:81], v[70:71], 1.0 op_sel_hi:[1,0]
	v_pk_add_f32 v[82:83], v[68:69], 1.0 op_sel_hi:[1,0]
	v_pk_fma_f32 v[78:79], v[80:81], v[78:79], v[66:67]
	v_pk_fma_f32 v[76:77], v[82:83], v[76:77], v[64:65]
	v_pk_mul_f32 v[74:75], v[74:75], v[102:103] op_sel_hi:[1,0]
	v_cvt_pk_bf16_f32 v76, v76, v77
	v_cvt_pk_bf16_f32 v77, v78, v79
	v_pk_mul_f32 v[72:73], v[72:73], v[102:103] op_sel_hi:[1,0]
	global_store_dwordx2 v[100:101], v[76:77], off offset:1024
	v_pk_mul_f32 v[72:73], v[12:13], v[72:73]
	v_pk_mul_f32 v[74:75], v[14:15], v[74:75]
	v_pk_add_f32 v[76:77], v[94:95], 1.0 op_sel_hi:[1,0]
	v_pk_add_f32 v[78:79], v[92:93], 1.0 op_sel_hi:[1,0]
	v_pk_fma_f32 v[74:75], v[76:77], v[74:75], v[90:91]
	v_pk_fma_f32 v[72:73], v[78:79], v[72:73], v[88:89]
	s_nop 0
	v_cvt_pk_bf16_f32 v72, v72, v73
	v_cvt_pk_bf16_f32 v73, v74, v75
	global_store_dwordx2 v[100:101], v[72:73], off offset:1536
	s_or_b64 exec, exec, s[6:7]
	v_cmp_lt_i32_e32 vcc, v164, v176
	s_and_saveexec_b64 s[6:7], vcc
	s_cbranch_execnz .LBB0_149

.LBB0_147:
	s_or_b64 exec, exec, s[8:9]
	s_waitcnt vmcnt(19)
	v_mov_b32_e32 v114, v109
	s_waitcnt vmcnt(18)
	v_mov_b32_e32 v115, v105
	v_mov_b32_e32 v112, v108
	v_mov_b32_e32 v113, v104
	v_pk_mul_f32 v[114:115], v[114:115], v[114:115]
	s_waitcnt vmcnt(17)
	v_mov_b32_e32 v116, v101
	v_pk_fma_f32 v[112:113], v[112:113], v[112:113], v[114:115]
	v_mov_b32_e32 v114, v110
	v_mov_b32_e32 v115, v106
	v_pk_fma_f32 v[112:113], v[114:115], v[114:115], v[112:113]
	v_mov_b32_e32 v114, v111
	v_mov_b32_e32 v115, v107
	s_waitcnt vmcnt(16)
	v_mov_b32_e32 v117, v97
	v_pk_fma_f32 v[112:113], v[114:115], v[114:115], v[112:113]
	v_mov_b32_e32 v114, v100
	v_mov_b32_e32 v115, v96
	v_pk_mul_f32 v[116:117], v[116:117], v[116:117]
	v_add_f32_e32 v112, v112, v113
	v_pk_fma_f32 v[114:115], v[114:115], v[114:115], v[116:117]
	v_mov_b32_e32 v116, v102
	v_mov_b32_e32 v117, v98
	v_pk_fma_f32 v[114:115], v[116:117], v[116:117], v[114:115]
	v_mov_b32_e32 v116, v103
	v_mov_b32_e32 v117, v99
	v_pk_fma_f32 v[114:115], v[116:117], v[116:117], v[114:115]
	v_ashrrev_i32_e32 v169, 31, v168
	v_add_f32_e32 v112, v112, v114
	v_add_f32_e32 v112, v112, v115
	v_mov_b32_e32 v113, v112
	v_lshlrev_b64 v[116:117], 11, v[168:169]
	v_lshl_add_u64 v[116:117], v[148:149], 0, v[116:117]
	s_nop 1
	v_permlane32_swap_b32_e32 v113, v112
	s_nop 1
	v_add_f32_e32 v112, v112, v113
	v_mov_b32_e32 v113, v112
	s_nop 1
	v_permlane16_swap_b32_e32 v113, v112
	s_nop 1
	v_add_f32_e32 v112, v112, v113
	s_nop 1
	v_add_f32_dpp v112, v112, v112 row_ror:8 row_mask:0xf bank_mask:0xf
	s_nop 1
	v_add_f32_dpp v112, v112, v112 row_ror:4 row_mask:0xf bank_mask:0xf
	s_nop 1
	v_add_f32_dpp v114, v112, v112 quad_perm:[2,3,0,1] row_mask:0xf bank_mask:0xf
	v_pk_add_f32 v[112:113], v[22:23], 1.0 op_sel_hi:[1,0]
	s_nop 1
	v_add_f32_dpp v114, v114, v114 quad_perm:[1,0,3,2] row_mask:0xf bank_mask:0xf
	v_fmamk_f32 v114, v114, 0x3a800000, v184
	v_mul_f32_e32 v115, 0x4b800000, v114
	v_cmp_gt_f32_e32 vcc, s14, v114
	s_nop 1
	v_cndmask_b32_e32 v114, v114, v115, vcc
	v_rsq_f32_e32 v118, v114
	v_pk_add_f32 v[114:115], v[20:21], 1.0 op_sel_hi:[1,0]
	v_mul_f32_e32 v119, 0x45800000, v118
	v_cndmask_b32_e32 v118, v118, v119, vcc
	v_pk_mul_f32 v[110:111], v[110:111], v[118:119] op_sel_hi:[1,0]
	v_pk_mul_f32 v[108:109], v[108:109], v[118:119] op_sel_hi:[1,0]
	v_pk_mul_f32 v[110:111], v[2:3], v[110:111]
	v_pk_mul_f32 v[108:109], v[0:1], v[108:109]
	v_pk_fma_f32 v[110:111], v[112:113], v[110:111], v[18:19]
	v_pk_fma_f32 v[108:109], v[114:115], v[108:109], v[16:17]
	v_pk_mul_f32 v[106:107], v[106:107], v[118:119] op_sel_hi:[1,0]
	v_cvt_pk_bf16_f32 v108, v108, v109
	v_cvt_pk_bf16_f32 v109, v110, v111
	v_pk_mul_f32 v[104:105], v[104:105], v[118:119] op_sel_hi:[1,0]
	global_store_dwordx2 v[116:117], v[108:109], off
	v_pk_mul_f32 v[104:105], v[4:5], v[104:105]
	v_pk_mul_f32 v[106:107], v[6:7], v[106:107]
	v_pk_add_f32 v[108:109], v[46:47], 1.0 op_sel_hi:[1,0]
	v_pk_add_f32 v[110:111], v[44:45], 1.0 op_sel_hi:[1,0]
	v_pk_fma_f32 v[106:107], v[108:109], v[106:107], v[42:43]
	v_pk_fma_f32 v[104:105], v[110:111], v[104:105], v[40:41]
	v_pk_mul_f32 v[102:103], v[102:103], v[118:119] op_sel_hi:[1,0]
	v_cvt_pk_bf16_f32 v104, v104, v105
	v_cvt_pk_bf16_f32 v105, v106, v107
	v_pk_mul_f32 v[100:101], v[100:101], v[118:119] op_sel_hi:[1,0]
	global_store_dwordx2 v[116:117], v[104:105], off offset:512
	v_pk_mul_f32 v[100:101], v[8:9], v[100:101]
	v_pk_mul_f32 v[102:103], v[10:11], v[102:103]
	v_pk_add_f32 v[104:105], v[70:71], 1.0 op_sel_hi:[1,0]
	v_pk_add_f32 v[106:107], v[68:69], 1.0 op_sel_hi:[1,0]
	v_pk_fma_f32 v[102:103], v[104:105], v[102:103], v[66:67]
	v_pk_fma_f32 v[100:101], v[106:107], v[100:101], v[64:65]
	v_pk_mul_f32 v[98:99], v[98:99], v[118:119] op_sel_hi:[1,0]
	v_cvt_pk_bf16_f32 v100, v100, v101
	v_cvt_pk_bf16_f32 v101, v102, v103
	v_pk_mul_f32 v[96:97], v[96:97], v[118:119] op_sel_hi:[1,0]
	global_store_dwordx2 v[116:117], v[100:101], off offset:1024
	v_pk_mul_f32 v[96:97], v[12:13], v[96:97]
	v_pk_mul_f32 v[98:99], v[14:15], v[98:99]
	v_pk_add_f32 v[100:101], v[94:95], 1.0 op_sel_hi:[1,0]
	v_pk_add_f32 v[102:103], v[92:93], 1.0 op_sel_hi:[1,0]
	v_pk_fma_f32 v[98:99], v[100:101], v[98:99], v[90:91]
	v_pk_fma_f32 v[96:97], v[102:103], v[96:97], v[88:89]
	s_nop 0
	v_cvt_pk_bf16_f32 v96, v96, v97
	v_cvt_pk_bf16_f32 v97, v98, v99
	global_store_dwordx2 v[116:117], v[96:97], off offset:1536
	s_or_b64 exec, exec, s[6:7]
	v_cmp_lt_i32_e32 vcc, v166, v176
	s_and_saveexec_b64 s[6:7], vcc
	s_cbranch_execnz .LBB0_124

.LBB0_159:
	s_or_b64 exec, exec, s[8:9]
	s_waitcnt vmcnt(11)
	v_mov_b32_e32 v74, v61
	s_waitcnt vmcnt(10)
	v_mov_b32_e32 v75, v57
	v_mov_b32_e32 v72, v60
	v_mov_b32_e32 v73, v56
	v_pk_mul_f32 v[74:75], v[74:75], v[74:75]
	s_waitcnt vmcnt(9)
	v_mov_b32_e32 v76, v53
	v_pk_fma_f32 v[72:73], v[72:73], v[72:73], v[74:75]
	v_mov_b32_e32 v74, v62
	v_mov_b32_e32 v75, v58
	v_pk_fma_f32 v[72:73], v[74:75], v[74:75], v[72:73]
	v_mov_b32_e32 v74, v63
	v_mov_b32_e32 v75, v59
	s_waitcnt vmcnt(8)
	v_mov_b32_e32 v77, v49
	v_pk_fma_f32 v[72:73], v[74:75], v[74:75], v[72:73]
	v_mov_b32_e32 v74, v52
	v_mov_b32_e32 v75, v48
	v_pk_mul_f32 v[76:77], v[76:77], v[76:77]
	v_add_f32_e32 v72, v72, v73
	v_pk_fma_f32 v[74:75], v[74:75], v[74:75], v[76:77]
	v_mov_b32_e32 v76, v54
	v_mov_b32_e32 v77, v50
	v_pk_fma_f32 v[74:75], v[76:77], v[76:77], v[74:75]
	v_mov_b32_e32 v76, v55
	v_mov_b32_e32 v77, v51
	v_pk_fma_f32 v[74:75], v[76:77], v[76:77], v[74:75]
	v_ashrrev_i32_e32 v165, 31, v164
	v_add_f32_e32 v72, v72, v74
	v_add_f32_e32 v72, v72, v75
	v_mov_b32_e32 v73, v72
	v_lshlrev_b64 v[76:77], 11, v[164:165]
	v_lshl_add_u64 v[76:77], v[148:149], 0, v[76:77]
	s_nop 1
	v_permlane32_swap_b32_e32 v73, v72
	s_nop 1
	v_add_f32_e32 v72, v72, v73
	v_mov_b32_e32 v73, v72
	s_nop 1
	v_permlane16_swap_b32_e32 v73, v72
	s_nop 1
	v_add_f32_e32 v72, v72, v73
	s_nop 1
	v_add_f32_dpp v72, v72, v72 row_ror:8 row_mask:0xf bank_mask:0xf
	s_nop 1
	v_add_f32_dpp v72, v72, v72 row_ror:4 row_mask:0xf bank_mask:0xf
	s_nop 1
	v_add_f32_dpp v74, v72, v72 quad_perm:[2,3,0,1] row_mask:0xf bank_mask:0xf
	v_pk_add_f32 v[72:73], v[22:23], 1.0 op_sel_hi:[1,0]
	s_nop 1
	v_add_f32_dpp v74, v74, v74 quad_perm:[1,0,3,2] row_mask:0xf bank_mask:0xf
	v_fmamk_f32 v74, v74, 0x3a800000, v184
	v_mul_f32_e32 v75, 0x4b800000, v74
	v_cmp_gt_f32_e32 vcc, s14, v74
	s_nop 1
	v_cndmask_b32_e32 v74, v74, v75, vcc
	v_rsq_f32_e32 v78, v74
	v_pk_add_f32 v[74:75], v[20:21], 1.0 op_sel_hi:[1,0]
	v_mul_f32_e32 v79, 0x45800000, v78
	v_cndmask_b32_e32 v78, v78, v79, vcc
	v_pk_mul_f32 v[62:63], v[62:63], v[78:79] op_sel_hi:[1,0]
	v_pk_mul_f32 v[60:61], v[60:61], v[78:79] op_sel_hi:[1,0]
	v_pk_mul_f32 v[62:63], v[2:3], v[62:63]
	v_pk_mul_f32 v[60:61], v[0:1], v[60:61]
	v_pk_fma_f32 v[62:63], v[72:73], v[62:63], v[18:19]
	v_pk_fma_f32 v[60:61], v[74:75], v[60:61], v[16:17]
	v_pk_mul_f32 v[58:59], v[58:59], v[78:79] op_sel_hi:[1,0]
	v_cvt_pk_bf16_f32 v60, v60, v61
	v_cvt_pk_bf16_f32 v61, v62, v63
	v_pk_mul_f32 v[56:57], v[56:57], v[78:79] op_sel_hi:[1,0]
	global_store_dwordx2 v[76:77], v[60:61], off
	v_pk_mul_f32 v[56:57], v[4:5], v[56:57]
	v_pk_mul_f32 v[58:59], v[6:7], v[58:59]
	v_pk_add_f32 v[60:61], v[46:47], 1.0 op_sel_hi:[1,0]
	v_pk_add_f32 v[62:63], v[44:45], 1.0 op_sel_hi:[1,0]
	v_pk_fma_f32 v[58:59], v[60:61], v[58:59], v[42:43]
	v_pk_fma_f32 v[56:57], v[62:63], v[56:57], v[40:41]
	v_pk_mul_f32 v[54:55], v[54:55], v[78:79] op_sel_hi:[1,0]
	v_cvt_pk_bf16_f32 v56, v56, v57
	v_cvt_pk_bf16_f32 v57, v58, v59
	v_pk_mul_f32 v[52:53], v[52:53], v[78:79] op_sel_hi:[1,0]
	global_store_dwordx2 v[76:77], v[56:57], off offset:512
	v_pk_mul_f32 v[52:53], v[8:9], v[52:53]
	v_pk_mul_f32 v[54:55], v[10:11], v[54:55]
	v_pk_add_f32 v[56:57], v[70:71], 1.0 op_sel_hi:[1,0]
	v_pk_add_f32 v[58:59], v[68:69], 1.0 op_sel_hi:[1,0]
	v_pk_fma_f32 v[54:55], v[56:57], v[54:55], v[66:67]
	v_pk_fma_f32 v[52:53], v[58:59], v[52:53], v[64:65]
	v_pk_mul_f32 v[50:51], v[50:51], v[78:79] op_sel_hi:[1,0]
	v_cvt_pk_bf16_f32 v52, v52, v53
	v_cvt_pk_bf16_f32 v53, v54, v55
	v_pk_mul_f32 v[48:49], v[48:49], v[78:79] op_sel_hi:[1,0]
	global_store_dwordx2 v[76:77], v[52:53], off offset:1024
	v_pk_mul_f32 v[48:49], v[12:13], v[48:49]
	v_pk_mul_f32 v[50:51], v[14:15], v[50:51]
	v_pk_add_f32 v[52:53], v[94:95], 1.0 op_sel_hi:[1,0]
	v_pk_add_f32 v[54:55], v[92:93], 1.0 op_sel_hi:[1,0]
	v_pk_fma_f32 v[50:51], v[52:53], v[50:51], v[90:91]
	v_pk_fma_f32 v[48:49], v[54:55], v[48:49], v[88:89]
	s_nop 0
	v_cvt_pk_bf16_f32 v48, v48, v49
	v_cvt_pk_bf16_f32 v49, v50, v51
	global_store_dwordx2 v[76:77], v[48:49], off offset:1536
	s_or_b64 exec, exec, s[6:7]
	v_cmp_lt_i32_e32 vcc, v162, v176
	s_and_saveexec_b64 s[6:7], vcc
	s_cbranch_execz .LBB0_100

.LBB0_996:
	s_or_b64 exec, exec, s[12:13]
	s_waitcnt vmcnt(27)
	v_lshlrev_b32_e32 v221, 16, v187
	v_lshlrev_b32_e32 v223, 16, v183
	v_and_b32_e32 v220, 0xffff0000, v187
	v_and_b32_e32 v222, 0xffff0000, v183
	s_waitcnt vmcnt(25)
	v_and_b32_e32 v218, 0xffff0000, v191
	v_lshlrev_b32_e32 v3, 16, v191
	v_pk_add_f32 v[220:221], v[220:221], v[222:223]
	v_lshlrev_b32_e32 v222, 16, v190
	v_and_b32_e32 v223, 0xffff0000, v190
	v_lshlrev_b32_e32 v190, 16, v186
	v_and_b32_e32 v191, 0xffff0000, v186
	v_lshlrev_b32_e32 v186, 16, v182
	v_and_b32_e32 v187, 0xffff0000, v182
	v_pk_add_f32 v[182:183], v[186:187], v[190:191]
	v_lshlrev_b32_e32 v190, 16, v189
	v_and_b32_e32 v191, 0xffff0000, v189
	v_lshlrev_b32_e32 v232, 16, v185
	v_and_b32_e32 v233, 0xffff0000, v185
	v_mul_f32_e32 v185, 0xbfb8aa3b, v190
	v_exp_f32_e32 v185, v185
	v_mul_f32_e32 v189, 0xbfb8aa3b, v191
	v_exp_f32_e32 v189, v189
	v_lshlrev_b32_e32 v234, 16, v181
	v_add_f32_e32 v185, 1.0, v185
	v_rcp_f32_e32 v236, v185
	v_add_f32_e32 v185, 1.0, v189
	v_rcp_f32_e32 v237, v185
	v_and_b32_e32 v235, 0xffff0000, v181
	v_and_b32_e32 v189, 0xffff0000, v184
	v_mad_i64_i32 v[24:25], s[12:13], v24, s19, v[202:203]
	v_pk_mul_f32 v[190:191], v[236:237], v[190:191]
	v_lshlrev_b32_e32 v236, 16, v188
	v_and_b32_e32 v237, 0xffff0000, v188
	v_mul_f32_e32 v181, 0xbfb8aa3b, v236
	v_lshlrev_b32_e32 v188, 16, v184
	v_exp_f32_e32 v181, v181
	v_mul_f32_e32 v184, 0xbfb8aa3b, v237
	v_exp_f32_e32 v185, v184
	v_lshlrev_b32_e32 v184, 16, v180
	v_add_f32_e32 v181, 1.0, v181
	v_rcp_f32_e32 v238, v181
	v_add_f32_e32 v181, 1.0, v185
	v_rcp_f32_e32 v239, v181
	v_and_b32_e32 v185, 0xffff0000, v180
	v_pk_add_f32 v[180:181], v[184:185], v[188:189]
	v_lshl_add_u64 v[28:29], v[194:195], 0, v[26:27]
	v_pk_mul_f32 v[188:189], v[238:239], v[236:237]
	s_waitcnt vmcnt(24)
	v_lshlrev_b32_e32 v236, 16, v171
	v_and_b32_e32 v237, 0xffff0000, v171
	v_mul_f32_e32 v171, 0xbfb8aa3b, v236
	v_lshl_add_u64 v[26:27], v[196:197], 0, v[26:27]
	v_lshlrev_b32_e32 v238, 16, v179
	v_and_b32_e32 v239, 0xffff0000, v179
	v_exp_f32_e32 v171, v171
	v_mul_f32_e32 v179, 0xbfb8aa3b, v237
	global_load_dwordx4 v[48:51], v[28:29], off offset:16
	global_load_dwordx4 v[32:35], v[28:29], off
	global_load_dwordx4 v[44:47], v[26:27], off offset:16
	s_nop 0
	global_load_dwordx4 v[28:31], v[26:27], off
	global_load_dwordx4 v[52:55], v[24:25], off offset:16
	s_nop 0
	global_load_dwordx4 v[24:27], v[24:25], off
	v_exp_f32_e32 v179, v179
	v_add_f32_e32 v171, 1.0, v171
	v_rcp_f32_e32 v242, v171
	v_lshlrev_b32_e32 v246, 16, v177
	v_add_f32_e32 v171, 1.0, v179
	v_rcp_f32_e32 v243, v171
	v_and_b32_e32 v247, 0xffff0000, v177
	v_lshlrev_b32_e32 v252, 16, v176
	v_and_b32_e32 v253, 0xffff0000, v176
	v_lshlrev_b32_e32 v176, 16, v172
	v_and_b32_e32 v177, 0xffff0000, v172
	v_lshlrev_b32_e32 v248, 16, v173
	v_and_b32_e32 v249, 0xffff0000, v173
	v_pk_add_f32 v[172:173], v[176:177], v[252:253]
	v_pk_mul_f32 v[236:237], v[242:243], v[236:237]
	v_lshlrev_b32_e32 v242, 16, v170
	v_pk_add_f32 v[246:247], v[248:249], v[246:247]
	v_pk_mul_f32 v[176:177], v[172:173], v[172:173]
	v_and_b32_e32 v243, 0xffff0000, v170
	v_lshlrev_b32_e32 v170, 16, v178
	v_and_b32_e32 v171, 0xffff0000, v178
	v_lshlrev_b32_e32 v178, 16, v174
	v_and_b32_e32 v179, 0xffff0000, v174
	v_mul_f32_e32 v174, 0xbfb8aa3b, v242
	v_pk_mul_f32 v[248:249], v[246:247], v[246:247]
	v_add_f32_e32 v176, v176, v177
	v_pk_add_f32 v[170:171], v[178:179], v[170:171]
	v_exp_f32_e32 v178, v174
	v_mul_f32_e32 v174, 0xbfb8aa3b, v243
	v_add_f32_e32 v176, v248, v176
	v_lshlrev_b32_e32 v240, 16, v175
	v_and_b32_e32 v241, 0xffff0000, v175
	v_exp_f32_e32 v179, v174
	v_pk_mul_f32 v[174:175], v[170:171], v[170:171]
	v_add_f32_e32 v176, v249, v176
	v_pk_add_f32 v[238:239], v[240:241], v[238:239]
	v_add_f32_e32 v174, v174, v176
	v_pk_mul_f32 v[240:241], v[238:239], v[238:239]
	v_add_f32_e32 v174, v175, v174
	v_add_f32_e32 v174, v240, v174
	v_pk_mul_f32 v[184:185], v[180:181], v[180:181]
	v_add_f32_e32 v174, v241, v174
	v_pk_add_f32 v[232:233], v[234:235], v[232:233]
	v_add_f32_e32 v174, v184, v174
	v_pk_mul_f32 v[234:235], v[232:233], v[232:233]
	v_lshlrev_b32_e32 v244, 16, v169
	v_add_f32_e32 v174, v185, v174
	v_and_b32_e32 v245, 0xffff0000, v169
	v_mul_f32_e32 v169, 0xbfb8aa3b, v244
	v_add_f32_e32 v174, v234, v174
	v_pk_mul_f32 v[186:187], v[182:183], v[182:183]
	v_exp_f32_e32 v169, v169
	v_add_f32_e32 v174, v235, v174
	v_add_f32_e32 v174, v186, v174
	v_pk_mul_f32 v[230:231], v[220:221], v[220:221]
	v_add_f32_e32 v174, v187, v174
	v_add_f32_e32 v174, v231, v174
	v_add_f32_e32 v169, 1.0, v169
	v_add_f32_e32 v176, v230, v174
	v_rcp_f32_e32 v250, v169
	v_mul_f32_e32 v169, 0xbfb8aa3b, v245
	v_exp_f32_e32 v169, v169
	v_lshlrev_b32_e32 v174, 16, v168
	v_and_b32_e32 v175, 0xffff0000, v168
	v_add_f32_e32 v178, 1.0, v178
	v_add_f32_e32 v169, 1.0, v169
	s_nop 1
	v_add_f32_dpp v168, v176, v176 quad_perm:[1,0,3,2] row_mask:0xf bank_mask:0xf
	v_rcp_f32_e32 v251, v169
	v_mul_f32_e32 v176, 0xbfb8aa3b, v174
	v_exp_f32_e32 v176, v176
	v_mul_f32_e32 v177, 0xbfb8aa3b, v175
	v_exp_f32_e32 v177, v177
	s_nop 1
	v_add_f32_dpp v184, v168, v168 quad_perm:[2,3,0,1] row_mask:0xf bank_mask:0xf
	v_add_f32_e32 v168, 1.0, v176
	v_add_f32_e32 v169, 1.0, v177
	v_rcp_f32_e32 v168, v168
	v_rcp_f32_e32 v169, v169
	s_nop 1
	v_add_f32_dpp v176, v184, v184 row_half_mirror row_mask:0xf bank_mask:0xf
	v_fmamk_f32 v176, v176, 0x3c000000, v226
	v_mul_f32_e32 v177, 0x4b800000, v176
	v_cmp_gt_f32_e32 vcc, s29, v176
	v_add_f32_e32 v179, 1.0, v179
	v_pk_mul_f32 v[168:169], v[168:169], v[174:175]
	v_cndmask_b32_e32 v176, v176, v177, vcc
	v_rsq_f32_e32 v184, v176
	v_rcp_f32_e32 v178, v178
	v_rcp_f32_e32 v179, v179
	v_mul_f32_e32 v174, 0x45800000, v184
	v_cndmask_b32_e32 v174, v184, v174, vcc
	v_pk_mul_f32 v[172:173], v[172:173], v[174:175] op_sel_hi:[1,0]
	v_pk_mul_f32 v[170:171], v[170:171], v[174:175] op_sel_hi:[1,0]
	v_pk_mul_f32 v[172:173], v[12:13], v[172:173]
	v_pk_mul_f32 v[176:177], v[178:179], v[242:243]
	v_pk_mul_f32 v[168:169], v[168:169], v[172:173]
	v_pk_mul_f32 v[172:173], v[246:247], v[174:175] op_sel_hi:[1,0]
	v_pk_mul_f32 v[178:179], v[250:251], v[244:245]
	v_pk_mul_f32 v[172:173], v[14:15], v[172:173]
	v_pk_mul_f32 v[170:171], v[8:9], v[170:171]
	v_pk_mul_f32 v[172:173], v[178:179], v[172:173]
	v_pk_mul_f32 v[170:171], v[176:177], v[170:171]
	v_pk_mul_f32 v[176:177], v[238:239], v[174:175] op_sel_hi:[1,0]
	v_pk_mul_f32 v[178:179], v[180:181], v[174:175] op_sel_hi:[1,0]
	v_pk_mul_f32 v[180:181], v[232:233], v[174:175] op_sel_hi:[1,0]
	v_mul_f32_e32 v175, 0xbfb8aa3b, v222
	v_exp_f32_e32 v175, v175
	v_mul_f32_e32 v184, 0xbfb8aa3b, v223
	v_exp_f32_e32 v185, v184
	v_mul_f32_e32 v219, v220, v174
	v_add_f32_e32 v175, 1.0, v175
	v_rcp_f32_e32 v184, v175
	v_add_f32_e32 v175, 1.0, v185
	v_rcp_f32_e32 v185, v175
	v_pk_mul_f32 v[182:183], v[182:183], v[174:175] op_sel_hi:[1,0]
	v_mul_f32_e32 v175, 0xbfb8aa3b, v3
	v_pk_mul_f32 v[182:183], v[0:1], v[182:183]
	v_pk_mul_f32 v[184:185], v[184:185], v[222:223]
	v_exp_f32_e32 v175, v175
	v_pk_mul_f32 v[182:183], v[184:185], v[182:183]
	v_mul_f32_e32 v184, 0xbfb8aa3b, v218
	v_exp_f32_e32 v184, v184
	v_add_f32_e32 v175, 1.0, v175
	v_rcp_f32_e32 v175, v175
	v_pk_mul_f32 v[176:177], v[10:11], v[176:177]
	v_add_f32_e32 v184, 1.0, v184
	v_rcp_f32_e32 v204, v184
	v_mul_f32_e32 v185, v221, v174
	v_mul_f32_e32 v186, v175, v3
	v_pk_mul_f32 v[176:177], v[236:237], v[176:177]
	v_pk_mul_f32 v[174:175], v[204:205], v[218:219]
	v_pk_mul_f32 v[178:179], v[4:5], v[178:179]
	v_pk_mul_f32 v[180:181], v[6:7], v[180:181]
	v_mul_f32_e32 v184, v2, v185
	v_mov_b32_e32 v187, v174
	v_mov_b32_e32 v185, v175
	v_pk_mul_f32 v[178:179], v[188:189], v[178:179]
	v_pk_mul_f32 v[180:181], v[190:191], v[180:181]
	v_cvt_pk_bf16_f32 v168, v168, v169
	v_cvt_pk_bf16_f32 v169, v172, v173
	v_cvt_pk_bf16_f32 v170, v170, v171
	v_cvt_pk_bf16_f32 v171, v176, v177
	v_lshl_add_u64 v[172:173], v[192:193], 0, v[216:217]
	v_pk_mul_f32 v[174:175], v[186:187], v[184:185]
	global_store_dwordx4 v[172:173], v[168:171], off
	v_cmp_gt_i32_e32 vcc, s3, v214
	s_nop 0
	v_cvt_pk_bf16_f32 v168, v178, v179
	v_cvt_pk_bf16_f32 v169, v180, v181
	v_cvt_pk_bf16_f32 v170, v182, v183
	v_cvt_pk_bf16_f32 v171, v174, v175
	global_store_dwordx4 v[172:173], v[168:171], off offset:16
	s_and_saveexec_b64 s[12:13], vcc
	s_cbranch_execz .LBB0_998
	s_waitcnt vmcnt(29)
	v_lshlrev_b32_e32 v171, 16, v163
	v_lshlrev_b32_e32 v173, 16, v159
	v_and_b32_e32 v170, 0xffff0000, v163
	v_and_b32_e32 v172, 0xffff0000, v159
	s_waitcnt vmcnt(27)
	v_and_b32_e32 v168, 0xffff0000, v167
	v_lshlrev_b32_e32 v3, 16, v167
	v_pk_add_f32 v[170:171], v[170:171], v[172:173]
	v_lshlrev_b32_e32 v172, 16, v166
	v_and_b32_e32 v173, 0xffff0000, v166
	v_lshlrev_b32_e32 v166, 16, v162
	v_and_b32_e32 v167, 0xffff0000, v162
	v_lshlrev_b32_e32 v162, 16, v158
	v_and_b32_e32 v163, 0xffff0000, v158
	v_pk_add_f32 v[158:159], v[162:163], v[166:167]
	v_lshlrev_b32_e32 v166, 16, v165
	v_and_b32_e32 v167, 0xffff0000, v165
	v_lshlrev_b32_e32 v176, 16, v161
	v_and_b32_e32 v177, 0xffff0000, v161
	v_mul_f32_e32 v161, 0xbfb8aa3b, v166
	v_exp_f32_e32 v161, v161
	v_mul_f32_e32 v165, 0xbfb8aa3b, v167
	v_exp_f32_e32 v165, v165
	v_lshlrev_b32_e32 v178, 16, v157
	v_add_f32_e32 v161, 1.0, v161
	v_rcp_f32_e32 v180, v161
	v_add_f32_e32 v161, 1.0, v165
	v_rcp_f32_e32 v181, v161
	v_and_b32_e32 v179, 0xffff0000, v157
	v_and_b32_e32 v165, 0xffff0000, v160
	v_lshlrev_b32_e32 v190, 16, v153
	v_pk_mul_f32 v[166:167], v[180:181], v[166:167]
	v_lshlrev_b32_e32 v180, 16, v164
	v_and_b32_e32 v181, 0xffff0000, v164
	v_mul_f32_e32 v157, 0xbfb8aa3b, v180
	v_lshlrev_b32_e32 v164, 16, v160
	v_exp_f32_e32 v157, v157
	v_mul_f32_e32 v160, 0xbfb8aa3b, v181
	v_exp_f32_e32 v161, v160
	v_lshlrev_b32_e32 v160, 16, v156
	v_add_f32_e32 v157, 1.0, v157
	v_rcp_f32_e32 v182, v157
	v_add_f32_e32 v157, 1.0, v161
	v_rcp_f32_e32 v183, v157
	v_and_b32_e32 v161, 0xffff0000, v156
	v_pk_add_f32 v[156:157], v[160:161], v[164:165]
	v_and_b32_e32 v191, 0xffff0000, v153
	v_pk_mul_f32 v[164:165], v[182:183], v[180:181]
	s_waitcnt vmcnt(26)
	v_lshlrev_b32_e32 v180, 16, v147
	v_and_b32_e32 v181, 0xffff0000, v147
	v_mul_f32_e32 v147, 0xbfb8aa3b, v180
	v_lshlrev_b32_e32 v182, 16, v155
	v_and_b32_e32 v183, 0xffff0000, v155
	v_exp_f32_e32 v147, v147
	v_mul_f32_e32 v155, 0xbfb8aa3b, v181
	v_exp_f32_e32 v155, v155
	v_lshlrev_b32_e32 v220, 16, v152
	v_add_f32_e32 v147, 1.0, v147
	v_rcp_f32_e32 v186, v147
	v_add_f32_e32 v147, 1.0, v155
	v_rcp_f32_e32 v187, v147
	v_and_b32_e32 v221, 0xffff0000, v152
	v_lshlrev_b32_e32 v152, 16, v148
	v_and_b32_e32 v153, 0xffff0000, v148
	v_lshlrev_b32_e32 v216, 16, v149
	v_and_b32_e32 v217, 0xffff0000, v149
	v_pk_add_f32 v[148:149], v[152:153], v[220:221]
	v_pk_mul_f32 v[180:181], v[186:187], v[180:181]
	v_lshlrev_b32_e32 v186, 16, v146
	v_pk_add_f32 v[190:191], v[216:217], v[190:191]
	v_pk_mul_f32 v[152:153], v[148:149], v[148:149]
	v_and_b32_e32 v187, 0xffff0000, v146
	v_lshlrev_b32_e32 v146, 16, v154
	v_and_b32_e32 v147, 0xffff0000, v154
	v_lshlrev_b32_e32 v154, 16, v150
	v_and_b32_e32 v155, 0xffff0000, v150
	v_mul_f32_e32 v150, 0xbfb8aa3b, v186
	v_pk_mul_f32 v[216:217], v[190:191], v[190:191]
	v_add_f32_e32 v152, v152, v153
	v_pk_add_f32 v[146:147], v[154:155], v[146:147]
	v_exp_f32_e32 v154, v150
	v_mul_f32_e32 v150, 0xbfb8aa3b, v187
	v_add_f32_e32 v152, v216, v152
	v_lshlrev_b32_e32 v184, 16, v151
	v_and_b32_e32 v185, 0xffff0000, v151
	v_exp_f32_e32 v155, v150
	v_pk_mul_f32 v[150:151], v[146:147], v[146:147]
	v_add_f32_e32 v152, v217, v152
	v_pk_add_f32 v[182:183], v[184:185], v[182:183]
	v_add_f32_e32 v150, v150, v152
	v_pk_mul_f32 v[184:185], v[182:183], v[182:183]
	v_add_f32_e32 v150, v151, v150
	v_add_f32_e32 v150, v184, v150
	v_pk_mul_f32 v[160:161], v[156:157], v[156:157]
	v_add_f32_e32 v150, v185, v150
	v_pk_add_f32 v[176:177], v[178:179], v[176:177]
	v_add_f32_e32 v150, v160, v150
	v_pk_mul_f32 v[178:179], v[176:177], v[176:177]
	v_lshlrev_b32_e32 v188, 16, v145
	v_add_f32_e32 v150, v161, v150
	v_and_b32_e32 v189, 0xffff0000, v145
	v_mul_f32_e32 v145, 0xbfb8aa3b, v188
	v_add_f32_e32 v150, v178, v150
	v_pk_mul_f32 v[162:163], v[158:159], v[158:159]
	v_exp_f32_e32 v145, v145
	v_add_f32_e32 v150, v179, v150
	v_add_f32_e32 v150, v162, v150
	v_pk_mul_f32 v[174:175], v[170:171], v[170:171]
	v_add_f32_e32 v150, v163, v150
	v_add_f32_e32 v150, v175, v150
	v_add_f32_e32 v145, 1.0, v145
	v_add_f32_e32 v152, v174, v150
	v_rcp_f32_e32 v218, v145
	v_mul_f32_e32 v145, 0xbfb8aa3b, v189
	v_exp_f32_e32 v145, v145
	v_lshlrev_b32_e32 v150, 16, v144
	v_and_b32_e32 v151, 0xffff0000, v144
	v_add_f32_e32 v154, 1.0, v154
	v_add_f32_e32 v145, 1.0, v145
	s_nop 1
	v_add_f32_dpp v144, v152, v152 quad_perm:[1,0,3,2] row_mask:0xf bank_mask:0xf
	v_rcp_f32_e32 v219, v145
	v_mul_f32_e32 v152, 0xbfb8aa3b, v150
	v_exp_f32_e32 v152, v152
	v_mul_f32_e32 v153, 0xbfb8aa3b, v151
	v_exp_f32_e32 v153, v153
	s_nop 1
	v_add_f32_dpp v160, v144, v144 quad_perm:[2,3,0,1] row_mask:0xf bank_mask:0xf
	v_add_f32_e32 v144, 1.0, v152
	v_add_f32_e32 v145, 1.0, v153
	v_rcp_f32_e32 v144, v144
	v_rcp_f32_e32 v145, v145
	s_nop 1
	v_add_f32_dpp v152, v160, v160 row_half_mirror row_mask:0xf bank_mask:0xf
	v_fmamk_f32 v152, v152, 0x3c000000, v226
	v_mul_f32_e32 v153, 0x4b800000, v152
	v_cmp_gt_f32_e32 vcc, s29, v152
	v_add_f32_e32 v155, 1.0, v155
	v_pk_mul_f32 v[144:145], v[144:145], v[150:151]
	v_cndmask_b32_e32 v152, v152, v153, vcc
	v_rsq_f32_e32 v160, v152
	v_rcp_f32_e32 v154, v154
	v_rcp_f32_e32 v155, v155
	v_ashrrev_i32_e32 v215, 31, v214
	v_mul_f32_e32 v150, 0x45800000, v160
	v_cndmask_b32_e32 v150, v160, v150, vcc
	v_pk_mul_f32 v[148:149], v[148:149], v[150:151] op_sel_hi:[1,0]
	v_pk_mul_f32 v[146:147], v[146:147], v[150:151] op_sel_hi:[1,0]
	v_pk_mul_f32 v[148:149], v[12:13], v[148:149]
	v_pk_mul_f32 v[152:153], v[154:155], v[186:187]
	v_pk_mul_f32 v[144:145], v[144:145], v[148:149]
	v_pk_mul_f32 v[148:149], v[190:191], v[150:151] op_sel_hi:[1,0]
	v_pk_mul_f32 v[154:155], v[218:219], v[188:189]
	v_pk_mul_f32 v[148:149], v[14:15], v[148:149]
	v_pk_mul_f32 v[146:147], v[8:9], v[146:147]
	v_pk_mul_f32 v[148:149], v[154:155], v[148:149]
	v_pk_mul_f32 v[146:147], v[152:153], v[146:147]
	v_pk_mul_f32 v[152:153], v[182:183], v[150:151] op_sel_hi:[1,0]
	v_pk_mul_f32 v[154:155], v[156:157], v[150:151] op_sel_hi:[1,0]
	v_pk_mul_f32 v[156:157], v[176:177], v[150:151] op_sel_hi:[1,0]
	v_mul_f32_e32 v151, 0xbfb8aa3b, v172
	v_exp_f32_e32 v151, v151
	v_mul_f32_e32 v160, 0xbfb8aa3b, v173
	v_exp_f32_e32 v161, v160
	v_mul_f32_e32 v169, v170, v150
	v_add_f32_e32 v151, 1.0, v151
	v_rcp_f32_e32 v160, v151
	v_add_f32_e32 v151, 1.0, v161
	v_rcp_f32_e32 v161, v151
	v_pk_mul_f32 v[158:159], v[158:159], v[150:151] op_sel_hi:[1,0]
	v_mul_f32_e32 v151, 0xbfb8aa3b, v3
	v_pk_mul_f32 v[158:159], v[0:1], v[158:159]
	v_pk_mul_f32 v[160:161], v[160:161], v[172:173]
	v_exp_f32_e32 v151, v151
	v_pk_mul_f32 v[158:159], v[160:161], v[158:159]
	v_mul_f32_e32 v160, 0xbfb8aa3b, v168
	v_exp_f32_e32 v160, v160
	v_add_f32_e32 v151, 1.0, v151
	v_rcp_f32_e32 v151, v151
	v_pk_mul_f32 v[152:153], v[10:11], v[152:153]
	v_add_f32_e32 v160, 1.0, v160
	v_rcp_f32_e32 v204, v160
	v_mul_f32_e32 v161, v171, v150
	v_mul_f32_e32 v162, v151, v3
	v_pk_mul_f32 v[152:153], v[180:181], v[152:153]
	v_pk_mul_f32 v[150:151], v[204:205], v[168:169]
	v_pk_mul_f32 v[154:155], v[4:5], v[154:155]
	v_pk_mul_f32 v[156:157], v[6:7], v[156:157]
	v_mul_f32_e32 v160, v2, v161
	v_mov_b32_e32 v163, v150
	v_mov_b32_e32 v161, v151
	v_cvt_pk_bf16_f32 v144, v144, v145
	v_cvt_pk_bf16_f32 v145, v148, v149
	v_lshlrev_b64 v[148:149], 11, v[214:215]
	v_pk_mul_f32 v[154:155], v[164:165], v[154:155]
	v_pk_mul_f32 v[156:157], v[166:167], v[156:157]
	v_cvt_pk_bf16_f32 v146, v146, v147
	v_cvt_pk_bf16_f32 v147, v152, v153
	v_lshl_add_u64 v[148:149], v[192:193], 0, v[148:149]
	v_pk_mul_f32 v[150:151], v[162:163], v[160:161]
	global_store_dwordx4 v[148:149], v[144:147], off
	s_nop 1
	v_cvt_pk_bf16_f32 v144, v154, v155
	v_cvt_pk_bf16_f32 v145, v156, v157
	v_cvt_pk_bf16_f32 v146, v158, v159
	v_cvt_pk_bf16_f32 v147, v150, v151
	global_store_dwordx4 v[148:149], v[144:147], off offset:16
.LBB0_998:
	s_or_b64 exec, exec, s[12:13]
	v_add_u32_e32 v3, s33, v214
	v_cmp_gt_i32_e32 vcc, s3, v3
	s_and_saveexec_b64 s[12:13], vcc
	s_cbranch_execz .LBB0_1000
	s_waitcnt vmcnt(23)
	v_lshlrev_b32_e32 v147, 16, v139
	v_lshlrev_b32_e32 v149, 16, v135
	v_and_b32_e32 v146, 0xffff0000, v139
	v_and_b32_e32 v148, 0xffff0000, v135
	s_waitcnt vmcnt(21)
	v_and_b32_e32 v144, 0xffff0000, v143
	v_lshlrev_b32_e32 v145, 16, v143
	v_pk_add_f32 v[146:147], v[146:147], v[148:149]
	v_lshlrev_b32_e32 v148, 16, v142
	v_and_b32_e32 v149, 0xffff0000, v142
	v_lshlrev_b32_e32 v142, 16, v138
	v_and_b32_e32 v143, 0xffff0000, v138
	v_lshlrev_b32_e32 v138, 16, v134
	v_and_b32_e32 v139, 0xffff0000, v134
	v_pk_add_f32 v[134:135], v[138:139], v[142:143]
	v_lshlrev_b32_e32 v142, 16, v141
	v_and_b32_e32 v143, 0xffff0000, v141
	v_lshlrev_b32_e32 v152, 16, v137
	v_and_b32_e32 v153, 0xffff0000, v137
	v_mul_f32_e32 v137, 0xbfb8aa3b, v142
	v_exp_f32_e32 v137, v137
	v_mul_f32_e32 v141, 0xbfb8aa3b, v143
	v_exp_f32_e32 v141, v141
	v_lshlrev_b32_e32 v154, 16, v133
	v_add_f32_e32 v137, 1.0, v137
	v_rcp_f32_e32 v156, v137
	v_add_f32_e32 v137, 1.0, v141
	v_rcp_f32_e32 v157, v137
	v_and_b32_e32 v155, 0xffff0000, v133
	v_and_b32_e32 v141, 0xffff0000, v136
	v_lshlrev_b32_e32 v166, 16, v129
	v_pk_mul_f32 v[142:143], v[156:157], v[142:143]
	v_lshlrev_b32_e32 v156, 16, v140
	v_and_b32_e32 v157, 0xffff0000, v140
	v_mul_f32_e32 v133, 0xbfb8aa3b, v156
	v_lshlrev_b32_e32 v140, 16, v136
	v_exp_f32_e32 v133, v133
	v_mul_f32_e32 v136, 0xbfb8aa3b, v157
	v_exp_f32_e32 v137, v136
	v_lshlrev_b32_e32 v136, 16, v132
	v_add_f32_e32 v133, 1.0, v133
	v_rcp_f32_e32 v158, v133
	v_add_f32_e32 v133, 1.0, v137
	v_rcp_f32_e32 v159, v133
	v_and_b32_e32 v137, 0xffff0000, v132
	v_pk_add_f32 v[132:133], v[136:137], v[140:141]
	v_and_b32_e32 v167, 0xffff0000, v129
	v_pk_mul_f32 v[140:141], v[158:159], v[156:157]
	s_waitcnt vmcnt(20)
	v_lshlrev_b32_e32 v156, 16, v123
	v_and_b32_e32 v157, 0xffff0000, v123
	v_mul_f32_e32 v123, 0xbfb8aa3b, v156
	v_lshlrev_b32_e32 v158, 16, v131
	v_and_b32_e32 v159, 0xffff0000, v131
	v_exp_f32_e32 v123, v123
	v_mul_f32_e32 v131, 0xbfb8aa3b, v157
	v_exp_f32_e32 v131, v131
	v_lshlrev_b32_e32 v172, 16, v128
	v_add_f32_e32 v123, 1.0, v123
	v_rcp_f32_e32 v162, v123
	v_add_f32_e32 v123, 1.0, v131
	v_rcp_f32_e32 v163, v123
	v_and_b32_e32 v173, 0xffff0000, v128
	v_lshlrev_b32_e32 v128, 16, v124
	v_and_b32_e32 v129, 0xffff0000, v124
	v_lshlrev_b32_e32 v168, 16, v125
	v_and_b32_e32 v169, 0xffff0000, v125
	v_pk_add_f32 v[124:125], v[128:129], v[172:173]
	v_pk_mul_f32 v[156:157], v[162:163], v[156:157]
	v_lshlrev_b32_e32 v162, 16, v122
	v_pk_add_f32 v[166:167], v[168:169], v[166:167]
	v_pk_mul_f32 v[128:129], v[124:125], v[124:125]
	v_and_b32_e32 v163, 0xffff0000, v122
	v_lshlrev_b32_e32 v122, 16, v130
	v_and_b32_e32 v123, 0xffff0000, v130
	v_lshlrev_b32_e32 v130, 16, v126
	v_and_b32_e32 v131, 0xffff0000, v126
	v_mul_f32_e32 v126, 0xbfb8aa3b, v162
	v_pk_mul_f32 v[168:169], v[166:167], v[166:167]
	v_add_f32_e32 v128, v128, v129
	v_pk_add_f32 v[122:123], v[130:131], v[122:123]
	v_exp_f32_e32 v130, v126
	v_mul_f32_e32 v126, 0xbfb8aa3b, v163
	v_add_f32_e32 v128, v168, v128
	v_lshlrev_b32_e32 v160, 16, v127
	v_and_b32_e32 v161, 0xffff0000, v127
	v_exp_f32_e32 v131, v126
	v_pk_mul_f32 v[126:127], v[122:123], v[122:123]
	v_add_f32_e32 v128, v169, v128
	v_pk_add_f32 v[158:159], v[160:161], v[158:159]
	v_add_f32_e32 v126, v126, v128
	v_pk_mul_f32 v[160:161], v[158:159], v[158:159]
	v_add_f32_e32 v126, v127, v126
	v_add_f32_e32 v126, v160, v126
	v_pk_mul_f32 v[136:137], v[132:133], v[132:133]
	v_add_f32_e32 v126, v161, v126
	v_pk_add_f32 v[152:153], v[154:155], v[152:153]
	v_add_f32_e32 v126, v136, v126
	v_pk_mul_f32 v[154:155], v[152:153], v[152:153]
	v_lshlrev_b32_e32 v164, 16, v121
	v_add_f32_e32 v126, v137, v126
	v_and_b32_e32 v165, 0xffff0000, v121
	v_mul_f32_e32 v121, 0xbfb8aa3b, v164
	v_add_f32_e32 v126, v154, v126
	v_pk_mul_f32 v[138:139], v[134:135], v[134:135]
	v_exp_f32_e32 v121, v121
	v_add_f32_e32 v126, v155, v126
	v_add_f32_e32 v126, v138, v126
	v_pk_mul_f32 v[150:151], v[146:147], v[146:147]
	v_add_f32_e32 v126, v139, v126
	v_add_f32_e32 v126, v151, v126
	v_add_f32_e32 v121, 1.0, v121
	v_add_f32_e32 v128, v150, v126
	v_rcp_f32_e32 v170, v121
	v_mul_f32_e32 v121, 0xbfb8aa3b, v165
	v_exp_f32_e32 v121, v121
	v_lshlrev_b32_e32 v126, 16, v120
	v_and_b32_e32 v127, 0xffff0000, v120
	v_add_f32_e32 v130, 1.0, v130
	v_add_f32_e32 v121, 1.0, v121
	s_nop 1
	v_add_f32_dpp v120, v128, v128 quad_perm:[1,0,3,2] row_mask:0xf bank_mask:0xf
	v_rcp_f32_e32 v171, v121
	v_mul_f32_e32 v128, 0xbfb8aa3b, v126
	v_exp_f32_e32 v128, v128
	v_mul_f32_e32 v129, 0xbfb8aa3b, v127
	v_exp_f32_e32 v129, v129
	s_nop 1
	v_add_f32_dpp v136, v120, v120 quad_perm:[2,3,0,1] row_mask:0xf bank_mask:0xf
	v_add_f32_e32 v120, 1.0, v128
	v_add_f32_e32 v121, 1.0, v129
	v_rcp_f32_e32 v120, v120
	v_rcp_f32_e32 v121, v121
	s_nop 1
	v_add_f32_dpp v128, v136, v136 row_half_mirror row_mask:0xf bank_mask:0xf
	v_fmamk_f32 v128, v128, 0x3c000000, v226
	v_mul_f32_e32 v129, 0x4b800000, v128
	v_cmp_gt_f32_e32 vcc, s29, v128
	v_add_f32_e32 v131, 1.0, v131
	v_pk_mul_f32 v[120:121], v[120:121], v[126:127]
	v_cndmask_b32_e32 v128, v128, v129, vcc
	v_rsq_f32_e32 v136, v128
	v_rcp_f32_e32 v130, v130
	v_rcp_f32_e32 v131, v131
	v_ashrrev_i32_e32 v213, 31, v212
	v_mul_f32_e32 v126, 0x45800000, v136
	v_cndmask_b32_e32 v126, v136, v126, vcc
	v_pk_mul_f32 v[124:125], v[124:125], v[126:127] op_sel_hi:[1,0]
	v_pk_mul_f32 v[122:123], v[122:123], v[126:127] op_sel_hi:[1,0]
	v_pk_mul_f32 v[124:125], v[12:13], v[124:125]
	v_pk_mul_f32 v[128:129], v[130:131], v[162:163]
	v_pk_mul_f32 v[120:121], v[120:121], v[124:125]
	v_pk_mul_f32 v[124:125], v[166:167], v[126:127] op_sel_hi:[1,0]
	v_pk_mul_f32 v[130:131], v[170:171], v[164:165]
	v_pk_mul_f32 v[124:125], v[14:15], v[124:125]
	v_pk_mul_f32 v[122:123], v[8:9], v[122:123]
	v_pk_mul_f32 v[124:125], v[130:131], v[124:125]
	v_pk_mul_f32 v[122:123], v[128:129], v[122:123]
	v_pk_mul_f32 v[128:129], v[158:159], v[126:127] op_sel_hi:[1,0]
	v_pk_mul_f32 v[130:131], v[132:133], v[126:127] op_sel_hi:[1,0]
	v_pk_mul_f32 v[132:133], v[152:153], v[126:127] op_sel_hi:[1,0]
	v_mul_f32_e32 v127, 0xbfb8aa3b, v148
	v_exp_f32_e32 v127, v127
	v_mul_f32_e32 v136, 0xbfb8aa3b, v149
	v_exp_f32_e32 v137, v136
	v_pk_mul_f32 v[128:129], v[10:11], v[128:129]
	v_add_f32_e32 v127, 1.0, v127
	v_rcp_f32_e32 v136, v127
	v_add_f32_e32 v127, 1.0, v137
	v_rcp_f32_e32 v137, v127
	v_pk_mul_f32 v[134:135], v[134:135], v[126:127] op_sel_hi:[1,0]
	v_mul_f32_e32 v127, 0xbfb8aa3b, v145
	v_pk_mul_f32 v[134:135], v[0:1], v[134:135]
	v_pk_mul_f32 v[136:137], v[136:137], v[148:149]
	v_exp_f32_e32 v127, v127
	v_pk_mul_f32 v[134:135], v[136:137], v[134:135]
	v_mul_f32_e32 v136, 0xbfb8aa3b, v144
	v_exp_f32_e32 v136, v136
	v_add_f32_e32 v127, 1.0, v127
	v_rcp_f32_e32 v127, v127
	v_mul_f32_e32 v137, v147, v126
	v_add_f32_e32 v136, 1.0, v136
	v_rcp_f32_e32 v204, v136
	v_mul_f32_e32 v138, v127, v145
	v_mul_f32_e32 v145, v146, v126
	v_pk_mul_f32 v[128:129], v[156:157], v[128:129]
	v_pk_mul_f32 v[126:127], v[204:205], v[144:145]
	v_pk_mul_f32 v[130:131], v[4:5], v[130:131]
	v_pk_mul_f32 v[132:133], v[6:7], v[132:133]
	v_mul_f32_e32 v136, v2, v137
	v_mov_b32_e32 v139, v126
	v_mov_b32_e32 v137, v127
	v_cvt_pk_bf16_f32 v120, v120, v121
	v_cvt_pk_bf16_f32 v121, v124, v125
	v_lshlrev_b64 v[124:125], 11, v[212:213]
	v_pk_mul_f32 v[130:131], v[140:141], v[130:131]
	v_pk_mul_f32 v[132:133], v[142:143], v[132:133]
	v_cvt_pk_bf16_f32 v122, v122, v123
	v_cvt_pk_bf16_f32 v123, v128, v129
	v_lshl_add_u64 v[124:125], v[192:193], 0, v[124:125]
	v_pk_mul_f32 v[126:127], v[138:139], v[136:137]
	global_store_dwordx4 v[124:125], v[120:123], off
	s_nop 1
	v_cvt_pk_bf16_f32 v120, v130, v131
	v_cvt_pk_bf16_f32 v121, v132, v133
	v_cvt_pk_bf16_f32 v122, v134, v135
	v_cvt_pk_bf16_f32 v123, v126, v127
	global_store_dwordx4 v[124:125], v[120:123], off offset:16
.LBB0_1000:
	s_or_b64 exec, exec, s[12:13]
	v_add_u32_e32 v3, s33, v3
	v_cmp_gt_i32_e32 vcc, s3, v3
	s_and_saveexec_b64 s[12:13], vcc
	s_cbranch_execz .LBB0_1002
	s_waitcnt vmcnt(17)
	v_lshlrev_b32_e32 v123, 16, v115
	v_lshlrev_b32_e32 v125, 16, v111
	v_and_b32_e32 v122, 0xffff0000, v115
	v_and_b32_e32 v124, 0xffff0000, v111
	s_waitcnt vmcnt(15)
	v_and_b32_e32 v120, 0xffff0000, v119
	v_lshlrev_b32_e32 v121, 16, v119
	v_pk_add_f32 v[122:123], v[122:123], v[124:125]
	v_lshlrev_b32_e32 v124, 16, v118
	v_and_b32_e32 v125, 0xffff0000, v118
	v_lshlrev_b32_e32 v118, 16, v114
	v_and_b32_e32 v119, 0xffff0000, v114
	v_lshlrev_b32_e32 v114, 16, v110
	v_and_b32_e32 v115, 0xffff0000, v110
	v_pk_add_f32 v[110:111], v[114:115], v[118:119]
	v_lshlrev_b32_e32 v118, 16, v117
	v_and_b32_e32 v119, 0xffff0000, v117
	v_lshlrev_b32_e32 v128, 16, v113
	v_and_b32_e32 v129, 0xffff0000, v113
	v_mul_f32_e32 v113, 0xbfb8aa3b, v118
	v_exp_f32_e32 v113, v113
	v_mul_f32_e32 v117, 0xbfb8aa3b, v119
	v_exp_f32_e32 v117, v117
	v_lshlrev_b32_e32 v130, 16, v109
	v_add_f32_e32 v113, 1.0, v113
	v_rcp_f32_e32 v132, v113
	v_add_f32_e32 v113, 1.0, v117
	v_rcp_f32_e32 v133, v113
	v_and_b32_e32 v131, 0xffff0000, v109
	v_and_b32_e32 v117, 0xffff0000, v112
	v_lshlrev_b32_e32 v142, 16, v105
	v_pk_mul_f32 v[118:119], v[132:133], v[118:119]
	v_lshlrev_b32_e32 v132, 16, v116
	v_and_b32_e32 v133, 0xffff0000, v116
	v_mul_f32_e32 v109, 0xbfb8aa3b, v132
	v_lshlrev_b32_e32 v116, 16, v112
	v_exp_f32_e32 v109, v109
	v_mul_f32_e32 v112, 0xbfb8aa3b, v133
	v_exp_f32_e32 v113, v112
	v_lshlrev_b32_e32 v112, 16, v108
	v_add_f32_e32 v109, 1.0, v109
	v_rcp_f32_e32 v134, v109
	v_add_f32_e32 v109, 1.0, v113
	v_rcp_f32_e32 v135, v109
	v_and_b32_e32 v113, 0xffff0000, v108
	v_pk_add_f32 v[108:109], v[112:113], v[116:117]
	v_and_b32_e32 v143, 0xffff0000, v105
	v_pk_mul_f32 v[116:117], v[134:135], v[132:133]
	s_waitcnt vmcnt(14)
	v_lshlrev_b32_e32 v132, 16, v99
	v_and_b32_e32 v133, 0xffff0000, v99
	v_mul_f32_e32 v99, 0xbfb8aa3b, v132
	v_lshlrev_b32_e32 v134, 16, v107
	v_and_b32_e32 v135, 0xffff0000, v107
	v_exp_f32_e32 v99, v99
	v_mul_f32_e32 v107, 0xbfb8aa3b, v133
	v_exp_f32_e32 v107, v107
	v_lshlrev_b32_e32 v148, 16, v104
	v_add_f32_e32 v99, 1.0, v99
	v_rcp_f32_e32 v138, v99
	v_add_f32_e32 v99, 1.0, v107
	v_rcp_f32_e32 v139, v99
	v_and_b32_e32 v149, 0xffff0000, v104
	v_lshlrev_b32_e32 v104, 16, v100
	v_and_b32_e32 v105, 0xffff0000, v100
	v_lshlrev_b32_e32 v144, 16, v101
	v_and_b32_e32 v145, 0xffff0000, v101
	v_pk_add_f32 v[100:101], v[104:105], v[148:149]
	v_pk_mul_f32 v[132:133], v[138:139], v[132:133]
	v_lshlrev_b32_e32 v138, 16, v98
	v_pk_add_f32 v[142:143], v[144:145], v[142:143]
	v_pk_mul_f32 v[104:105], v[100:101], v[100:101]
	v_and_b32_e32 v139, 0xffff0000, v98
	v_lshlrev_b32_e32 v98, 16, v106
	v_and_b32_e32 v99, 0xffff0000, v106
	v_lshlrev_b32_e32 v106, 16, v102
	v_and_b32_e32 v107, 0xffff0000, v102
	v_mul_f32_e32 v102, 0xbfb8aa3b, v138
	v_pk_mul_f32 v[144:145], v[142:143], v[142:143]
	v_add_f32_e32 v104, v104, v105
	v_pk_add_f32 v[98:99], v[106:107], v[98:99]
	v_exp_f32_e32 v106, v102
	v_mul_f32_e32 v102, 0xbfb8aa3b, v139
	v_add_f32_e32 v104, v144, v104
	v_lshlrev_b32_e32 v136, 16, v103
	v_and_b32_e32 v137, 0xffff0000, v103
	v_exp_f32_e32 v107, v102
	v_pk_mul_f32 v[102:103], v[98:99], v[98:99]
	v_add_f32_e32 v104, v145, v104
	v_pk_add_f32 v[134:135], v[136:137], v[134:135]
	v_add_f32_e32 v102, v102, v104
	v_pk_mul_f32 v[136:137], v[134:135], v[134:135]
	v_add_f32_e32 v102, v103, v102
	v_add_f32_e32 v102, v136, v102
	v_pk_mul_f32 v[112:113], v[108:109], v[108:109]
	v_add_f32_e32 v102, v137, v102
	v_pk_add_f32 v[128:129], v[130:131], v[128:129]
	v_add_f32_e32 v102, v112, v102
	v_pk_mul_f32 v[130:131], v[128:129], v[128:129]
	v_lshlrev_b32_e32 v140, 16, v97
	v_add_f32_e32 v102, v113, v102
	v_and_b32_e32 v141, 0xffff0000, v97
	v_mul_f32_e32 v97, 0xbfb8aa3b, v140
	v_add_f32_e32 v102, v130, v102
	v_pk_mul_f32 v[114:115], v[110:111], v[110:111]
	v_exp_f32_e32 v97, v97
	v_add_f32_e32 v102, v131, v102
	v_add_f32_e32 v102, v114, v102
	v_pk_mul_f32 v[126:127], v[122:123], v[122:123]
	v_add_f32_e32 v102, v115, v102
	v_add_f32_e32 v102, v127, v102
	v_add_f32_e32 v97, 1.0, v97
	v_add_f32_e32 v104, v126, v102
	v_rcp_f32_e32 v146, v97
	v_mul_f32_e32 v97, 0xbfb8aa3b, v141
	v_exp_f32_e32 v97, v97
	v_lshlrev_b32_e32 v102, 16, v96
	v_and_b32_e32 v103, 0xffff0000, v96
	v_add_f32_e32 v106, 1.0, v106
	v_add_f32_e32 v97, 1.0, v97
	s_nop 1
	v_add_f32_dpp v96, v104, v104 quad_perm:[1,0,3,2] row_mask:0xf bank_mask:0xf
	v_rcp_f32_e32 v147, v97
	v_mul_f32_e32 v104, 0xbfb8aa3b, v102
	v_exp_f32_e32 v104, v104
	v_mul_f32_e32 v105, 0xbfb8aa3b, v103
	v_exp_f32_e32 v105, v105
	s_nop 1
	v_add_f32_dpp v112, v96, v96 quad_perm:[2,3,0,1] row_mask:0xf bank_mask:0xf
	v_add_f32_e32 v96, 1.0, v104
	v_add_f32_e32 v97, 1.0, v105
	v_rcp_f32_e32 v96, v96
	v_rcp_f32_e32 v97, v97
	s_nop 1
	v_add_f32_dpp v104, v112, v112 row_half_mirror row_mask:0xf bank_mask:0xf
	v_fmamk_f32 v104, v104, 0x3c000000, v226
	v_mul_f32_e32 v105, 0x4b800000, v104
	v_cmp_gt_f32_e32 vcc, s29, v104
	v_add_f32_e32 v107, 1.0, v107
	v_pk_mul_f32 v[96:97], v[96:97], v[102:103]
	v_cndmask_b32_e32 v104, v104, v105, vcc
	v_rsq_f32_e32 v112, v104
	v_rcp_f32_e32 v106, v106
	v_rcp_f32_e32 v107, v107
	v_ashrrev_i32_e32 v211, 31, v210
	v_mul_f32_e32 v102, 0x45800000, v112
	v_cndmask_b32_e32 v102, v112, v102, vcc
	v_pk_mul_f32 v[100:101], v[100:101], v[102:103] op_sel_hi:[1,0]
	v_pk_mul_f32 v[98:99], v[98:99], v[102:103] op_sel_hi:[1,0]
	v_pk_mul_f32 v[100:101], v[12:13], v[100:101]
	v_pk_mul_f32 v[104:105], v[106:107], v[138:139]
	v_pk_mul_f32 v[96:97], v[96:97], v[100:101]
	v_pk_mul_f32 v[100:101], v[142:143], v[102:103] op_sel_hi:[1,0]
	v_pk_mul_f32 v[106:107], v[146:147], v[140:141]
	v_pk_mul_f32 v[100:101], v[14:15], v[100:101]
	v_pk_mul_f32 v[98:99], v[8:9], v[98:99]
	v_pk_mul_f32 v[100:101], v[106:107], v[100:101]
	v_pk_mul_f32 v[98:99], v[104:105], v[98:99]
	v_pk_mul_f32 v[104:105], v[134:135], v[102:103] op_sel_hi:[1,0]
	v_pk_mul_f32 v[106:107], v[108:109], v[102:103] op_sel_hi:[1,0]
	v_pk_mul_f32 v[108:109], v[128:129], v[102:103] op_sel_hi:[1,0]
	v_mul_f32_e32 v103, 0xbfb8aa3b, v124
	v_exp_f32_e32 v103, v103
	v_mul_f32_e32 v112, 0xbfb8aa3b, v125
	v_exp_f32_e32 v113, v112
	v_pk_mul_f32 v[104:105], v[10:11], v[104:105]
	v_add_f32_e32 v103, 1.0, v103
	v_rcp_f32_e32 v112, v103
	v_add_f32_e32 v103, 1.0, v113
	v_rcp_f32_e32 v113, v103
	v_pk_mul_f32 v[110:111], v[110:111], v[102:103] op_sel_hi:[1,0]
	v_mul_f32_e32 v103, 0xbfb8aa3b, v121
	v_pk_mul_f32 v[110:111], v[0:1], v[110:111]
	v_pk_mul_f32 v[112:113], v[112:113], v[124:125]
	v_exp_f32_e32 v103, v103
	v_pk_mul_f32 v[110:111], v[112:113], v[110:111]
	v_mul_f32_e32 v112, 0xbfb8aa3b, v120
	v_exp_f32_e32 v112, v112
	v_add_f32_e32 v103, 1.0, v103
	v_rcp_f32_e32 v103, v103
	v_mul_f32_e32 v113, v123, v102
	v_add_f32_e32 v112, 1.0, v112
	v_rcp_f32_e32 v204, v112
	v_mul_f32_e32 v114, v103, v121
	v_mul_f32_e32 v121, v122, v102
	v_pk_mul_f32 v[104:105], v[132:133], v[104:105]
	v_pk_mul_f32 v[102:103], v[204:205], v[120:121]
	v_pk_mul_f32 v[106:107], v[4:5], v[106:107]
	v_pk_mul_f32 v[108:109], v[6:7], v[108:109]
	v_mul_f32_e32 v112, v2, v113
	v_mov_b32_e32 v115, v102
	v_mov_b32_e32 v113, v103
	v_cvt_pk_bf16_f32 v96, v96, v97
	v_cvt_pk_bf16_f32 v97, v100, v101
	v_lshlrev_b64 v[100:101], 11, v[210:211]
	v_pk_mul_f32 v[106:107], v[116:117], v[106:107]
	v_pk_mul_f32 v[108:109], v[118:119], v[108:109]
	v_cvt_pk_bf16_f32 v98, v98, v99
	v_cvt_pk_bf16_f32 v99, v104, v105
	v_lshl_add_u64 v[100:101], v[192:193], 0, v[100:101]
	v_pk_mul_f32 v[102:103], v[114:115], v[112:113]
	global_store_dwordx4 v[100:101], v[96:99], off
	s_nop 1
	v_cvt_pk_bf16_f32 v96, v106, v107
	v_cvt_pk_bf16_f32 v97, v108, v109
	v_cvt_pk_bf16_f32 v98, v110, v111
	v_cvt_pk_bf16_f32 v99, v102, v103
	global_store_dwordx4 v[100:101], v[96:99], off offset:16
.LBB0_1002:
	s_or_b64 exec, exec, s[12:13]
	v_add_u32_e32 v3, s33, v3
	v_cmp_gt_i32_e32 vcc, s3, v3
	s_and_saveexec_b64 s[12:13], vcc
	s_cbranch_execz .LBB0_1004
	s_waitcnt vmcnt(15)
	v_and_b32_e32 v101, 0xffff0000, v83
	v_and_b32_e32 v100, 0xffff0000, v79
	s_waitcnt vmcnt(11)
	v_and_b32_e32 v103, 0xffff0000, v87
	v_and_b32_e32 v102, 0xffff0000, v91
	s_waitcnt vmcnt(9)
	v_lshlrev_b32_e32 v97, 16, v95
	v_and_b32_e32 v96, 0xffff0000, v95
	v_lshlrev_b32_e32 v95, 16, v79
	v_lshlrev_b32_e32 v98, 16, v91
	v_pk_add_f32 v[100:101], v[100:101], v[102:103]
	v_add_f32_e32 v99, v95, v98
	v_lshlrev_b32_e32 v79, 16, v83
	v_lshlrev_b32_e32 v83, 16, v87
	v_mov_b32_e32 v98, v100
	v_mov_b32_e32 v102, v101
	v_lshlrev_b32_e32 v100, 16, v94
	v_and_b32_e32 v101, 0xffff0000, v94
	v_lshlrev_b32_e32 v94, 16, v90
	v_and_b32_e32 v95, 0xffff0000, v90
	v_lshlrev_b32_e32 v90, 16, v78
	v_and_b32_e32 v91, 0xffff0000, v78
	v_add_f32_e32 v103, v79, v83
	v_pk_add_f32 v[78:79], v[90:91], v[94:95]
	v_lshlrev_b32_e32 v90, 16, v82
	v_and_b32_e32 v91, 0xffff0000, v82
	v_lshlrev_b32_e32 v82, 16, v86
	v_and_b32_e32 v83, 0xffff0000, v86
	v_pk_add_f32 v[82:83], v[90:91], v[82:83]
	v_lshlrev_b32_e32 v86, 16, v89
	v_pk_add_f32 v[78:79], v[78:79], v[82:83]
	v_lshlrev_b32_e32 v82, 16, v93
	v_and_b32_e32 v83, 0xffff0000, v93
	v_and_b32_e32 v87, 0xffff0000, v89
	v_lshlrev_b32_e32 v94, 16, v77
	v_and_b32_e32 v95, 0xffff0000, v77
	v_mul_f32_e32 v77, 0xbfb8aa3b, v82
	v_pk_add_f32 v[86:87], v[94:95], v[86:87]
	v_lshlrev_b32_e32 v94, 16, v81
	v_and_b32_e32 v95, 0xffff0000, v81
	v_exp_f32_e32 v77, v77
	v_mul_f32_e32 v81, 0xbfb8aa3b, v83
	v_exp_f32_e32 v81, v81
	v_lshlrev_b32_e32 v104, 16, v85
	v_and_b32_e32 v105, 0xffff0000, v85
	v_add_f32_e32 v77, 1.0, v77
	v_pk_add_f32 v[94:95], v[94:95], v[104:105]
	v_lshlrev_b32_e32 v104, 16, v92
	v_rcp_f32_e32 v106, v77
	v_add_f32_e32 v77, 1.0, v81
	v_and_b32_e32 v105, 0xffff0000, v92
	v_mul_f32_e32 v81, 0xbfb8aa3b, v104
	v_lshlrev_b32_e32 v92, 16, v88
	v_and_b32_e32 v93, 0xffff0000, v88
	v_lshlrev_b32_e32 v88, 16, v76
	v_and_b32_e32 v89, 0xffff0000, v76
	v_exp_f32_e32 v85, v81
	v_mul_f32_e32 v81, 0xbfb8aa3b, v105
	v_rcp_f32_e32 v107, v77
	v_pk_add_f32 v[76:77], v[88:89], v[92:93]
	v_exp_f32_e32 v92, v81
	v_lshlrev_b32_e32 v88, 16, v80
	v_and_b32_e32 v89, 0xffff0000, v80
	v_lshlrev_b32_e32 v80, 16, v84
	v_and_b32_e32 v81, 0xffff0000, v84
	v_add_f32_e32 v84, 1.0, v85
	v_add_f32_e32 v85, 1.0, v92
	v_rcp_f32_e32 v84, v84
	v_rcp_f32_e32 v85, v85
	v_pk_add_f32 v[80:81], v[88:89], v[80:81]
	s_waitcnt vmcnt(8)
	v_lshlrev_b32_e32 v88, 16, v67
	v_and_b32_e32 v89, 0xffff0000, v67
	v_pk_mul_f32 v[84:85], v[84:85], v[104:105]
	v_lshlrev_b32_e32 v92, 16, v75
	v_and_b32_e32 v93, 0xffff0000, v75
	v_lshlrev_b32_e32 v104, 16, v59
	v_and_b32_e32 v105, 0xffff0000, v59
	v_mul_f32_e32 v59, 0xbfb8aa3b, v88
	v_pk_add_f32 v[92:93], v[104:105], v[92:93]
	v_lshlrev_b32_e32 v104, 16, v63
	v_and_b32_e32 v105, 0xffff0000, v63
	v_exp_f32_e32 v59, v59
	v_mul_f32_e32 v63, 0xbfb8aa3b, v89
	v_exp_f32_e32 v63, v63
	v_pk_mul_f32 v[82:83], v[106:107], v[82:83]
	v_add_f32_e32 v59, 1.0, v59
	v_rcp_f32_e32 v108, v59
	v_add_f32_e32 v59, 1.0, v63
	v_rcp_f32_e32 v109, v59
	v_lshlrev_b32_e32 v106, 16, v71
	v_and_b32_e32 v107, 0xffff0000, v71
	v_pk_add_f32 v[104:105], v[104:105], v[106:107]
	v_lshlrev_b32_e32 v106, 16, v66
	v_and_b32_e32 v107, 0xffff0000, v66
	v_lshlrev_b32_e32 v66, 16, v74
	v_and_b32_e32 v67, 0xffff0000, v74
	v_lshlrev_b32_e32 v74, 16, v58
	v_and_b32_e32 v75, 0xffff0000, v58
	v_pk_add_f32 v[58:59], v[74:75], v[66:67]
	v_lshlrev_b32_e32 v66, 16, v62
	v_and_b32_e32 v67, 0xffff0000, v62
	v_lshlrev_b32_e32 v62, 16, v70
	v_and_b32_e32 v63, 0xffff0000, v70
	v_lshlrev_b32_e32 v70, 16, v65
	v_pk_mul_f32 v[88:89], v[108:109], v[88:89]
	v_lshlrev_b32_e32 v108, 16, v57
	v_and_b32_e32 v109, 0xffff0000, v57
	v_mul_f32_e32 v57, 0xbfb8aa3b, v70
	v_exp_f32_e32 v57, v57
	v_lshlrev_b32_e32 v74, 16, v73
	v_and_b32_e32 v75, 0xffff0000, v73
	v_and_b32_e32 v71, 0xffff0000, v65
	v_pk_add_f32 v[74:75], v[108:109], v[74:75]
	v_lshlrev_b32_e32 v108, 16, v61
	v_and_b32_e32 v109, 0xffff0000, v61
	v_lshlrev_b32_e32 v110, 16, v69
	v_and_b32_e32 v111, 0xffff0000, v69
	v_add_f32_e32 v57, 1.0, v57
	v_pk_add_f32 v[108:109], v[108:109], v[110:111]
	v_rcp_f32_e32 v110, v57
	v_mul_f32_e32 v57, 0xbfb8aa3b, v71
	v_lshlrev_b32_e32 v112, 16, v72
	v_and_b32_e32 v113, 0xffff0000, v72
	v_lshlrev_b32_e32 v72, 16, v56
	v_and_b32_e32 v73, 0xffff0000, v56
	v_exp_f32_e32 v65, v57
	v_pk_add_f32 v[56:57], v[72:73], v[112:113]
	v_lshlrev_b32_e32 v72, 16, v60
	v_and_b32_e32 v73, 0xffff0000, v60
	v_lshlrev_b32_e32 v60, 16, v68
	v_and_b32_e32 v61, 0xffff0000, v68
	v_pk_add_f32 v[60:61], v[72:73], v[60:61]
	v_pk_add_f32 v[62:63], v[66:67], v[62:63]
	v_pk_add_f32 v[56:57], v[56:57], v[60:61]
	v_pk_add_f32 v[74:75], v[74:75], v[108:109]
	v_pk_mul_f32 v[60:61], v[56:57], v[56:57]
	v_pk_add_f32 v[58:59], v[58:59], v[62:63]
	v_mul_f32_e32 v62, 0xbfb8aa3b, v106
	v_pk_mul_f32 v[108:109], v[74:75], v[74:75]
	v_add_f32_e32 v60, v60, v61
	v_exp_f32_e32 v66, v62
	v_mul_f32_e32 v62, 0xbfb8aa3b, v107
	v_add_f32_e32 v60, v108, v60
	v_exp_f32_e32 v67, v62
	v_pk_mul_f32 v[62:63], v[58:59], v[58:59]
	v_add_f32_e32 v60, v109, v60
	v_pk_add_f32 v[92:93], v[92:93], v[104:105]
	v_add_f32_e32 v60, v62, v60
	v_pk_mul_f32 v[104:105], v[92:93], v[92:93]
	v_add_f32_e32 v60, v63, v60
	v_pk_add_f32 v[76:77], v[76:77], v[80:81]
	v_add_f32_e32 v60, v104, v60
	v_pk_mul_f32 v[80:81], v[76:77], v[76:77]
	v_add_f32_e32 v60, v105, v60
	v_pk_add_f32 v[86:87], v[86:87], v[94:95]
	v_add_f32_e32 v60, v80, v60
	v_pk_mul_f32 v[94:95], v[86:87], v[86:87]
	v_add_f32_e32 v60, v81, v60
	v_add_f32_e32 v60, v94, v60
	v_pk_mul_f32 v[90:91], v[78:79], v[78:79]
	v_add_f32_e32 v60, v95, v60
	v_pk_add_f32 v[98:99], v[98:99], v[102:103]
	v_add_f32_e32 v60, v90, v60
	v_pk_mul_f32 v[102:103], v[98:99], v[98:99]
	v_add_f32_e32 v60, v91, v60
	v_add_f32_e32 v60, v103, v60
	v_add_f32_e32 v62, v102, v60
	v_add_f32_e32 v60, 1.0, v65
	v_rcp_f32_e32 v111, v60
	v_lshlrev_b32_e32 v60, 16, v64
	v_and_b32_e32 v61, 0xffff0000, v64
	s_nop 1
	v_add_f32_dpp v62, v62, v62 quad_perm:[1,0,3,2] row_mask:0xf bank_mask:0xf
	v_mul_f32_e32 v64, 0xbfb8aa3b, v60
	v_exp_f32_e32 v64, v64
	v_mul_f32_e32 v65, 0xbfb8aa3b, v61
	v_exp_f32_e32 v65, v65
	s_nop 1
	v_add_f32_dpp v68, v62, v62 quad_perm:[2,3,0,1] row_mask:0xf bank_mask:0xf
	v_add_f32_e32 v62, 1.0, v64
	v_add_f32_e32 v63, 1.0, v65
	v_rcp_f32_e32 v62, v62
	v_rcp_f32_e32 v63, v63
	s_nop 1
	v_add_f32_dpp v64, v68, v68 row_half_mirror row_mask:0xf bank_mask:0xf
	v_fmamk_f32 v64, v64, 0x3c000000, v226
	v_mul_f32_e32 v65, 0x4b800000, v64
	v_cmp_gt_f32_e32 vcc, s29, v64
	v_add_f32_e32 v66, 1.0, v66
	v_add_f32_e32 v67, 1.0, v67
	v_cndmask_b32_e32 v64, v64, v65, vcc
	v_rsq_f32_e32 v68, v64
	v_pk_mul_f32 v[60:61], v[62:63], v[60:61]
	v_rcp_f32_e32 v66, v66
	v_rcp_f32_e32 v67, v67
	v_mul_f32_e32 v62, 0x45800000, v68
	v_cndmask_b32_e32 v62, v68, v62, vcc
	v_pk_mul_f32 v[56:57], v[56:57], v[62:63] op_sel_hi:[1,0]
	v_pk_mul_f32 v[58:59], v[58:59], v[62:63] op_sel_hi:[1,0]
	v_pk_mul_f32 v[56:57], v[12:13], v[56:57]
	v_pk_mul_f32 v[64:65], v[66:67], v[106:107]
	v_pk_mul_f32 v[56:57], v[60:61], v[56:57]
	v_pk_mul_f32 v[60:61], v[74:75], v[62:63] op_sel_hi:[1,0]
	v_pk_mul_f32 v[66:67], v[110:111], v[70:71]
	v_pk_mul_f32 v[60:61], v[14:15], v[60:61]
	v_pk_mul_f32 v[58:59], v[8:9], v[58:59]
	v_pk_mul_f32 v[60:61], v[66:67], v[60:61]
	v_pk_mul_f32 v[58:59], v[64:65], v[58:59]
	v_pk_mul_f32 v[64:65], v[92:93], v[62:63] op_sel_hi:[1,0]
	v_pk_mul_f32 v[66:67], v[76:77], v[62:63] op_sel_hi:[1,0]
	v_pk_mul_f32 v[68:69], v[86:87], v[62:63] op_sel_hi:[1,0]
	v_mul_f32_e32 v63, 0xbfb8aa3b, v100
	v_exp_f32_e32 v63, v63
	v_mul_f32_e32 v70, 0xbfb8aa3b, v101
	v_exp_f32_e32 v71, v70
	v_pk_mul_f32 v[64:65], v[10:11], v[64:65]
	v_add_f32_e32 v63, 1.0, v63
	v_rcp_f32_e32 v70, v63
	v_add_f32_e32 v63, 1.0, v71
	v_rcp_f32_e32 v71, v63
	v_pk_mul_f32 v[72:73], v[78:79], v[62:63] op_sel_hi:[1,0]
	v_mul_f32_e32 v63, 0xbfb8aa3b, v97
	v_pk_mul_f32 v[72:73], v[0:1], v[72:73]
	v_pk_mul_f32 v[70:71], v[70:71], v[100:101]
	v_exp_f32_e32 v63, v63
	v_pk_mul_f32 v[70:71], v[70:71], v[72:73]
	v_mul_f32_e32 v72, 0xbfb8aa3b, v96
	v_exp_f32_e32 v72, v72
	v_add_f32_e32 v63, 1.0, v63
	v_rcp_f32_e32 v63, v63
	v_mul_f32_e32 v73, v99, v62
	v_add_f32_e32 v72, 1.0, v72
	v_rcp_f32_e32 v204, v72
	v_mul_f32_e32 v74, v63, v97
	v_mul_f32_e32 v97, v98, v62
	v_ashrrev_i32_e32 v209, 31, v208
	v_pk_mul_f32 v[62:63], v[204:205], v[96:97]
	v_pk_mul_f32 v[64:65], v[88:89], v[64:65]
	v_pk_mul_f32 v[66:67], v[4:5], v[66:67]
	v_pk_mul_f32 v[68:69], v[6:7], v[68:69]
	v_mul_f32_e32 v72, v2, v73
	v_mov_b32_e32 v75, v62
	v_mov_b32_e32 v73, v63
	v_cvt_pk_bf16_f32 v56, v56, v57
	v_cvt_pk_bf16_f32 v57, v60, v61
	v_lshlrev_b64 v[60:61], 11, v[208:209]
	v_pk_mul_f32 v[66:67], v[84:85], v[66:67]
	v_pk_mul_f32 v[68:69], v[82:83], v[68:69]
	v_cvt_pk_bf16_f32 v58, v58, v59
	v_cvt_pk_bf16_f32 v59, v64, v65
	v_lshl_add_u64 v[60:61], v[192:193], 0, v[60:61]
	v_pk_mul_f32 v[62:63], v[74:75], v[72:73]
	global_store_dwordx4 v[60:61], v[56:59], off
	s_nop 1
	v_cvt_pk_bf16_f32 v56, v66, v67
	v_cvt_pk_bf16_f32 v57, v68, v69
	v_cvt_pk_bf16_f32 v58, v70, v71
	v_cvt_pk_bf16_f32 v59, v62, v63
	global_store_dwordx4 v[60:61], v[56:59], off offset:16
.LBB0_1004:
	s_or_b64 exec, exec, s[12:13]
	v_add_u32_e32 v3, s33, v3
	v_cmp_gt_i32_e32 vcc, s3, v3
	s_and_saveexec_b64 s[12:13], vcc
	s_cbranch_execz .LBB0_991
	s_waitcnt vmcnt(9)
	v_and_b32_e32 v61, 0xffff0000, v43
	v_and_b32_e32 v60, 0xffff0000, v39
	s_waitcnt vmcnt(5)
	v_and_b32_e32 v63, 0xffff0000, v47
	v_and_b32_e32 v62, 0xffff0000, v51
	s_waitcnt vmcnt(3)
	v_lshlrev_b32_e32 v57, 16, v55
	v_and_b32_e32 v56, 0xffff0000, v55
	v_lshlrev_b32_e32 v55, 16, v39
	v_lshlrev_b32_e32 v58, 16, v51
	v_pk_add_f32 v[60:61], v[60:61], v[62:63]
	v_add_f32_e32 v59, v55, v58
	v_lshlrev_b32_e32 v39, 16, v43
	v_lshlrev_b32_e32 v43, 16, v47
	v_mov_b32_e32 v58, v60
	v_mov_b32_e32 v62, v61
	v_lshlrev_b32_e32 v60, 16, v54
	v_and_b32_e32 v61, 0xffff0000, v54
	v_lshlrev_b32_e32 v54, 16, v50
	v_and_b32_e32 v55, 0xffff0000, v50
	v_lshlrev_b32_e32 v50, 16, v38
	v_and_b32_e32 v51, 0xffff0000, v38
	v_add_f32_e32 v63, v39, v43
	v_pk_add_f32 v[38:39], v[50:51], v[54:55]
	v_lshlrev_b32_e32 v50, 16, v42
	v_and_b32_e32 v51, 0xffff0000, v42
	v_lshlrev_b32_e32 v42, 16, v46
	v_and_b32_e32 v43, 0xffff0000, v46
	v_pk_add_f32 v[42:43], v[50:51], v[42:43]
	v_lshlrev_b32_e32 v46, 16, v49
	v_pk_add_f32 v[38:39], v[38:39], v[42:43]
	v_lshlrev_b32_e32 v42, 16, v53
	v_and_b32_e32 v43, 0xffff0000, v53
	v_and_b32_e32 v47, 0xffff0000, v49
	v_lshlrev_b32_e32 v54, 16, v37
	v_and_b32_e32 v55, 0xffff0000, v37
	v_mul_f32_e32 v37, 0xbfb8aa3b, v42
	v_pk_add_f32 v[46:47], v[54:55], v[46:47]
	v_lshlrev_b32_e32 v54, 16, v41
	v_and_b32_e32 v55, 0xffff0000, v41
	v_exp_f32_e32 v37, v37
	v_mul_f32_e32 v41, 0xbfb8aa3b, v43
	v_exp_f32_e32 v41, v41
	v_lshlrev_b32_e32 v64, 16, v45
	v_and_b32_e32 v65, 0xffff0000, v45
	v_add_f32_e32 v37, 1.0, v37
	v_pk_add_f32 v[54:55], v[54:55], v[64:65]
	v_lshlrev_b32_e32 v64, 16, v52
	v_rcp_f32_e32 v66, v37
	v_add_f32_e32 v37, 1.0, v41
	v_and_b32_e32 v65, 0xffff0000, v52
	v_mul_f32_e32 v41, 0xbfb8aa3b, v64
	v_lshlrev_b32_e32 v52, 16, v48
	v_and_b32_e32 v53, 0xffff0000, v48
	v_lshlrev_b32_e32 v48, 16, v36
	v_and_b32_e32 v49, 0xffff0000, v36
	v_exp_f32_e32 v45, v41
	v_mul_f32_e32 v41, 0xbfb8aa3b, v65
	v_rcp_f32_e32 v67, v37
	v_pk_add_f32 v[36:37], v[48:49], v[52:53]
	v_exp_f32_e32 v52, v41
	v_lshlrev_b32_e32 v48, 16, v40
	v_and_b32_e32 v49, 0xffff0000, v40
	v_lshlrev_b32_e32 v40, 16, v44
	v_and_b32_e32 v41, 0xffff0000, v44
	v_add_f32_e32 v44, 1.0, v45
	v_add_f32_e32 v45, 1.0, v52
	v_rcp_f32_e32 v44, v44
	v_rcp_f32_e32 v45, v45
	v_pk_add_f32 v[40:41], v[48:49], v[40:41]
	s_waitcnt vmcnt(2)
	v_lshlrev_b32_e32 v48, 16, v27
	v_and_b32_e32 v49, 0xffff0000, v27
	v_pk_mul_f32 v[44:45], v[44:45], v[64:65]
	v_lshlrev_b32_e32 v52, 16, v35
	v_and_b32_e32 v53, 0xffff0000, v35
	v_lshlrev_b32_e32 v64, 16, v19
	v_and_b32_e32 v65, 0xffff0000, v19
	v_mul_f32_e32 v19, 0xbfb8aa3b, v48
	v_pk_add_f32 v[52:53], v[64:65], v[52:53]
	v_lshlrev_b32_e32 v64, 16, v23
	v_and_b32_e32 v65, 0xffff0000, v23
	v_exp_f32_e32 v19, v19
	v_mul_f32_e32 v23, 0xbfb8aa3b, v49
	v_exp_f32_e32 v23, v23
	v_pk_mul_f32 v[42:43], v[66:67], v[42:43]
	v_add_f32_e32 v19, 1.0, v19
	v_rcp_f32_e32 v68, v19
	v_add_f32_e32 v19, 1.0, v23
	v_rcp_f32_e32 v69, v19
	v_lshlrev_b32_e32 v66, 16, v31
	v_and_b32_e32 v67, 0xffff0000, v31
	v_pk_add_f32 v[64:65], v[64:65], v[66:67]
	v_lshlrev_b32_e32 v66, 16, v26
	v_and_b32_e32 v67, 0xffff0000, v26
	v_lshlrev_b32_e32 v26, 16, v34
	v_and_b32_e32 v27, 0xffff0000, v34
	v_lshlrev_b32_e32 v34, 16, v18
	v_and_b32_e32 v35, 0xffff0000, v18
	v_pk_add_f32 v[18:19], v[34:35], v[26:27]
	v_lshlrev_b32_e32 v26, 16, v22
	v_and_b32_e32 v27, 0xffff0000, v22
	v_lshlrev_b32_e32 v22, 16, v30
	v_and_b32_e32 v23, 0xffff0000, v30
	v_lshlrev_b32_e32 v30, 16, v25
	v_pk_mul_f32 v[48:49], v[68:69], v[48:49]
	v_lshlrev_b32_e32 v68, 16, v17
	v_and_b32_e32 v69, 0xffff0000, v17
	v_mul_f32_e32 v17, 0xbfb8aa3b, v30
	v_exp_f32_e32 v17, v17
	v_lshlrev_b32_e32 v34, 16, v33
	v_and_b32_e32 v35, 0xffff0000, v33
	v_and_b32_e32 v31, 0xffff0000, v25
	v_pk_add_f32 v[34:35], v[68:69], v[34:35]
	v_lshlrev_b32_e32 v68, 16, v21
	v_and_b32_e32 v69, 0xffff0000, v21
	v_lshlrev_b32_e32 v70, 16, v29
	v_and_b32_e32 v71, 0xffff0000, v29
	v_add_f32_e32 v17, 1.0, v17
	v_pk_add_f32 v[68:69], v[68:69], v[70:71]
	v_rcp_f32_e32 v70, v17
	v_mul_f32_e32 v17, 0xbfb8aa3b, v31
	v_lshlrev_b32_e32 v72, 16, v32
	v_and_b32_e32 v73, 0xffff0000, v32
	v_lshlrev_b32_e32 v32, 16, v16
	v_and_b32_e32 v33, 0xffff0000, v16
	v_exp_f32_e32 v25, v17
	v_pk_add_f32 v[16:17], v[32:33], v[72:73]
	v_lshlrev_b32_e32 v32, 16, v20
	v_and_b32_e32 v33, 0xffff0000, v20
	v_lshlrev_b32_e32 v20, 16, v28
	v_and_b32_e32 v21, 0xffff0000, v28
	v_pk_add_f32 v[20:21], v[32:33], v[20:21]
	v_pk_add_f32 v[22:23], v[26:27], v[22:23]
	v_pk_add_f32 v[16:17], v[16:17], v[20:21]
	v_pk_add_f32 v[34:35], v[34:35], v[68:69]
	v_pk_mul_f32 v[20:21], v[16:17], v[16:17]
	v_pk_add_f32 v[18:19], v[18:19], v[22:23]
	v_mul_f32_e32 v22, 0xbfb8aa3b, v66
	v_pk_mul_f32 v[68:69], v[34:35], v[34:35]
	v_add_f32_e32 v20, v20, v21
	v_exp_f32_e32 v26, v22
	v_mul_f32_e32 v22, 0xbfb8aa3b, v67
	v_add_f32_e32 v20, v68, v20
	v_exp_f32_e32 v27, v22
	v_pk_mul_f32 v[22:23], v[18:19], v[18:19]
	v_add_f32_e32 v20, v69, v20
	v_pk_add_f32 v[52:53], v[52:53], v[64:65]
	v_add_f32_e32 v20, v22, v20
	v_pk_mul_f32 v[64:65], v[52:53], v[52:53]
	v_add_f32_e32 v20, v23, v20
	v_pk_add_f32 v[36:37], v[36:37], v[40:41]
	v_add_f32_e32 v20, v64, v20
	v_pk_mul_f32 v[40:41], v[36:37], v[36:37]
	v_add_f32_e32 v20, v65, v20
	v_pk_add_f32 v[46:47], v[46:47], v[54:55]
	v_add_f32_e32 v20, v40, v20
	v_pk_mul_f32 v[54:55], v[46:47], v[46:47]
	v_add_f32_e32 v20, v41, v20
	v_add_f32_e32 v20, v54, v20
	v_pk_mul_f32 v[50:51], v[38:39], v[38:39]
	v_add_f32_e32 v20, v55, v20
	v_pk_add_f32 v[58:59], v[58:59], v[62:63]
	v_add_f32_e32 v20, v50, v20
	v_pk_mul_f32 v[62:63], v[58:59], v[58:59]
	v_add_f32_e32 v20, v51, v20
	v_add_f32_e32 v20, v63, v20
	v_add_f32_e32 v22, v62, v20
	v_add_f32_e32 v20, 1.0, v25
	v_rcp_f32_e32 v71, v20
	v_lshlrev_b32_e32 v20, 16, v24
	v_and_b32_e32 v21, 0xffff0000, v24
	s_nop 1
	v_add_f32_dpp v22, v22, v22 quad_perm:[1,0,3,2] row_mask:0xf bank_mask:0xf
	v_mul_f32_e32 v24, 0xbfb8aa3b, v20
	v_exp_f32_e32 v24, v24
	v_mul_f32_e32 v25, 0xbfb8aa3b, v21
	v_exp_f32_e32 v25, v25
	s_nop 1
	v_add_f32_dpp v28, v22, v22 quad_perm:[2,3,0,1] row_mask:0xf bank_mask:0xf
	v_add_f32_e32 v22, 1.0, v24
	v_add_f32_e32 v23, 1.0, v25
	v_rcp_f32_e32 v22, v22
	v_rcp_f32_e32 v23, v23
	s_nop 1
	v_add_f32_dpp v24, v28, v28 row_half_mirror row_mask:0xf bank_mask:0xf
	v_fmamk_f32 v24, v24, 0x3c000000, v226
	v_mul_f32_e32 v25, 0x4b800000, v24
	v_cmp_gt_f32_e32 vcc, s29, v24
	v_add_f32_e32 v26, 1.0, v26
	v_add_f32_e32 v27, 1.0, v27
	v_cndmask_b32_e32 v24, v24, v25, vcc
	v_rsq_f32_e32 v28, v24
	v_pk_mul_f32 v[20:21], v[22:23], v[20:21]
	v_rcp_f32_e32 v26, v26
	v_rcp_f32_e32 v27, v27
	v_mul_f32_e32 v22, 0x45800000, v28
	v_cndmask_b32_e32 v22, v28, v22, vcc
	v_pk_mul_f32 v[16:17], v[16:17], v[22:23] op_sel_hi:[1,0]
	v_pk_mul_f32 v[18:19], v[18:19], v[22:23] op_sel_hi:[1,0]
	v_pk_mul_f32 v[16:17], v[12:13], v[16:17]
	v_pk_mul_f32 v[24:25], v[26:27], v[66:67]
	v_pk_mul_f32 v[16:17], v[20:21], v[16:17]
	v_pk_mul_f32 v[20:21], v[34:35], v[22:23] op_sel_hi:[1,0]
	v_pk_mul_f32 v[26:27], v[70:71], v[30:31]
	v_pk_mul_f32 v[20:21], v[14:15], v[20:21]
	v_pk_mul_f32 v[18:19], v[8:9], v[18:19]
	v_pk_mul_f32 v[20:21], v[26:27], v[20:21]
	v_pk_mul_f32 v[18:19], v[24:25], v[18:19]
	v_pk_mul_f32 v[24:25], v[52:53], v[22:23] op_sel_hi:[1,0]
	v_pk_mul_f32 v[26:27], v[36:37], v[22:23] op_sel_hi:[1,0]
	v_pk_mul_f32 v[28:29], v[46:47], v[22:23] op_sel_hi:[1,0]
	v_mul_f32_e32 v23, 0xbfb8aa3b, v60
	v_exp_f32_e32 v23, v23
	v_mul_f32_e32 v30, 0xbfb8aa3b, v61
	v_exp_f32_e32 v31, v30
	v_pk_mul_f32 v[24:25], v[10:11], v[24:25]
	v_add_f32_e32 v23, 1.0, v23
	v_rcp_f32_e32 v30, v23
	v_add_f32_e32 v23, 1.0, v31
	v_rcp_f32_e32 v31, v23
	v_pk_mul_f32 v[32:33], v[38:39], v[22:23] op_sel_hi:[1,0]
	v_mul_f32_e32 v23, 0xbfb8aa3b, v57
	v_pk_mul_f32 v[32:33], v[0:1], v[32:33]
	v_pk_mul_f32 v[30:31], v[30:31], v[60:61]
	v_exp_f32_e32 v23, v23
	v_pk_mul_f32 v[30:31], v[30:31], v[32:33]
	v_mul_f32_e32 v32, 0xbfb8aa3b, v56
	v_exp_f32_e32 v32, v32
	v_add_f32_e32 v23, 1.0, v23
	v_rcp_f32_e32 v23, v23
	v_mul_f32_e32 v33, v59, v22
	v_add_f32_e32 v32, 1.0, v32
	v_rcp_f32_e32 v204, v32
	v_mul_f32_e32 v34, v23, v57
	v_mul_f32_e32 v57, v58, v22
	v_ashrrev_i32_e32 v207, 31, v206
	v_pk_mul_f32 v[22:23], v[204:205], v[56:57]
	v_pk_mul_f32 v[24:25], v[48:49], v[24:25]
	v_pk_mul_f32 v[26:27], v[4:5], v[26:27]
	v_pk_mul_f32 v[28:29], v[6:7], v[28:29]
	v_mul_f32_e32 v32, v2, v33
	v_mov_b32_e32 v35, v22
	v_mov_b32_e32 v33, v23
	v_cvt_pk_bf16_f32 v16, v16, v17
	v_cvt_pk_bf16_f32 v17, v20, v21
	v_lshlrev_b64 v[20:21], 11, v[206:207]
	v_pk_mul_f32 v[26:27], v[44:45], v[26:27]
	v_pk_mul_f32 v[28:29], v[42:43], v[28:29]
	v_cvt_pk_bf16_f32 v18, v18, v19
	v_cvt_pk_bf16_f32 v19, v24, v25
	v_lshl_add_u64 v[20:21], v[192:193], 0, v[20:21]
	v_pk_mul_f32 v[22:23], v[34:35], v[32:33]
	global_store_dwordx4 v[20:21], v[16:19], off
	s_nop 1
	v_cvt_pk_bf16_f32 v16, v26, v27
	v_cvt_pk_bf16_f32 v17, v28, v29
	v_cvt_pk_bf16_f32 v18, v30, v31
	v_cvt_pk_bf16_f32 v19, v22, v23
	global_store_dwordx4 v[20:21], v[16:19], off offset:16
	s_branch .LBB0_991

.LBB0_1130:
	s_or_b64 exec, exec, s[40:41]
	v_mov_b32_e32 v60, v45
	v_mov_b32_e32 v61, v41
	v_mov_b32_e32 v58, v44
	v_mov_b32_e32 v59, v40
	v_pk_mul_f32 v[60:61], v[60:61], v[60:61]
	v_mov_b32_e32 v62, v37
	v_pk_fma_f32 v[58:59], v[58:59], v[58:59], v[60:61]
	v_mov_b32_e32 v60, v46
	v_mov_b32_e32 v61, v42
	v_pk_fma_f32 v[58:59], v[60:61], v[60:61], v[58:59]
	v_mov_b32_e32 v60, v47
	v_mov_b32_e32 v61, v43
	v_mov_b32_e32 v63, v33
	v_pk_fma_f32 v[58:59], v[60:61], v[60:61], v[58:59]
	v_mov_b32_e32 v60, v36
	v_mov_b32_e32 v61, v32
	v_pk_mul_f32 v[62:63], v[62:63], v[62:63]
	v_add_f32_e32 v58, v58, v59
	v_pk_fma_f32 v[60:61], v[60:61], v[60:61], v[62:63]
	v_mov_b32_e32 v62, v38
	v_mov_b32_e32 v63, v34
	v_pk_fma_f32 v[60:61], v[62:63], v[62:63], v[60:61]
	v_mov_b32_e32 v62, v39
	v_mov_b32_e32 v63, v35
	v_pk_fma_f32 v[60:61], v[62:63], v[62:63], v[60:61]
	v_lshl_add_u64 v[56:57], v[132:133], 0, v[56:57]
	v_add_f32_e32 v58, v58, v60
	v_add_f32_e32 v58, v58, v61
	v_mov_b32_e32 v59, v58
	v_pk_add_f32 v[60:61], v[20:21], 1.0 op_sel_hi:[1,0]
	s_nop 1
	v_permlane32_swap_b32_e32 v59, v58
	s_nop 1
	v_add_f32_e32 v58, v58, v59
	v_mov_b32_e32 v59, v58
	s_nop 1
	v_permlane16_swap_b32_e32 v59, v58
	s_nop 1
	v_add_f32_e32 v58, v58, v59
	s_nop 1
	v_add_f32_dpp v58, v58, v58 row_ror:8 row_mask:0xf bank_mask:0xf
	s_nop 1
	v_add_f32_dpp v58, v58, v58 row_ror:4 row_mask:0xf bank_mask:0xf
	s_nop 1
	v_add_f32_dpp v58, v58, v58 quad_perm:[2,3,0,1] row_mask:0xf bank_mask:0xf
	s_nop 1
	v_add_f32_dpp v58, v58, v58 quad_perm:[1,0,3,2] row_mask:0xf bank_mask:0xf
	v_fmamk_f32 v58, v58, 0x3a800000, v234
	v_mul_f32_e32 v59, 0x4b800000, v58
	v_cmp_gt_f32_e32 vcc, s28, v58
	s_nop 1
	v_cndmask_b32_e32 v58, v58, v59, vcc
	v_rsq_f32_e32 v62, v58
	v_pk_add_f32 v[58:59], v[22:23], 1.0 op_sel_hi:[1,0]
	v_mul_f32_e32 v63, 0x45800000, v62
	v_cndmask_b32_e32 v62, v62, v63, vcc
	v_pk_mul_f32 v[46:47], v[46:47], v[62:63] op_sel_hi:[1,0]
	v_pk_mul_f32 v[44:45], v[44:45], v[62:63] op_sel_hi:[1,0]
	v_pk_mul_f32 v[46:47], v[10:11], v[46:47]
	v_pk_mul_f32 v[44:45], v[8:9], v[44:45]
	v_pk_fma_f32 v[46:47], v[58:59], v[46:47], v[18:19]
	v_pk_fma_f32 v[44:45], v[60:61], v[44:45], v[16:17]
	v_pk_mul_f32 v[42:43], v[42:43], v[62:63] op_sel_hi:[1,0]
	v_cvt_pk_bf16_f32 v44, v44, v45
	v_cvt_pk_bf16_f32 v45, v46, v47
	v_pk_mul_f32 v[40:41], v[40:41], v[62:63] op_sel_hi:[1,0]
	global_store_dwordx2 v[56:57], v[44:45], off
	v_pk_mul_f32 v[40:41], v[0:1], v[40:41]
	v_pk_mul_f32 v[42:43], v[2:3], v[42:43]
	v_pk_add_f32 v[44:45], v[30:31], 1.0 op_sel_hi:[1,0]
	v_pk_add_f32 v[46:47], v[28:29], 1.0 op_sel_hi:[1,0]
	v_pk_fma_f32 v[42:43], v[44:45], v[42:43], v[26:27]
	v_pk_fma_f32 v[40:41], v[46:47], v[40:41], v[24:25]
	v_pk_mul_f32 v[38:39], v[38:39], v[62:63] op_sel_hi:[1,0]
	v_cvt_pk_bf16_f32 v40, v40, v41
	v_cvt_pk_bf16_f32 v41, v42, v43
	v_pk_mul_f32 v[36:37], v[36:37], v[62:63] op_sel_hi:[1,0]
	global_store_dwordx2 v[56:57], v[40:41], off offset:512
	v_pk_mul_f32 v[36:37], v[4:5], v[36:37]
	v_pk_mul_f32 v[38:39], v[6:7], v[38:39]
	v_pk_add_f32 v[40:41], v[54:55], 1.0 op_sel_hi:[1,0]
	v_pk_add_f32 v[42:43], v[52:53], 1.0 op_sel_hi:[1,0]
	v_pk_fma_f32 v[38:39], v[40:41], v[38:39], v[50:51]
	v_pk_fma_f32 v[36:37], v[42:43], v[36:37], v[48:49]
	v_pk_mul_f32 v[34:35], v[34:35], v[62:63] op_sel_hi:[1,0]
	v_cvt_pk_bf16_f32 v36, v36, v37
	v_cvt_pk_bf16_f32 v37, v38, v39
	v_pk_mul_f32 v[32:33], v[32:33], v[62:63] op_sel_hi:[1,0]
	global_store_dwordx2 v[56:57], v[36:37], off offset:1024
	v_pk_mul_f32 v[32:33], v[12:13], v[32:33]
	v_pk_mul_f32 v[34:35], v[14:15], v[34:35]
	v_pk_add_f32 v[36:37], v[78:79], 1.0 op_sel_hi:[1,0]
	v_pk_add_f32 v[38:39], v[76:77], 1.0 op_sel_hi:[1,0]
	v_pk_fma_f32 v[34:35], v[36:37], v[34:35], v[74:75]
	v_pk_fma_f32 v[32:33], v[38:39], v[32:33], v[72:73]
	s_nop 0
	v_cvt_pk_bf16_f32 v32, v32, v33
	v_cvt_pk_bf16_f32 v33, v34, v35
	global_store_dwordx2 v[56:57], v[32:33], off offset:1536

.LBB0_1142:
	s_or_b64 exec, exec, s[6:7]
	v_mov_b32_e32 v236, v217
	v_mov_b32_e32 v237, v213
	v_mov_b32_e32 v222, v216
	v_mov_b32_e32 v223, v212
	v_pk_mul_f32 v[236:237], v[236:237], v[236:237]
	v_mov_b32_e32 v238, v209
	v_pk_fma_f32 v[222:223], v[222:223], v[222:223], v[236:237]
	v_mov_b32_e32 v236, v218
	v_mov_b32_e32 v237, v214
	v_pk_fma_f32 v[222:223], v[236:237], v[236:237], v[222:223]
	v_mov_b32_e32 v236, v219
	v_mov_b32_e32 v237, v215
	v_mov_b32_e32 v239, v205
	v_pk_fma_f32 v[222:223], v[236:237], v[236:237], v[222:223]
	v_mov_b32_e32 v236, v208
	v_mov_b32_e32 v237, v204
	v_pk_mul_f32 v[238:239], v[238:239], v[238:239]
	v_add_f32_e32 v129, v222, v223
	v_pk_fma_f32 v[236:237], v[236:237], v[236:237], v[238:239]
	v_mov_b32_e32 v238, v210
	v_mov_b32_e32 v239, v206
	v_pk_fma_f32 v[236:237], v[238:239], v[238:239], v[236:237]
	v_mov_b32_e32 v238, v211
	v_mov_b32_e32 v239, v207
	v_pk_fma_f32 v[236:237], v[238:239], v[238:239], v[236:237]
	v_pk_add_f32 v[222:223], v[20:21], 1.0 op_sel_hi:[1,0]
	v_add_f32_e32 v129, v129, v236
	v_add_f32_e32 v129, v129, v237
	v_mov_b32_e32 v155, v129
	v_lshl_add_u64 v[236:237], v[132:133], 0, v[220:221]
	v_pk_add_f32 v[220:221], v[22:23], 1.0 op_sel_hi:[1,0]
	s_nop 1
	v_permlane32_swap_b32_e32 v155, v129
	s_nop 1
	v_add_f32_e32 v129, v129, v155
	v_mov_b32_e32 v155, v129
	s_nop 1
	v_permlane16_swap_b32_e32 v155, v129
	s_nop 1
	v_add_f32_e32 v129, v129, v155
	s_nop 1
	v_add_f32_dpp v129, v129, v129 row_ror:8 row_mask:0xf bank_mask:0xf
	s_nop 1
	v_add_f32_dpp v129, v129, v129 row_ror:4 row_mask:0xf bank_mask:0xf
	s_nop 1
	v_add_f32_dpp v129, v129, v129 quad_perm:[2,3,0,1] row_mask:0xf bank_mask:0xf
	s_nop 1
	v_add_f32_dpp v129, v129, v129 quad_perm:[1,0,3,2] row_mask:0xf bank_mask:0xf
	v_fmamk_f32 v129, v129, 0x3a800000, v234
	v_mul_f32_e32 v155, 0x4b800000, v129
	v_cmp_gt_f32_e32 vcc, s28, v129
	s_nop 1
	v_cndmask_b32_e32 v129, v129, v155, vcc
	v_rsq_f32_e32 v129, v129
	s_nop 0
	v_mul_f32_e32 v155, 0x45800000, v129
	v_cndmask_b32_e32 v238, v129, v155, vcc
	v_pk_mul_f32 v[218:219], v[218:219], v[238:239] op_sel_hi:[1,0]
	v_pk_mul_f32 v[216:217], v[216:217], v[238:239] op_sel_hi:[1,0]
	v_pk_mul_f32 v[218:219], v[10:11], v[218:219]
	v_pk_mul_f32 v[216:217], v[8:9], v[216:217]
	v_pk_fma_f32 v[218:219], v[220:221], v[218:219], v[18:19]
	v_pk_fma_f32 v[216:217], v[222:223], v[216:217], v[16:17]
	v_pk_mul_f32 v[214:215], v[214:215], v[238:239] op_sel_hi:[1,0]
	v_cvt_pk_bf16_f32 v216, v216, v217
	v_cvt_pk_bf16_f32 v217, v218, v219
	v_pk_mul_f32 v[212:213], v[212:213], v[238:239] op_sel_hi:[1,0]
	global_store_dwordx2 v[236:237], v[216:217], off
	v_pk_mul_f32 v[216:217], v[0:1], v[212:213]
	v_pk_mul_f32 v[218:219], v[2:3], v[214:215]
	v_pk_add_f32 v[212:213], v[30:31], 1.0 op_sel_hi:[1,0]
	v_pk_add_f32 v[214:215], v[28:29], 1.0 op_sel_hi:[1,0]
	v_pk_fma_f32 v[218:219], v[212:213], v[218:219], v[26:27]
	v_pk_fma_f32 v[216:217], v[214:215], v[216:217], v[24:25]
	v_pk_mul_f32 v[210:211], v[210:211], v[238:239] op_sel_hi:[1,0]
	v_cvt_pk_bf16_f32 v216, v216, v217
	v_cvt_pk_bf16_f32 v217, v218, v219
	v_pk_mul_f32 v[208:209], v[208:209], v[238:239] op_sel_hi:[1,0]
	global_store_dwordx2 v[236:237], v[216:217], off offset:512
	v_pk_mul_f32 v[216:217], v[4:5], v[208:209]
	v_pk_mul_f32 v[218:219], v[6:7], v[210:211]
	v_pk_add_f32 v[208:209], v[54:55], 1.0 op_sel_hi:[1,0]
	v_pk_add_f32 v[210:211], v[52:53], 1.0 op_sel_hi:[1,0]
	v_pk_fma_f32 v[218:219], v[208:209], v[218:219], v[50:51]
	v_pk_fma_f32 v[216:217], v[210:211], v[216:217], v[48:49]
	v_pk_mul_f32 v[206:207], v[206:207], v[238:239] op_sel_hi:[1,0]
	v_cvt_pk_bf16_f32 v216, v216, v217
	v_cvt_pk_bf16_f32 v217, v218, v219
	v_pk_mul_f32 v[204:205], v[204:205], v[238:239] op_sel_hi:[1,0]
	global_store_dwordx2 v[236:237], v[216:217], off offset:1024
	v_pk_mul_f32 v[216:217], v[12:13], v[204:205]
	v_pk_mul_f32 v[218:219], v[14:15], v[206:207]
	v_pk_add_f32 v[204:205], v[78:79], 1.0 op_sel_hi:[1,0]
	v_pk_add_f32 v[206:207], v[76:77], 1.0 op_sel_hi:[1,0]
	v_pk_fma_f32 v[218:219], v[204:205], v[218:219], v[74:75]
	v_pk_fma_f32 v[216:217], v[206:207], v[216:217], v[72:73]
	v_cmp_lt_i32_e32 vcc, v194, v226
	v_cvt_pk_bf16_f32 v216, v216, v217
	v_cvt_pk_bf16_f32 v217, v218, v219
	global_store_dwordx2 v[236:237], v[216:217], off offset:1536
	s_and_saveexec_b64 s[6:7], vcc
	s_cbranch_execz .LBB0_1167
	s_waitcnt vmcnt(43)
	v_lshlrev_b32_e32 v216, 16, v202
	v_and_b32_e32 v217, 0xffff0000, v202
	v_lshlrev_b32_e32 v202, 16, v203
	v_and_b32_e32 v203, 0xffff0000, v203
	v_pk_add_f32 v[126:127], v[126:127], v[202:203]
	s_waitcnt vmcnt(42)
	v_lshlrev_b32_e32 v202, 16, v200
	v_and_b32_e32 v203, 0xffff0000, v200
	v_lshlrev_b32_e32 v200, 16, v201
	v_and_b32_e32 v201, 0xffff0000, v201
	v_pk_add_f32 v[122:123], v[122:123], v[200:201]
	s_waitcnt vmcnt(41)
	v_lshlrev_b32_e32 v200, 16, v198
	v_and_b32_e32 v201, 0xffff0000, v198
	v_lshlrev_b32_e32 v198, 16, v199
	v_and_b32_e32 v199, 0xffff0000, v199
	v_ashrrev_i32_e32 v195, 31, v194
	v_pk_add_f32 v[124:125], v[124:125], v[216:217]
	v_pk_add_f32 v[118:119], v[118:119], v[198:199]
	s_waitcnt vmcnt(40)
	v_lshlrev_b32_e32 v198, 16, v196
	v_and_b32_e32 v199, 0xffff0000, v196
	v_lshlrev_b32_e32 v196, 16, v197
	v_and_b32_e32 v197, 0xffff0000, v197
	v_add_u32_e32 v129, 0xffffe001, v128
	v_lshlrev_b64 v[194:195], 11, v[194:195]
	v_pk_add_f32 v[120:121], v[120:121], v[202:203]
	v_pk_add_f32 v[114:115], v[114:115], v[196:197]
	v_pk_add_f32 v[112:113], v[112:113], v[198:199]
	v_ashrrev_i32_e32 v129, 10, v129
	v_lshl_add_u64 v[196:197], v[134:135], 0, v[194:195]
	v_cvt_pk_bf16_f32 v198, v124, v125
	v_cvt_pk_bf16_f32 v199, v126, v127
	v_pk_add_f32 v[116:117], v[116:117], v[200:201]
	v_add_u32_e32 v129, 1, v129
	v_cmp_lt_i32_e32 vcc, s29, v128
	global_store_dwordx2 v[196:197], v[198:199], off
	v_cvt_pk_bf16_f32 v198, v120, v121
	v_cvt_pk_bf16_f32 v199, v122, v123
	v_cndmask_b32_e32 v129, 0, v129, vcc
	global_store_dwordx2 v[196:197], v[198:199], off offset:512
	v_cvt_pk_bf16_f32 v198, v116, v117
	v_cvt_pk_bf16_f32 v199, v118, v119
	global_store_dwordx2 v[196:197], v[198:199], off offset:1024
	v_cvt_pk_bf16_f32 v198, v112, v113
	v_cvt_pk_bf16_f32 v199, v114, v115
	v_cmp_ne_u32_e32 vcc, v129, v235
	global_store_dwordx2 v[196:197], v[198:199], off offset:1536
	s_and_saveexec_b64 s[40:41], vcc
	s_cbranch_execz .LBB0_1153
	global_load_dwordx4 v[16:19], v[136:137], off
	global_load_dwordx4 v[20:23], v[138:139], off
	v_mad_i64_i32 v[196:197], s[42:43], v129, s16, v[152:153]
	s_mov_b64 s[42:43], 0

.LBB0_1153:
	s_or_b64 exec, exec, s[40:41]
	v_mov_b32_e32 v198, v125
	v_mov_b32_e32 v199, v121
	v_mov_b32_e32 v196, v124
	v_mov_b32_e32 v197, v120
	v_pk_mul_f32 v[198:199], v[198:199], v[198:199]
	v_mov_b32_e32 v200, v117
	v_pk_fma_f32 v[196:197], v[196:197], v[196:197], v[198:199]
	v_mov_b32_e32 v198, v126
	v_mov_b32_e32 v199, v122
	v_pk_fma_f32 v[196:197], v[198:199], v[198:199], v[196:197]
	v_mov_b32_e32 v198, v127
	v_mov_b32_e32 v199, v123
	v_mov_b32_e32 v201, v113
	v_pk_fma_f32 v[196:197], v[198:199], v[198:199], v[196:197]
	v_mov_b32_e32 v198, v116
	v_mov_b32_e32 v199, v112
	v_pk_mul_f32 v[200:201], v[200:201], v[200:201]
	v_add_f32_e32 v129, v196, v197
	v_pk_fma_f32 v[198:199], v[198:199], v[198:199], v[200:201]
	v_mov_b32_e32 v200, v118
	v_mov_b32_e32 v201, v114
	v_pk_fma_f32 v[198:199], v[200:201], v[200:201], v[198:199]
	v_mov_b32_e32 v200, v119
	v_mov_b32_e32 v201, v115
	v_pk_fma_f32 v[198:199], v[200:201], v[200:201], v[198:199]
	v_lshl_add_u64 v[194:195], v[132:133], 0, v[194:195]
	v_add_f32_e32 v129, v129, v198
	v_add_f32_e32 v129, v129, v199
	v_mov_b32_e32 v155, v129
	s_nop 1
	v_permlane32_swap_b32_e32 v155, v129
	s_nop 1
	v_add_f32_e32 v129, v129, v155
	v_mov_b32_e32 v155, v129
	s_nop 1
	v_permlane16_swap_b32_e32 v155, v129
	s_nop 1
	v_add_f32_e32 v129, v129, v155
	s_nop 1
	v_add_f32_dpp v129, v129, v129 row_ror:8 row_mask:0xf bank_mask:0xf
	s_nop 1
	v_add_f32_dpp v129, v129, v129 row_ror:4 row_mask:0xf bank_mask:0xf
	s_nop 1
	v_add_f32_dpp v129, v129, v129 quad_perm:[2,3,0,1] row_mask:0xf bank_mask:0xf
	s_nop 1
	v_add_f32_dpp v129, v129, v129 quad_perm:[1,0,3,2] row_mask:0xf bank_mask:0xf
	v_fmamk_f32 v129, v129, 0x3a800000, v234
	v_mul_f32_e32 v155, 0x4b800000, v129
	v_cmp_gt_f32_e32 vcc, s28, v129
	s_nop 1
	v_cndmask_b32_e32 v129, v129, v155, vcc
	v_rsq_f32_e32 v129, v129
	s_nop 0
	v_mul_f32_e32 v155, 0x45800000, v129
	v_cndmask_b32_e32 v196, v129, v155, vcc
	v_pk_mul_f32 v[126:127], v[126:127], v[196:197] op_sel_hi:[1,0]
	v_pk_mul_f32 v[124:125], v[124:125], v[196:197] op_sel_hi:[1,0]
	v_pk_mul_f32 v[122:123], v[122:123], v[196:197] op_sel_hi:[1,0]
	v_pk_mul_f32 v[120:121], v[120:121], v[196:197] op_sel_hi:[1,0]
	v_pk_mul_f32 v[118:119], v[118:119], v[196:197] op_sel_hi:[1,0]
	v_pk_mul_f32 v[116:117], v[116:117], v[196:197] op_sel_hi:[1,0]
	v_pk_mul_f32 v[114:115], v[114:115], v[196:197] op_sel_hi:[1,0]
	v_pk_mul_f32 v[112:113], v[112:113], v[196:197] op_sel_hi:[1,0]
	v_pk_mul_f32 v[124:125], v[8:9], v[124:125]
	v_pk_mul_f32 v[126:127], v[10:11], v[126:127]
	v_pk_mul_f32 v[120:121], v[0:1], v[120:121]
	v_pk_mul_f32 v[122:123], v[2:3], v[122:123]
	v_pk_mul_f32 v[116:117], v[4:5], v[116:117]
	v_pk_mul_f32 v[118:119], v[6:7], v[118:119]
	v_pk_mul_f32 v[112:113], v[12:13], v[112:113]
	v_pk_mul_f32 v[114:115], v[14:15], v[114:115]
	v_pk_fma_f32 v[126:127], v[220:221], v[126:127], v[18:19]
	v_pk_fma_f32 v[124:125], v[222:223], v[124:125], v[16:17]
	v_pk_fma_f32 v[122:123], v[212:213], v[122:123], v[26:27]
	v_pk_fma_f32 v[120:121], v[214:215], v[120:121], v[24:25]
	v_pk_fma_f32 v[118:119], v[208:209], v[118:119], v[50:51]
	v_pk_fma_f32 v[116:117], v[210:211], v[116:117], v[48:49]
	v_pk_fma_f32 v[114:115], v[204:205], v[114:115], v[74:75]
	v_pk_fma_f32 v[112:113], v[206:207], v[112:113], v[72:73]
	v_cvt_pk_bf16_f32 v124, v124, v125
	v_cvt_pk_bf16_f32 v125, v126, v127
	v_cvt_pk_bf16_f32 v120, v120, v121
	v_cvt_pk_bf16_f32 v121, v122, v123
	v_cvt_pk_bf16_f32 v116, v116, v117
	v_cvt_pk_bf16_f32 v117, v118, v119
	v_cvt_pk_bf16_f32 v112, v112, v113
	v_cvt_pk_bf16_f32 v113, v114, v115
	global_store_dwordx2 v[194:195], v[124:125], off
	global_store_dwordx2 v[194:195], v[120:121], off offset:512
	global_store_dwordx2 v[194:195], v[116:117], off offset:1024
	global_store_dwordx2 v[194:195], v[112:113], off offset:1536
	s_or_b64 exec, exec, s[6:7]
	v_cmp_lt_i32_e32 vcc, v184, v226
	s_and_saveexec_b64 s[6:7], vcc
	s_cbranch_execnz .LBB0_1168

.LBB0_1165:
	s_or_b64 exec, exec, s[40:41]
	v_mov_b32_e32 v100, v93
	v_mov_b32_e32 v101, v89
	v_mov_b32_e32 v98, v92
	v_mov_b32_e32 v99, v88
	v_pk_mul_f32 v[100:101], v[100:101], v[100:101]
	v_mov_b32_e32 v102, v85
	v_pk_fma_f32 v[98:99], v[98:99], v[98:99], v[100:101]
	v_mov_b32_e32 v100, v94
	v_mov_b32_e32 v101, v90
	v_pk_fma_f32 v[98:99], v[100:101], v[100:101], v[98:99]
	v_mov_b32_e32 v100, v95
	v_mov_b32_e32 v101, v91
	v_mov_b32_e32 v103, v81
	v_pk_fma_f32 v[98:99], v[100:101], v[100:101], v[98:99]
	v_mov_b32_e32 v100, v84
	v_mov_b32_e32 v101, v80
	v_pk_mul_f32 v[102:103], v[102:103], v[102:103]
	v_add_f32_e32 v98, v98, v99
	v_pk_fma_f32 v[100:101], v[100:101], v[100:101], v[102:103]
	v_mov_b32_e32 v102, v86
	v_mov_b32_e32 v103, v82
	v_pk_fma_f32 v[100:101], v[102:103], v[102:103], v[100:101]
	v_mov_b32_e32 v102, v87
	v_mov_b32_e32 v103, v83
	v_pk_fma_f32 v[100:101], v[102:103], v[102:103], v[100:101]
	v_lshl_add_u64 v[96:97], v[132:133], 0, v[96:97]
	v_add_f32_e32 v98, v98, v100
	v_add_f32_e32 v98, v98, v101
	v_mov_b32_e32 v99, v98
	v_pk_add_f32 v[100:101], v[20:21], 1.0 op_sel_hi:[1,0]
	s_nop 1
	v_permlane32_swap_b32_e32 v99, v98
	s_nop 1
	v_add_f32_e32 v98, v98, v99
	v_mov_b32_e32 v99, v98
	s_nop 1
	v_permlane16_swap_b32_e32 v99, v98
	s_nop 1
	v_add_f32_e32 v98, v98, v99
	s_nop 1
	v_add_f32_dpp v98, v98, v98 row_ror:8 row_mask:0xf bank_mask:0xf
	s_nop 1
	v_add_f32_dpp v98, v98, v98 row_ror:4 row_mask:0xf bank_mask:0xf
	s_nop 1
	v_add_f32_dpp v98, v98, v98 quad_perm:[2,3,0,1] row_mask:0xf bank_mask:0xf
	s_nop 1
	v_add_f32_dpp v98, v98, v98 quad_perm:[1,0,3,2] row_mask:0xf bank_mask:0xf
	v_fmamk_f32 v98, v98, 0x3a800000, v234
	v_mul_f32_e32 v99, 0x4b800000, v98
	v_cmp_gt_f32_e32 vcc, s28, v98
	s_nop 1
	v_cndmask_b32_e32 v98, v98, v99, vcc
	v_rsq_f32_e32 v102, v98
	v_pk_add_f32 v[98:99], v[22:23], 1.0 op_sel_hi:[1,0]
	v_mul_f32_e32 v103, 0x45800000, v102
	v_cndmask_b32_e32 v102, v102, v103, vcc
	v_pk_mul_f32 v[94:95], v[94:95], v[102:103] op_sel_hi:[1,0]
	v_pk_mul_f32 v[92:93], v[92:93], v[102:103] op_sel_hi:[1,0]
	v_pk_mul_f32 v[94:95], v[10:11], v[94:95]
	v_pk_mul_f32 v[92:93], v[8:9], v[92:93]
	v_pk_fma_f32 v[94:95], v[98:99], v[94:95], v[18:19]
	v_pk_fma_f32 v[92:93], v[100:101], v[92:93], v[16:17]
	v_pk_mul_f32 v[90:91], v[90:91], v[102:103] op_sel_hi:[1,0]
	v_cvt_pk_bf16_f32 v92, v92, v93
	v_cvt_pk_bf16_f32 v93, v94, v95
	v_pk_mul_f32 v[88:89], v[88:89], v[102:103] op_sel_hi:[1,0]
	global_store_dwordx2 v[96:97], v[92:93], off
	v_pk_mul_f32 v[88:89], v[0:1], v[88:89]
	v_pk_mul_f32 v[90:91], v[2:3], v[90:91]
	v_pk_add_f32 v[92:93], v[30:31], 1.0 op_sel_hi:[1,0]
	v_pk_add_f32 v[94:95], v[28:29], 1.0 op_sel_hi:[1,0]
	v_pk_fma_f32 v[90:91], v[92:93], v[90:91], v[26:27]
	v_pk_fma_f32 v[88:89], v[94:95], v[88:89], v[24:25]
	v_pk_mul_f32 v[86:87], v[86:87], v[102:103] op_sel_hi:[1,0]
	v_cvt_pk_bf16_f32 v88, v88, v89
	v_cvt_pk_bf16_f32 v89, v90, v91
	v_pk_mul_f32 v[84:85], v[84:85], v[102:103] op_sel_hi:[1,0]
	global_store_dwordx2 v[96:97], v[88:89], off offset:512
	v_pk_mul_f32 v[84:85], v[4:5], v[84:85]
	v_pk_mul_f32 v[86:87], v[6:7], v[86:87]
	v_pk_add_f32 v[88:89], v[54:55], 1.0 op_sel_hi:[1,0]
	v_pk_add_f32 v[90:91], v[52:53], 1.0 op_sel_hi:[1,0]
	v_pk_fma_f32 v[86:87], v[88:89], v[86:87], v[50:51]
	v_pk_fma_f32 v[84:85], v[90:91], v[84:85], v[48:49]
	v_pk_mul_f32 v[82:83], v[82:83], v[102:103] op_sel_hi:[1,0]
	v_cvt_pk_bf16_f32 v84, v84, v85
	v_cvt_pk_bf16_f32 v85, v86, v87
	v_pk_mul_f32 v[80:81], v[80:81], v[102:103] op_sel_hi:[1,0]
	global_store_dwordx2 v[96:97], v[84:85], off offset:1024
	v_pk_mul_f32 v[80:81], v[12:13], v[80:81]
	v_pk_mul_f32 v[82:83], v[14:15], v[82:83]
	v_pk_add_f32 v[84:85], v[78:79], 1.0 op_sel_hi:[1,0]
	v_pk_add_f32 v[86:87], v[76:77], 1.0 op_sel_hi:[1,0]
	v_pk_fma_f32 v[82:83], v[84:85], v[82:83], v[74:75]
	v_pk_fma_f32 v[80:81], v[86:87], v[80:81], v[72:73]
	s_nop 0
	v_cvt_pk_bf16_f32 v80, v80, v81
	v_cvt_pk_bf16_f32 v81, v82, v83
	global_store_dwordx2 v[96:97], v[80:81], off offset:1536
	s_or_b64 exec, exec, s[6:7]
	v_cmp_lt_i32_e32 vcc, v164, v226
	s_and_saveexec_b64 s[6:7], vcc
	s_cbranch_execnz .LBB0_1180

.LBB0_1178:
	s_or_b64 exec, exec, s[40:41]
	v_mov_b32_e32 v116, v109
	v_mov_b32_e32 v117, v105
	v_mov_b32_e32 v114, v108
	v_mov_b32_e32 v115, v104
	v_pk_mul_f32 v[116:117], v[116:117], v[116:117]
	v_mov_b32_e32 v118, v101
	v_pk_fma_f32 v[114:115], v[114:115], v[114:115], v[116:117]
	v_mov_b32_e32 v116, v110
	v_mov_b32_e32 v117, v106
	v_pk_fma_f32 v[114:115], v[116:117], v[116:117], v[114:115]
	v_mov_b32_e32 v116, v111
	v_mov_b32_e32 v117, v107
	v_mov_b32_e32 v119, v97
	v_pk_fma_f32 v[114:115], v[116:117], v[116:117], v[114:115]
	v_mov_b32_e32 v116, v100
	v_mov_b32_e32 v117, v96
	v_pk_mul_f32 v[118:119], v[118:119], v[118:119]
	v_add_f32_e32 v114, v114, v115
	v_pk_fma_f32 v[116:117], v[116:117], v[116:117], v[118:119]
	v_mov_b32_e32 v118, v102
	v_mov_b32_e32 v119, v98
	v_pk_fma_f32 v[116:117], v[118:119], v[118:119], v[116:117]
	v_mov_b32_e32 v118, v103
	v_mov_b32_e32 v119, v99
	v_pk_fma_f32 v[116:117], v[118:119], v[118:119], v[116:117]
	v_lshl_add_u64 v[112:113], v[132:133], 0, v[112:113]
	v_add_f32_e32 v114, v114, v116
	v_add_f32_e32 v114, v114, v117
	v_mov_b32_e32 v115, v114
	v_pk_add_f32 v[116:117], v[20:21], 1.0 op_sel_hi:[1,0]
	s_nop 1
	v_permlane32_swap_b32_e32 v115, v114
	s_nop 1
	v_add_f32_e32 v114, v114, v115
	v_mov_b32_e32 v115, v114
	s_nop 1
	v_permlane16_swap_b32_e32 v115, v114
	s_nop 1
	v_add_f32_e32 v114, v114, v115
	s_nop 1
	v_add_f32_dpp v114, v114, v114 row_ror:8 row_mask:0xf bank_mask:0xf
	s_nop 1
	v_add_f32_dpp v114, v114, v114 row_ror:4 row_mask:0xf bank_mask:0xf
	s_nop 1
	v_add_f32_dpp v114, v114, v114 quad_perm:[2,3,0,1] row_mask:0xf bank_mask:0xf
	s_nop 1
	v_add_f32_dpp v114, v114, v114 quad_perm:[1,0,3,2] row_mask:0xf bank_mask:0xf
	v_fmamk_f32 v114, v114, 0x3a800000, v234
	v_mul_f32_e32 v115, 0x4b800000, v114
	v_cmp_gt_f32_e32 vcc, s28, v114
	s_nop 1
	v_cndmask_b32_e32 v114, v114, v115, vcc
	v_rsq_f32_e32 v118, v114
	v_pk_add_f32 v[114:115], v[22:23], 1.0 op_sel_hi:[1,0]
	v_mul_f32_e32 v119, 0x45800000, v118
	v_cndmask_b32_e32 v118, v118, v119, vcc
	v_pk_mul_f32 v[110:111], v[110:111], v[118:119] op_sel_hi:[1,0]
	v_pk_mul_f32 v[108:109], v[108:109], v[118:119] op_sel_hi:[1,0]
	v_pk_mul_f32 v[110:111], v[10:11], v[110:111]
	v_pk_mul_f32 v[108:109], v[8:9], v[108:109]
	v_pk_fma_f32 v[110:111], v[114:115], v[110:111], v[18:19]
	v_pk_fma_f32 v[108:109], v[116:117], v[108:109], v[16:17]
	v_pk_mul_f32 v[106:107], v[106:107], v[118:119] op_sel_hi:[1,0]
	v_cvt_pk_bf16_f32 v108, v108, v109
	v_cvt_pk_bf16_f32 v109, v110, v111
	v_pk_mul_f32 v[104:105], v[104:105], v[118:119] op_sel_hi:[1,0]
	global_store_dwordx2 v[112:113], v[108:109], off
	v_pk_mul_f32 v[104:105], v[0:1], v[104:105]
	v_pk_mul_f32 v[106:107], v[2:3], v[106:107]
	v_pk_add_f32 v[108:109], v[30:31], 1.0 op_sel_hi:[1,0]
	v_pk_add_f32 v[110:111], v[28:29], 1.0 op_sel_hi:[1,0]
	v_pk_fma_f32 v[106:107], v[108:109], v[106:107], v[26:27]
	v_pk_fma_f32 v[104:105], v[110:111], v[104:105], v[24:25]
	v_pk_mul_f32 v[102:103], v[102:103], v[118:119] op_sel_hi:[1,0]
	v_cvt_pk_bf16_f32 v104, v104, v105
	v_cvt_pk_bf16_f32 v105, v106, v107
	v_pk_mul_f32 v[100:101], v[100:101], v[118:119] op_sel_hi:[1,0]
	global_store_dwordx2 v[112:113], v[104:105], off offset:512
	v_pk_mul_f32 v[100:101], v[4:5], v[100:101]
	v_pk_mul_f32 v[102:103], v[6:7], v[102:103]
	v_pk_add_f32 v[104:105], v[54:55], 1.0 op_sel_hi:[1,0]
	v_pk_add_f32 v[106:107], v[52:53], 1.0 op_sel_hi:[1,0]
	v_pk_fma_f32 v[102:103], v[104:105], v[102:103], v[50:51]
	v_pk_fma_f32 v[100:101], v[106:107], v[100:101], v[48:49]
	v_pk_mul_f32 v[98:99], v[98:99], v[118:119] op_sel_hi:[1,0]
	v_cvt_pk_bf16_f32 v100, v100, v101
	v_cvt_pk_bf16_f32 v101, v102, v103
	v_pk_mul_f32 v[96:97], v[96:97], v[118:119] op_sel_hi:[1,0]
	global_store_dwordx2 v[112:113], v[100:101], off offset:1024
	v_pk_mul_f32 v[96:97], v[12:13], v[96:97]
	v_pk_mul_f32 v[98:99], v[14:15], v[98:99]
	v_pk_add_f32 v[100:101], v[78:79], 1.0 op_sel_hi:[1,0]
	v_pk_add_f32 v[102:103], v[76:77], 1.0 op_sel_hi:[1,0]
	v_pk_fma_f32 v[98:99], v[100:101], v[98:99], v[74:75]
	v_pk_fma_f32 v[96:97], v[102:103], v[96:97], v[72:73]
	s_nop 0
	v_cvt_pk_bf16_f32 v96, v96, v97
	v_cvt_pk_bf16_f32 v97, v98, v99
	global_store_dwordx2 v[112:113], v[96:97], off offset:1536
	s_or_b64 exec, exec, s[6:7]
	v_cmp_lt_i32_e32 vcc, v174, v226
	s_and_saveexec_b64 s[6:7], vcc
	s_cbranch_execnz .LBB0_1155

.LBB0_1190:
	s_or_b64 exec, exec, s[40:41]
	v_mov_b32_e32 v84, v69
	v_mov_b32_e32 v85, v65
	v_mov_b32_e32 v82, v68
	v_mov_b32_e32 v83, v64
	v_pk_mul_f32 v[84:85], v[84:85], v[84:85]
	v_mov_b32_e32 v86, v61
	v_pk_fma_f32 v[82:83], v[82:83], v[82:83], v[84:85]
	v_mov_b32_e32 v84, v70
	v_mov_b32_e32 v85, v66
	v_pk_fma_f32 v[82:83], v[84:85], v[84:85], v[82:83]
	v_mov_b32_e32 v84, v71
	v_mov_b32_e32 v85, v67
	v_mov_b32_e32 v87, v57
	v_pk_fma_f32 v[82:83], v[84:85], v[84:85], v[82:83]
	v_mov_b32_e32 v84, v60
	v_mov_b32_e32 v85, v56
	v_pk_mul_f32 v[86:87], v[86:87], v[86:87]
	v_add_f32_e32 v82, v82, v83
	v_pk_fma_f32 v[84:85], v[84:85], v[84:85], v[86:87]
	v_mov_b32_e32 v86, v62
	v_mov_b32_e32 v87, v58
	v_pk_fma_f32 v[84:85], v[86:87], v[86:87], v[84:85]
	v_mov_b32_e32 v86, v63
	v_mov_b32_e32 v87, v59
	v_pk_fma_f32 v[84:85], v[86:87], v[86:87], v[84:85]
	v_lshl_add_u64 v[80:81], v[132:133], 0, v[80:81]
	v_add_f32_e32 v82, v82, v84
	v_add_f32_e32 v82, v82, v85
	v_mov_b32_e32 v83, v82
	v_pk_add_f32 v[84:85], v[20:21], 1.0 op_sel_hi:[1,0]
	s_nop 1
	v_permlane32_swap_b32_e32 v83, v82
	s_nop 1
	v_add_f32_e32 v82, v82, v83
	v_mov_b32_e32 v83, v82
	s_nop 1
	v_permlane16_swap_b32_e32 v83, v82
	s_nop 1
	v_add_f32_e32 v82, v82, v83
	s_nop 1
	v_add_f32_dpp v82, v82, v82 row_ror:8 row_mask:0xf bank_mask:0xf
	s_nop 1
	v_add_f32_dpp v82, v82, v82 row_ror:4 row_mask:0xf bank_mask:0xf
	s_nop 1
	v_add_f32_dpp v82, v82, v82 quad_perm:[2,3,0,1] row_mask:0xf bank_mask:0xf
	s_nop 1
	v_add_f32_dpp v82, v82, v82 quad_perm:[1,0,3,2] row_mask:0xf bank_mask:0xf
	v_fmamk_f32 v82, v82, 0x3a800000, v234
	v_mul_f32_e32 v83, 0x4b800000, v82
	v_cmp_gt_f32_e32 vcc, s28, v82
	s_nop 1
	v_cndmask_b32_e32 v82, v82, v83, vcc
	v_rsq_f32_e32 v86, v82
	v_pk_add_f32 v[82:83], v[22:23], 1.0 op_sel_hi:[1,0]
	v_mul_f32_e32 v87, 0x45800000, v86
	v_cndmask_b32_e32 v86, v86, v87, vcc
	v_pk_mul_f32 v[70:71], v[70:71], v[86:87] op_sel_hi:[1,0]
	v_pk_mul_f32 v[68:69], v[68:69], v[86:87] op_sel_hi:[1,0]
	v_pk_mul_f32 v[70:71], v[10:11], v[70:71]
	v_pk_mul_f32 v[68:69], v[8:9], v[68:69]
	v_pk_fma_f32 v[70:71], v[82:83], v[70:71], v[18:19]
	v_pk_fma_f32 v[68:69], v[84:85], v[68:69], v[16:17]
	v_pk_mul_f32 v[66:67], v[66:67], v[86:87] op_sel_hi:[1,0]
	v_cvt_pk_bf16_f32 v68, v68, v69
	v_cvt_pk_bf16_f32 v69, v70, v71
	v_pk_mul_f32 v[64:65], v[64:65], v[86:87] op_sel_hi:[1,0]
	global_store_dwordx2 v[80:81], v[68:69], off
	v_pk_mul_f32 v[64:65], v[0:1], v[64:65]
	v_pk_mul_f32 v[66:67], v[2:3], v[66:67]
	v_pk_add_f32 v[68:69], v[30:31], 1.0 op_sel_hi:[1,0]
	v_pk_add_f32 v[70:71], v[28:29], 1.0 op_sel_hi:[1,0]
	v_pk_fma_f32 v[66:67], v[68:69], v[66:67], v[26:27]
	v_pk_fma_f32 v[64:65], v[70:71], v[64:65], v[24:25]
	v_pk_mul_f32 v[62:63], v[62:63], v[86:87] op_sel_hi:[1,0]
	v_cvt_pk_bf16_f32 v64, v64, v65
	v_cvt_pk_bf16_f32 v65, v66, v67
	v_pk_mul_f32 v[60:61], v[60:61], v[86:87] op_sel_hi:[1,0]
	global_store_dwordx2 v[80:81], v[64:65], off offset:512
	v_pk_mul_f32 v[60:61], v[4:5], v[60:61]
	v_pk_mul_f32 v[62:63], v[6:7], v[62:63]
	v_pk_add_f32 v[64:65], v[54:55], 1.0 op_sel_hi:[1,0]
	v_pk_add_f32 v[66:67], v[52:53], 1.0 op_sel_hi:[1,0]
	v_pk_fma_f32 v[62:63], v[64:65], v[62:63], v[50:51]
	v_pk_fma_f32 v[60:61], v[66:67], v[60:61], v[48:49]
	v_pk_mul_f32 v[58:59], v[58:59], v[86:87] op_sel_hi:[1,0]
	v_cvt_pk_bf16_f32 v60, v60, v61
	v_cvt_pk_bf16_f32 v61, v62, v63
	v_pk_mul_f32 v[56:57], v[56:57], v[86:87] op_sel_hi:[1,0]
	global_store_dwordx2 v[80:81], v[60:61], off offset:1024
	v_pk_mul_f32 v[56:57], v[12:13], v[56:57]
	v_pk_mul_f32 v[58:59], v[14:15], v[58:59]
	v_pk_add_f32 v[60:61], v[78:79], 1.0 op_sel_hi:[1,0]
	v_pk_add_f32 v[62:63], v[76:77], 1.0 op_sel_hi:[1,0]
	v_pk_fma_f32 v[58:59], v[60:61], v[58:59], v[74:75]
	v_pk_fma_f32 v[56:57], v[62:63], v[56:57], v[72:73]
	s_nop 0
	v_cvt_pk_bf16_f32 v56, v56, v57
	v_cvt_pk_bf16_f32 v57, v58, v59
	global_store_dwordx2 v[80:81], v[56:57], off offset:1536
	s_or_b64 exec, exec, s[6:7]
	v_cmp_lt_i32_e32 vcc, v154, v226
	s_and_saveexec_b64 s[6:7], vcc
	s_cbranch_execz .LBB0_1131

.LBB0_1429:
	v_ashrrev_i32_e32 v17, 31, v16
	v_lshlrev_b64 v[18:19], 13, v[16:17]
	v_lshl_add_u64 v[18:19], s[60:61], 0, v[18:19]
	v_lshl_add_u64 v[18:19], v[18:19], 0, v[148:149]
	v_lshlrev_b64 v[168:169], 11, v[16:17]
	v_lshl_add_u64 v[20:21], v[18:19], 0, s[6:7]
	v_lshl_add_u64 v[22:23], v[152:153], 0, v[168:169]
	s_waitcnt vmcnt(3)
	v_lshl_add_u64 v[24:25], v[154:155], 0, v[168:169]
	v_add_co_u32_e32 v18, vcc, s19, v18
	global_load_dwordx4 v[180:183], v[22:23], off offset:16
	global_load_dwordx4 v[140:143], v[24:25], off
	v_addc_co_u32_e32 v19, vcc, 0, v19, vcc
	global_load_dwordx4 v[184:187], v[24:25], off offset:16
	global_load_dwordx4 v[136:139], v[18:19], off offset:2048
	global_load_dwordx4 v[144:147], v[22:23], off
	global_load_dwordx4 v[188:191], v[20:21], off offset:16
	v_add_u32_e32 v166, s33, v16
	v_min_i32_e32 v18, 0x2fff, v166
	v_ashrrev_i32_e32 v19, 31, v18
	v_lshlrev_b64 v[20:21], 13, v[18:19]
	v_lshl_add_u64 v[20:21], s[60:61], 0, v[20:21]
	v_lshl_add_u64 v[20:21], v[20:21], 0, v[148:149]
	v_lshlrev_b64 v[18:19], 11, v[18:19]
	v_lshl_add_u64 v[22:23], v[20:21], 0, s[6:7]
	v_lshl_add_u64 v[24:25], v[152:153], 0, v[18:19]
	v_lshl_add_u64 v[18:19], v[154:155], 0, v[18:19]
	v_add_co_u32_e32 v20, vcc, s19, v20
	v_add_u32_e32 v164, s16, v16
	global_load_dwordx4 v[124:127], v[24:25], off offset:16
	global_load_dwordx4 v[116:119], v[18:19], off
	v_addc_co_u32_e32 v21, vcc, 0, v21, vcc
	global_load_dwordx4 v[128:131], v[18:19], off offset:16
	global_load_dwordx4 v[112:115], v[20:21], off offset:2048
	global_load_dwordx4 v[120:123], v[24:25], off
	global_load_dwordx4 v[132:135], v[22:23], off offset:16
	v_min_i32_e32 v18, 0x2fff, v164
	v_ashrrev_i32_e32 v19, 31, v18
	v_lshlrev_b64 v[20:21], 13, v[18:19]
	v_lshl_add_u64 v[20:21], s[60:61], 0, v[20:21]
	v_lshl_add_u64 v[20:21], v[20:21], 0, v[148:149]
	v_lshlrev_b64 v[18:19], 11, v[18:19]
	v_lshl_add_u64 v[22:23], v[20:21], 0, s[6:7]
	v_lshl_add_u64 v[24:25], v[152:153], 0, v[18:19]
	v_lshl_add_u64 v[18:19], v[154:155], 0, v[18:19]
	v_add_co_u32_e32 v20, vcc, s19, v20
	v_add_u32_e32 v162, s71, v16
	global_load_dwordx4 v[100:103], v[24:25], off offset:16
	global_load_dwordx4 v[92:95], v[18:19], off
	v_addc_co_u32_e32 v21, vcc, 0, v21, vcc
	global_load_dwordx4 v[104:107], v[18:19], off offset:16
	global_load_dwordx4 v[88:91], v[20:21], off offset:2048
	global_load_dwordx4 v[96:99], v[24:25], off
	global_load_dwordx4 v[108:111], v[22:23], off offset:16
	v_min_i32_e32 v18, 0x2fff, v162
	v_ashrrev_i32_e32 v19, 31, v18
	v_lshlrev_b64 v[20:21], 13, v[18:19]
	v_lshl_add_u64 v[20:21], s[60:61], 0, v[20:21]
	v_lshl_add_u64 v[20:21], v[20:21], 0, v[148:149]
	v_lshlrev_b64 v[18:19], 11, v[18:19]
	v_lshl_add_u64 v[22:23], v[20:21], 0, s[6:7]
	v_lshl_add_u64 v[24:25], v[152:153], 0, v[18:19]
	v_lshl_add_u64 v[18:19], v[154:155], 0, v[18:19]
	v_add_co_u32_e32 v20, vcc, s19, v20
	v_add_u32_e32 v160, s17, v16
	global_load_dwordx4 v[76:79], v[24:25], off offset:16
	global_load_dwordx4 v[68:71], v[18:19], off
	v_addc_co_u32_e32 v21, vcc, 0, v21, vcc
	global_load_dwordx4 v[80:83], v[18:19], off offset:16
	global_load_dwordx4 v[64:67], v[20:21], off offset:2048
	global_load_dwordx4 v[72:75], v[24:25], off
	global_load_dwordx4 v[84:87], v[22:23], off offset:16
	v_min_i32_e32 v18, 0x2fff, v160
	v_ashrrev_i32_e32 v19, 31, v18
	v_lshlrev_b64 v[20:21], 13, v[18:19]
	v_lshl_add_u64 v[20:21], s[60:61], 0, v[20:21]
	v_add_u32_e32 v158, s72, v16
	v_lshl_add_u64 v[20:21], v[20:21], 0, v[148:149]
	v_lshlrev_b64 v[18:19], 11, v[18:19]
	v_min_i32_e32 v16, 0x2fff, v158
	v_lshl_add_u64 v[22:23], v[20:21], 0, s[6:7]
	v_lshl_add_u64 v[24:25], v[152:153], 0, v[18:19]
	v_lshl_add_u64 v[18:19], v[154:155], 0, v[18:19]
	v_add_co_u32_e32 v20, vcc, s19, v20
	v_ashrrev_i32_e32 v17, 31, v16
	global_load_dwordx4 v[56:59], v[24:25], off offset:16
	global_load_dwordx4 v[44:47], v[18:19], off
	v_addc_co_u32_e32 v21, vcc, 0, v21, vcc
	global_load_dwordx4 v[52:55], v[18:19], off offset:16
	global_load_dwordx4 v[40:43], v[20:21], off offset:2048
	global_load_dwordx4 v[48:51], v[24:25], off
	global_load_dwordx4 v[60:63], v[22:23], off offset:16
	v_lshlrev_b64 v[18:19], 13, v[16:17]
	v_lshl_add_u64 v[18:19], s[60:61], 0, v[18:19]
	v_lshl_add_u64 v[18:19], v[18:19], 0, v[148:149]
	s_waitcnt vmcnt(32)
	v_lshl_add_u64 v[36:37], v[18:19], 0, s[6:7]
	v_lshlrev_b64 v[16:17], 11, v[16:17]
	v_add_co_u32_e32 v18, vcc, s19, v18
	v_lshl_add_u64 v[24:25], v[152:153], 0, v[16:17]
	s_waitcnt vmcnt(29)
	v_lshlrev_b32_e32 v175, 16, v183
	s_waitcnt vmcnt(27)
	v_lshlrev_b32_e32 v173, 16, v187
	v_and_b32_e32 v172, 0xffff0000, v187
	v_and_b32_e32 v174, 0xffff0000, v183
	s_waitcnt vmcnt(24)
	v_and_b32_e32 v170, 0xffff0000, v191
	v_lshlrev_b32_e32 v3, 16, v191
	v_pk_add_f32 v[172:173], v[172:173], v[174:175]
	v_lshlrev_b32_e32 v174, 16, v190
	v_and_b32_e32 v175, 0xffff0000, v190
	v_lshlrev_b32_e32 v190, 16, v186
	v_and_b32_e32 v191, 0xffff0000, v186
	v_lshlrev_b32_e32 v186, 16, v182
	v_and_b32_e32 v187, 0xffff0000, v182
	v_pk_add_f32 v[182:183], v[186:187], v[190:191]
	v_lshlrev_b32_e32 v190, 16, v189
	v_and_b32_e32 v191, 0xffff0000, v189
	v_mul_f32_e32 v156, 0xbfb8aa3b, v190
	v_exp_f32_e32 v156, v156
	v_mul_f32_e32 v159, 0xbfb8aa3b, v191
	v_exp_f32_e32 v159, v159
	v_lshl_add_u64 v[16:17], v[154:155], 0, v[16:17]
	v_add_f32_e32 v156, 1.0, v156
	v_rcp_f32_e32 v198, v156
	v_add_f32_e32 v156, 1.0, v159
	v_rcp_f32_e32 v199, v156
	v_addc_co_u32_e32 v19, vcc, 0, v19, vcc
	global_load_dwordx4 v[32:35], v[24:25], off offset:16
	global_load_dwordx4 v[20:23], v[16:17], off
	v_pk_mul_f32 v[190:191], v[198:199], v[190:191]
	v_lshlrev_b32_e32 v198, 16, v188
	v_and_b32_e32 v199, 0xffff0000, v188
	v_mul_f32_e32 v156, 0xbfb8aa3b, v198
	v_exp_f32_e32 v156, v156
	v_mul_f32_e32 v159, 0xbfb8aa3b, v199
	v_exp_f32_e32 v159, v159
	global_load_dwordx4 v[28:31], v[16:17], off offset:16
	s_nop 0
	global_load_dwordx4 v[16:19], v[18:19], off offset:2048
	s_nop 0
	global_load_dwordx4 v[24:27], v[24:25], off
	s_nop 0
	global_load_dwordx4 v[36:39], v[36:37], off offset:16
	v_add_f32_e32 v156, 1.0, v156
	v_rcp_f32_e32 v200, v156
	v_add_f32_e32 v156, 1.0, v159
	v_rcp_f32_e32 v201, v156
	v_lshlrev_b32_e32 v194, 16, v185
	v_and_b32_e32 v195, 0xffff0000, v185
	v_lshlrev_b32_e32 v188, 16, v184
	v_and_b32_e32 v189, 0xffff0000, v184
	v_lshlrev_b32_e32 v184, 16, v180
	v_and_b32_e32 v185, 0xffff0000, v180
	v_lshlrev_b32_e32 v196, 16, v181
	v_and_b32_e32 v197, 0xffff0000, v181
	v_pk_add_f32 v[180:181], v[184:185], v[188:189]
	v_pk_mul_f32 v[188:189], v[200:201], v[198:199]
	v_lshlrev_b32_e32 v198, 16, v139
	v_and_b32_e32 v199, 0xffff0000, v139
	v_mul_f32_e32 v139, 0xbfb8aa3b, v198
	v_lshlrev_b32_e32 v200, 16, v143
	v_and_b32_e32 v201, 0xffff0000, v143
	v_exp_f32_e32 v139, v139
	v_mul_f32_e32 v143, 0xbfb8aa3b, v199
	v_exp_f32_e32 v143, v143
	v_lshlrev_b32_e32 v208, 16, v141
	v_add_f32_e32 v139, 1.0, v139
	v_rcp_f32_e32 v204, v139
	v_add_f32_e32 v139, 1.0, v143
	v_rcp_f32_e32 v205, v139
	v_and_b32_e32 v209, 0xffff0000, v141
	v_lshlrev_b32_e32 v214, 16, v140
	v_and_b32_e32 v215, 0xffff0000, v140
	v_lshlrev_b32_e32 v140, 16, v144
	v_and_b32_e32 v141, 0xffff0000, v144
	v_lshlrev_b32_e32 v210, 16, v145
	v_and_b32_e32 v211, 0xffff0000, v145
	v_pk_add_f32 v[140:141], v[140:141], v[214:215]
	v_pk_mul_f32 v[198:199], v[204:205], v[198:199]
	v_lshlrev_b32_e32 v204, 16, v138
	v_and_b32_e32 v205, 0xffff0000, v138
	v_lshlrev_b32_e32 v138, 16, v142
	v_and_b32_e32 v139, 0xffff0000, v142
	v_lshlrev_b32_e32 v142, 16, v146
	v_and_b32_e32 v143, 0xffff0000, v146
	v_pk_add_f32 v[208:209], v[210:211], v[208:209]
	v_pk_mul_f32 v[144:145], v[140:141], v[140:141]
	v_pk_add_f32 v[138:139], v[142:143], v[138:139]
	v_mul_f32_e32 v142, 0xbfb8aa3b, v204
	v_pk_mul_f32 v[210:211], v[208:209], v[208:209]
	v_add_f32_e32 v144, v144, v145
	v_exp_f32_e32 v146, v142
	v_mul_f32_e32 v142, 0xbfb8aa3b, v205
	v_add_f32_e32 v144, v210, v144
	v_lshlrev_b32_e32 v202, 16, v147
	v_and_b32_e32 v203, 0xffff0000, v147
	v_exp_f32_e32 v147, v142
	v_pk_mul_f32 v[142:143], v[138:139], v[138:139]
	v_add_f32_e32 v144, v211, v144
	v_pk_add_f32 v[200:201], v[202:203], v[200:201]
	v_add_f32_e32 v142, v142, v144
	v_pk_mul_f32 v[202:203], v[200:201], v[200:201]
	v_add_f32_e32 v142, v143, v142
	v_add_f32_e32 v142, v202, v142
	v_pk_mul_f32 v[184:185], v[180:181], v[180:181]
	v_add_f32_e32 v142, v203, v142
	v_pk_add_f32 v[194:195], v[196:197], v[194:195]
	v_add_f32_e32 v142, v184, v142
	v_pk_mul_f32 v[196:197], v[194:195], v[194:195]
	v_lshlrev_b32_e32 v206, 16, v137
	v_add_f32_e32 v142, v185, v142
	v_and_b32_e32 v207, 0xffff0000, v137
	v_mul_f32_e32 v137, 0xbfb8aa3b, v206
	v_add_f32_e32 v142, v196, v142
	v_pk_mul_f32 v[186:187], v[182:183], v[182:183]
	v_exp_f32_e32 v137, v137
	v_add_f32_e32 v142, v197, v142
	v_add_f32_e32 v142, v186, v142
	v_pk_mul_f32 v[192:193], v[172:173], v[172:173]
	v_add_f32_e32 v142, v187, v142
	v_add_f32_e32 v142, v193, v142
	v_add_f32_e32 v137, 1.0, v137
	v_add_f32_e32 v144, v192, v142
	v_rcp_f32_e32 v212, v137
	v_mul_f32_e32 v137, 0xbfb8aa3b, v207
	v_exp_f32_e32 v137, v137
	v_lshlrev_b32_e32 v142, 16, v136
	v_and_b32_e32 v143, 0xffff0000, v136
	v_add_f32_e32 v146, 1.0, v146
	v_add_f32_e32 v137, 1.0, v137
	s_nop 1
	v_add_f32_dpp v136, v144, v144 quad_perm:[1,0,3,2] row_mask:0xf bank_mask:0xf
	v_rcp_f32_e32 v213, v137
	v_mul_f32_e32 v144, 0xbfb8aa3b, v142
	v_exp_f32_e32 v144, v144
	v_mul_f32_e32 v145, 0xbfb8aa3b, v143
	v_exp_f32_e32 v145, v145
	s_nop 1
	v_add_f32_dpp v156, v136, v136 quad_perm:[2,3,0,1] row_mask:0xf bank_mask:0xf
	v_add_f32_e32 v136, 1.0, v144
	v_add_f32_e32 v137, 1.0, v145
	v_rcp_f32_e32 v136, v136
	v_rcp_f32_e32 v137, v137
	s_nop 1
	v_add_f32_dpp v144, v156, v156 row_half_mirror row_mask:0xf bank_mask:0xf
	v_fmamk_f32 v144, v144, 0x3c000000, v176
	v_mul_f32_e32 v145, 0x4b800000, v144
	v_cmp_gt_f32_e32 vcc, s29, v144
	v_add_f32_e32 v147, 1.0, v147
	v_pk_mul_f32 v[136:137], v[136:137], v[142:143]
	v_cndmask_b32_e32 v144, v144, v145, vcc
	v_rsq_f32_e32 v156, v144
	v_rcp_f32_e32 v146, v146
	v_rcp_f32_e32 v147, v147
	v_mul_f32_e32 v142, 0x45800000, v156
	v_cndmask_b32_e32 v142, v156, v142, vcc
	v_pk_mul_f32 v[140:141], v[140:141], v[142:143] op_sel_hi:[1,0]
	v_pk_mul_f32 v[138:139], v[138:139], v[142:143] op_sel_hi:[1,0]
	v_pk_mul_f32 v[140:141], v[12:13], v[140:141]
	v_pk_mul_f32 v[144:145], v[146:147], v[204:205]
	v_pk_mul_f32 v[136:137], v[136:137], v[140:141]
	v_pk_mul_f32 v[140:141], v[208:209], v[142:143] op_sel_hi:[1,0]
	v_pk_mul_f32 v[146:147], v[212:213], v[206:207]
	v_pk_mul_f32 v[140:141], v[14:15], v[140:141]
	v_pk_mul_f32 v[138:139], v[8:9], v[138:139]
	v_pk_mul_f32 v[140:141], v[146:147], v[140:141]
	v_pk_mul_f32 v[138:139], v[144:145], v[138:139]
	v_pk_mul_f32 v[144:145], v[200:201], v[142:143] op_sel_hi:[1,0]
	v_pk_mul_f32 v[146:147], v[180:181], v[142:143] op_sel_hi:[1,0]
	v_pk_mul_f32 v[180:181], v[194:195], v[142:143] op_sel_hi:[1,0]
	v_mul_f32_e32 v143, 0xbfb8aa3b, v174
	v_exp_f32_e32 v143, v143
	v_mul_f32_e32 v156, 0xbfb8aa3b, v175
	v_exp_f32_e32 v156, v156
	v_mul_f32_e32 v171, v172, v142
	v_add_f32_e32 v143, 1.0, v143
	v_rcp_f32_e32 v184, v143
	v_add_f32_e32 v143, 1.0, v156
	v_rcp_f32_e32 v185, v143
	v_pk_mul_f32 v[182:183], v[182:183], v[142:143] op_sel_hi:[1,0]
	v_mul_f32_e32 v143, 0xbfb8aa3b, v3
	v_mul_f32_e32 v156, 0xbfb8aa3b, v170
	v_exp_f32_e32 v143, v143
	v_exp_f32_e32 v156, v156
	v_pk_mul_f32 v[144:145], v[10:11], v[144:145]
	v_pk_mul_f32 v[182:183], v[0:1], v[182:183]
	v_add_f32_e32 v143, 1.0, v143
	v_add_f32_e32 v156, 1.0, v156
	v_rcp_f32_e32 v143, v143
	v_rcp_f32_e32 v156, v156
	v_pk_mul_f32 v[174:175], v[184:185], v[174:175]
	v_mul_f32_e32 v159, v173, v142
	v_mul_f32_e32 v184, v143, v3
	v_pk_mul_f32 v[142:143], v[156:157], v[170:171]
	v_pk_mul_f32 v[144:145], v[198:199], v[144:145]
	v_pk_mul_f32 v[146:147], v[4:5], v[146:147]
	v_pk_mul_f32 v[180:181], v[6:7], v[180:181]
	v_pk_mul_f32 v[174:175], v[174:175], v[182:183]
	v_mul_f32_e32 v182, v2, v159
	v_mov_b32_e32 v185, v142
	v_mov_b32_e32 v183, v143
	v_pk_mul_f32 v[146:147], v[188:189], v[146:147]
	v_pk_mul_f32 v[180:181], v[190:191], v[180:181]
	v_cvt_pk_bf16_f32 v136, v136, v137
	v_cvt_pk_bf16_f32 v137, v140, v141
	v_cvt_pk_bf16_f32 v138, v138, v139
	v_cvt_pk_bf16_f32 v139, v144, v145
	v_lshl_add_u64 v[140:141], v[150:151], 0, v[168:169]
	v_pk_mul_f32 v[142:143], v[184:185], v[182:183]
	global_store_dwordx4 v[140:141], v[136:139], off
	v_cmp_gt_i32_e32 vcc, s3, v166
	s_nop 0
	v_cvt_pk_bf16_f32 v136, v146, v147
	v_cvt_pk_bf16_f32 v137, v180, v181
	v_cvt_pk_bf16_f32 v138, v174, v175
	v_cvt_pk_bf16_f32 v139, v142, v143
	global_store_dwordx4 v[140:141], v[136:139], off offset:16
	s_and_saveexec_b64 s[14:15], vcc
	s_cbranch_execz .LBB0_1431
	s_waitcnt vmcnt(29)
	v_lshlrev_b32_e32 v139, 16, v131
	v_lshlrev_b32_e32 v141, 16, v127
	v_and_b32_e32 v138, 0xffff0000, v131
	v_and_b32_e32 v140, 0xffff0000, v127
	s_waitcnt vmcnt(26)
	v_and_b32_e32 v136, 0xffff0000, v135
	v_lshlrev_b32_e32 v3, 16, v135
	v_pk_add_f32 v[138:139], v[138:139], v[140:141]
	v_lshlrev_b32_e32 v140, 16, v134
	v_and_b32_e32 v141, 0xffff0000, v134
	v_lshlrev_b32_e32 v134, 16, v130
	v_and_b32_e32 v135, 0xffff0000, v130
	v_lshlrev_b32_e32 v130, 16, v126
	v_and_b32_e32 v131, 0xffff0000, v126
	v_pk_add_f32 v[126:127], v[130:131], v[134:135]
	v_lshlrev_b32_e32 v134, 16, v133
	v_and_b32_e32 v135, 0xffff0000, v133
	v_lshlrev_b32_e32 v144, 16, v129
	v_and_b32_e32 v145, 0xffff0000, v129
	v_mul_f32_e32 v129, 0xbfb8aa3b, v134
	v_exp_f32_e32 v129, v129
	v_mul_f32_e32 v133, 0xbfb8aa3b, v135
	v_exp_f32_e32 v133, v133
	v_lshlrev_b32_e32 v146, 16, v125
	v_add_f32_e32 v129, 1.0, v129
	v_rcp_f32_e32 v168, v129
	v_add_f32_e32 v129, 1.0, v133
	v_rcp_f32_e32 v169, v129
	v_and_b32_e32 v147, 0xffff0000, v125
	v_and_b32_e32 v133, 0xffff0000, v128
	v_lshlrev_b32_e32 v182, 16, v117
	v_pk_mul_f32 v[134:135], v[168:169], v[134:135]
	v_lshlrev_b32_e32 v168, 16, v132
	v_and_b32_e32 v169, 0xffff0000, v132
	v_mul_f32_e32 v125, 0xbfb8aa3b, v168
	v_lshlrev_b32_e32 v132, 16, v128
	v_exp_f32_e32 v125, v125
	v_mul_f32_e32 v128, 0xbfb8aa3b, v169
	v_exp_f32_e32 v129, v128
	v_lshlrev_b32_e32 v128, 16, v124
	v_add_f32_e32 v125, 1.0, v125
	v_rcp_f32_e32 v170, v125
	v_add_f32_e32 v125, 1.0, v129
	v_rcp_f32_e32 v171, v125
	v_and_b32_e32 v129, 0xffff0000, v124
	v_pk_add_f32 v[124:125], v[128:129], v[132:133]
	v_and_b32_e32 v183, 0xffff0000, v117
	v_pk_mul_f32 v[132:133], v[170:171], v[168:169]
	v_lshlrev_b32_e32 v168, 16, v115
	v_and_b32_e32 v169, 0xffff0000, v115
	v_mul_f32_e32 v115, 0xbfb8aa3b, v168
	v_lshlrev_b32_e32 v170, 16, v119
	v_and_b32_e32 v171, 0xffff0000, v119
	v_exp_f32_e32 v115, v115
	v_mul_f32_e32 v119, 0xbfb8aa3b, v169
	v_exp_f32_e32 v119, v119
	v_lshlrev_b32_e32 v188, 16, v116
	v_add_f32_e32 v115, 1.0, v115
	v_rcp_f32_e32 v174, v115
	v_add_f32_e32 v115, 1.0, v119
	v_rcp_f32_e32 v175, v115
	v_and_b32_e32 v189, 0xffff0000, v116
	v_lshlrev_b32_e32 v116, 16, v120
	v_and_b32_e32 v117, 0xffff0000, v120
	v_lshlrev_b32_e32 v184, 16, v121
	v_and_b32_e32 v185, 0xffff0000, v121
	v_pk_add_f32 v[116:117], v[116:117], v[188:189]
	v_pk_mul_f32 v[168:169], v[174:175], v[168:169]
	v_lshlrev_b32_e32 v174, 16, v114
	v_and_b32_e32 v175, 0xffff0000, v114
	v_lshlrev_b32_e32 v114, 16, v118
	v_and_b32_e32 v115, 0xffff0000, v118
	v_lshlrev_b32_e32 v118, 16, v122
	v_and_b32_e32 v119, 0xffff0000, v122
	v_pk_add_f32 v[182:183], v[184:185], v[182:183]
	v_pk_mul_f32 v[120:121], v[116:117], v[116:117]
	v_pk_add_f32 v[114:115], v[118:119], v[114:115]
	v_mul_f32_e32 v118, 0xbfb8aa3b, v174
	v_pk_mul_f32 v[184:185], v[182:183], v[182:183]
	v_add_f32_e32 v120, v120, v121
	v_exp_f32_e32 v122, v118
	v_mul_f32_e32 v118, 0xbfb8aa3b, v175
	v_add_f32_e32 v120, v184, v120
	v_lshlrev_b32_e32 v172, 16, v123
	v_and_b32_e32 v173, 0xffff0000, v123
	v_exp_f32_e32 v123, v118
	v_pk_mul_f32 v[118:119], v[114:115], v[114:115]
	v_add_f32_e32 v120, v185, v120
	v_pk_add_f32 v[170:171], v[172:173], v[170:171]
	v_add_f32_e32 v118, v118, v120
	v_pk_mul_f32 v[172:173], v[170:171], v[170:171]
	v_add_f32_e32 v118, v119, v118
	v_add_f32_e32 v118, v172, v118
	v_pk_mul_f32 v[128:129], v[124:125], v[124:125]
	v_add_f32_e32 v118, v173, v118
	v_pk_add_f32 v[144:145], v[146:147], v[144:145]
	v_add_f32_e32 v118, v128, v118
	v_pk_mul_f32 v[146:147], v[144:145], v[144:145]
	v_lshlrev_b32_e32 v180, 16, v113
	v_add_f32_e32 v118, v129, v118
	v_and_b32_e32 v181, 0xffff0000, v113
	v_mul_f32_e32 v113, 0xbfb8aa3b, v180
	v_add_f32_e32 v118, v146, v118
	v_pk_mul_f32 v[130:131], v[126:127], v[126:127]
	v_exp_f32_e32 v113, v113
	v_add_f32_e32 v118, v147, v118
	v_add_f32_e32 v118, v130, v118
	v_pk_mul_f32 v[142:143], v[138:139], v[138:139]
	v_add_f32_e32 v118, v131, v118
	v_add_f32_e32 v118, v143, v118
	v_add_f32_e32 v113, 1.0, v113
	v_add_f32_e32 v120, v142, v118
	v_rcp_f32_e32 v186, v113
	v_mul_f32_e32 v113, 0xbfb8aa3b, v181
	v_exp_f32_e32 v113, v113
	v_lshlrev_b32_e32 v118, 16, v112
	v_and_b32_e32 v119, 0xffff0000, v112
	v_add_f32_e32 v122, 1.0, v122
	v_add_f32_e32 v113, 1.0, v113
	s_nop 1
	v_add_f32_dpp v112, v120, v120 quad_perm:[1,0,3,2] row_mask:0xf bank_mask:0xf
	v_rcp_f32_e32 v187, v113
	v_mul_f32_e32 v120, 0xbfb8aa3b, v118
	v_exp_f32_e32 v120, v120
	v_mul_f32_e32 v121, 0xbfb8aa3b, v119
	v_exp_f32_e32 v121, v121
	s_nop 1
	v_add_f32_dpp v128, v112, v112 quad_perm:[2,3,0,1] row_mask:0xf bank_mask:0xf
	v_add_f32_e32 v112, 1.0, v120
	v_add_f32_e32 v113, 1.0, v121
	v_rcp_f32_e32 v112, v112
	v_rcp_f32_e32 v113, v113
	s_nop 1
	v_add_f32_dpp v120, v128, v128 row_half_mirror row_mask:0xf bank_mask:0xf
	v_fmamk_f32 v120, v120, 0x3c000000, v176
	v_mul_f32_e32 v121, 0x4b800000, v120
	v_cmp_gt_f32_e32 vcc, s29, v120
	v_add_f32_e32 v123, 1.0, v123
	v_pk_mul_f32 v[112:113], v[112:113], v[118:119]
	v_cndmask_b32_e32 v120, v120, v121, vcc
	v_rsq_f32_e32 v128, v120
	v_rcp_f32_e32 v122, v122
	v_rcp_f32_e32 v123, v123
	v_ashrrev_i32_e32 v167, 31, v166
	v_mul_f32_e32 v118, 0x45800000, v128
	v_cndmask_b32_e32 v118, v128, v118, vcc
	v_pk_mul_f32 v[116:117], v[116:117], v[118:119] op_sel_hi:[1,0]
	v_pk_mul_f32 v[114:115], v[114:115], v[118:119] op_sel_hi:[1,0]
	v_pk_mul_f32 v[116:117], v[12:13], v[116:117]
	v_pk_mul_f32 v[120:121], v[122:123], v[174:175]
	v_pk_mul_f32 v[112:113], v[112:113], v[116:117]
	v_pk_mul_f32 v[116:117], v[182:183], v[118:119] op_sel_hi:[1,0]
	v_pk_mul_f32 v[122:123], v[186:187], v[180:181]
	v_pk_mul_f32 v[116:117], v[14:15], v[116:117]
	v_pk_mul_f32 v[114:115], v[8:9], v[114:115]
	v_pk_mul_f32 v[116:117], v[122:123], v[116:117]
	v_pk_mul_f32 v[114:115], v[120:121], v[114:115]
	v_pk_mul_f32 v[120:121], v[170:171], v[118:119] op_sel_hi:[1,0]
	v_pk_mul_f32 v[122:123], v[124:125], v[118:119] op_sel_hi:[1,0]
	v_pk_mul_f32 v[124:125], v[144:145], v[118:119] op_sel_hi:[1,0]
	v_mul_f32_e32 v119, 0xbfb8aa3b, v140
	v_exp_f32_e32 v119, v119
	v_mul_f32_e32 v128, 0xbfb8aa3b, v141
	v_exp_f32_e32 v129, v128
	v_mul_f32_e32 v137, v138, v118
	v_add_f32_e32 v119, 1.0, v119
	v_rcp_f32_e32 v128, v119
	v_add_f32_e32 v119, 1.0, v129
	v_rcp_f32_e32 v129, v119
	v_pk_mul_f32 v[126:127], v[126:127], v[118:119] op_sel_hi:[1,0]
	v_mul_f32_e32 v119, 0xbfb8aa3b, v3
	v_pk_mul_f32 v[126:127], v[0:1], v[126:127]
	v_pk_mul_f32 v[128:129], v[128:129], v[140:141]
	v_exp_f32_e32 v119, v119
	v_pk_mul_f32 v[126:127], v[128:129], v[126:127]
	v_mul_f32_e32 v128, 0xbfb8aa3b, v136
	v_exp_f32_e32 v128, v128
	v_add_f32_e32 v119, 1.0, v119
	v_rcp_f32_e32 v119, v119
	v_pk_mul_f32 v[120:121], v[10:11], v[120:121]
	v_add_f32_e32 v128, 1.0, v128
	v_rcp_f32_e32 v156, v128
	v_mul_f32_e32 v129, v139, v118
	v_mul_f32_e32 v130, v119, v3
	v_pk_mul_f32 v[120:121], v[168:169], v[120:121]
	v_pk_mul_f32 v[118:119], v[156:157], v[136:137]
	v_pk_mul_f32 v[122:123], v[4:5], v[122:123]
	v_pk_mul_f32 v[124:125], v[6:7], v[124:125]
	v_mul_f32_e32 v128, v2, v129
	v_mov_b32_e32 v131, v118
	v_mov_b32_e32 v129, v119
	v_cvt_pk_bf16_f32 v112, v112, v113
	v_cvt_pk_bf16_f32 v113, v116, v117
	v_lshlrev_b64 v[116:117], 11, v[166:167]
	v_pk_mul_f32 v[122:123], v[132:133], v[122:123]
	v_pk_mul_f32 v[124:125], v[134:135], v[124:125]
	v_cvt_pk_bf16_f32 v114, v114, v115
	v_cvt_pk_bf16_f32 v115, v120, v121
	v_lshl_add_u64 v[116:117], v[150:151], 0, v[116:117]
	v_pk_mul_f32 v[118:119], v[130:131], v[128:129]
	global_store_dwordx4 v[116:117], v[112:115], off
	s_nop 1
	v_cvt_pk_bf16_f32 v112, v122, v123
	v_cvt_pk_bf16_f32 v113, v124, v125
	v_cvt_pk_bf16_f32 v114, v126, v127
	v_cvt_pk_bf16_f32 v115, v118, v119
	global_store_dwordx4 v[116:117], v[112:115], off offset:16
.LBB0_1431:
	s_or_b64 exec, exec, s[14:15]
	v_add_u32_e32 v3, s33, v166
	v_cmp_gt_i32_e32 vcc, s3, v3
	s_and_saveexec_b64 s[14:15], vcc
	s_cbranch_execz .LBB0_1433
	s_waitcnt vmcnt(23)
	v_lshlrev_b32_e32 v115, 16, v107
	v_lshlrev_b32_e32 v117, 16, v103
	v_and_b32_e32 v114, 0xffff0000, v107
	v_and_b32_e32 v116, 0xffff0000, v103
	s_waitcnt vmcnt(20)
	v_and_b32_e32 v112, 0xffff0000, v111
	v_lshlrev_b32_e32 v113, 16, v111
	v_pk_add_f32 v[114:115], v[114:115], v[116:117]
	v_lshlrev_b32_e32 v116, 16, v110
	v_and_b32_e32 v117, 0xffff0000, v110
	v_lshlrev_b32_e32 v110, 16, v106
	v_and_b32_e32 v111, 0xffff0000, v106
	v_lshlrev_b32_e32 v106, 16, v102
	v_and_b32_e32 v107, 0xffff0000, v102
	v_pk_add_f32 v[102:103], v[106:107], v[110:111]
	v_lshlrev_b32_e32 v110, 16, v109
	v_and_b32_e32 v111, 0xffff0000, v109
	v_lshlrev_b32_e32 v120, 16, v105
	v_and_b32_e32 v121, 0xffff0000, v105
	v_mul_f32_e32 v105, 0xbfb8aa3b, v110
	v_exp_f32_e32 v105, v105
	v_mul_f32_e32 v109, 0xbfb8aa3b, v111
	v_exp_f32_e32 v109, v109
	v_lshlrev_b32_e32 v122, 16, v101
	v_add_f32_e32 v105, 1.0, v105
	v_rcp_f32_e32 v124, v105
	v_add_f32_e32 v105, 1.0, v109
	v_rcp_f32_e32 v125, v105
	v_and_b32_e32 v123, 0xffff0000, v101
	v_and_b32_e32 v109, 0xffff0000, v104
	v_lshlrev_b32_e32 v134, 16, v93
	v_pk_mul_f32 v[110:111], v[124:125], v[110:111]
	v_lshlrev_b32_e32 v124, 16, v108
	v_and_b32_e32 v125, 0xffff0000, v108
	v_mul_f32_e32 v101, 0xbfb8aa3b, v124
	v_lshlrev_b32_e32 v108, 16, v104
	v_exp_f32_e32 v101, v101
	v_mul_f32_e32 v104, 0xbfb8aa3b, v125
	v_exp_f32_e32 v105, v104
	v_lshlrev_b32_e32 v104, 16, v100
	v_add_f32_e32 v101, 1.0, v101
	v_rcp_f32_e32 v126, v101
	v_add_f32_e32 v101, 1.0, v105
	v_rcp_f32_e32 v127, v101
	v_and_b32_e32 v105, 0xffff0000, v100
	v_pk_add_f32 v[100:101], v[104:105], v[108:109]
	v_and_b32_e32 v135, 0xffff0000, v93
	v_pk_mul_f32 v[108:109], v[126:127], v[124:125]
	v_lshlrev_b32_e32 v124, 16, v91
	v_and_b32_e32 v125, 0xffff0000, v91
	v_mul_f32_e32 v91, 0xbfb8aa3b, v124
	v_lshlrev_b32_e32 v126, 16, v95
	v_and_b32_e32 v127, 0xffff0000, v95
	v_exp_f32_e32 v91, v91
	v_mul_f32_e32 v95, 0xbfb8aa3b, v125
	v_exp_f32_e32 v95, v95
	v_lshlrev_b32_e32 v140, 16, v92
	v_add_f32_e32 v91, 1.0, v91
	v_rcp_f32_e32 v130, v91
	v_add_f32_e32 v91, 1.0, v95
	v_rcp_f32_e32 v131, v91
	v_and_b32_e32 v141, 0xffff0000, v92
	v_lshlrev_b32_e32 v92, 16, v96
	v_and_b32_e32 v93, 0xffff0000, v96
	v_lshlrev_b32_e32 v136, 16, v97
	v_and_b32_e32 v137, 0xffff0000, v97
	v_pk_add_f32 v[92:93], v[92:93], v[140:141]
	v_pk_mul_f32 v[124:125], v[130:131], v[124:125]
	v_lshlrev_b32_e32 v130, 16, v90
	v_and_b32_e32 v131, 0xffff0000, v90
	v_lshlrev_b32_e32 v90, 16, v94
	v_and_b32_e32 v91, 0xffff0000, v94
	v_lshlrev_b32_e32 v94, 16, v98
	v_and_b32_e32 v95, 0xffff0000, v98
	v_pk_add_f32 v[134:135], v[136:137], v[134:135]
	v_pk_mul_f32 v[96:97], v[92:93], v[92:93]
	v_pk_add_f32 v[90:91], v[94:95], v[90:91]
	v_mul_f32_e32 v94, 0xbfb8aa3b, v130
	v_pk_mul_f32 v[136:137], v[134:135], v[134:135]
	v_add_f32_e32 v96, v96, v97
	v_exp_f32_e32 v98, v94
	v_mul_f32_e32 v94, 0xbfb8aa3b, v131
	v_add_f32_e32 v96, v136, v96
	v_lshlrev_b32_e32 v128, 16, v99
	v_and_b32_e32 v129, 0xffff0000, v99
	v_exp_f32_e32 v99, v94
	v_pk_mul_f32 v[94:95], v[90:91], v[90:91]
	v_add_f32_e32 v96, v137, v96
	v_pk_add_f32 v[126:127], v[128:129], v[126:127]
	v_add_f32_e32 v94, v94, v96
	v_pk_mul_f32 v[128:129], v[126:127], v[126:127]
	v_add_f32_e32 v94, v95, v94
	v_add_f32_e32 v94, v128, v94
	v_pk_mul_f32 v[104:105], v[100:101], v[100:101]
	v_add_f32_e32 v94, v129, v94
	v_pk_add_f32 v[120:121], v[122:123], v[120:121]
	v_add_f32_e32 v94, v104, v94
	v_pk_mul_f32 v[122:123], v[120:121], v[120:121]
	v_lshlrev_b32_e32 v132, 16, v89
	v_add_f32_e32 v94, v105, v94
	v_and_b32_e32 v133, 0xffff0000, v89
	v_mul_f32_e32 v89, 0xbfb8aa3b, v132
	v_add_f32_e32 v94, v122, v94
	v_pk_mul_f32 v[106:107], v[102:103], v[102:103]
	v_exp_f32_e32 v89, v89
	v_add_f32_e32 v94, v123, v94
	v_add_f32_e32 v94, v106, v94
	v_pk_mul_f32 v[118:119], v[114:115], v[114:115]
	v_add_f32_e32 v94, v107, v94
	v_add_f32_e32 v94, v119, v94
	v_add_f32_e32 v89, 1.0, v89
	v_add_f32_e32 v96, v118, v94
	v_rcp_f32_e32 v138, v89
	v_mul_f32_e32 v89, 0xbfb8aa3b, v133
	v_exp_f32_e32 v89, v89
	v_lshlrev_b32_e32 v94, 16, v88
	v_and_b32_e32 v95, 0xffff0000, v88
	v_add_f32_e32 v98, 1.0, v98
	v_add_f32_e32 v89, 1.0, v89
	s_nop 1
	v_add_f32_dpp v88, v96, v96 quad_perm:[1,0,3,2] row_mask:0xf bank_mask:0xf
	v_rcp_f32_e32 v139, v89
	v_mul_f32_e32 v96, 0xbfb8aa3b, v94
	v_exp_f32_e32 v96, v96
	v_mul_f32_e32 v97, 0xbfb8aa3b, v95
	v_exp_f32_e32 v97, v97
	s_nop 1
	v_add_f32_dpp v104, v88, v88 quad_perm:[2,3,0,1] row_mask:0xf bank_mask:0xf
	v_add_f32_e32 v88, 1.0, v96
	v_add_f32_e32 v89, 1.0, v97
	v_rcp_f32_e32 v88, v88
	v_rcp_f32_e32 v89, v89
	s_nop 1
	v_add_f32_dpp v96, v104, v104 row_half_mirror row_mask:0xf bank_mask:0xf
	v_fmamk_f32 v96, v96, 0x3c000000, v176
	v_mul_f32_e32 v97, 0x4b800000, v96
	v_cmp_gt_f32_e32 vcc, s29, v96
	v_add_f32_e32 v99, 1.0, v99
	v_pk_mul_f32 v[88:89], v[88:89], v[94:95]
	v_cndmask_b32_e32 v96, v96, v97, vcc
	v_rsq_f32_e32 v104, v96
	v_rcp_f32_e32 v98, v98
	v_rcp_f32_e32 v99, v99
	v_ashrrev_i32_e32 v165, 31, v164
	v_mul_f32_e32 v94, 0x45800000, v104
	v_cndmask_b32_e32 v94, v104, v94, vcc
	v_pk_mul_f32 v[92:93], v[92:93], v[94:95] op_sel_hi:[1,0]
	v_pk_mul_f32 v[90:91], v[90:91], v[94:95] op_sel_hi:[1,0]
	v_pk_mul_f32 v[92:93], v[12:13], v[92:93]
	v_pk_mul_f32 v[96:97], v[98:99], v[130:131]
	v_pk_mul_f32 v[88:89], v[88:89], v[92:93]
	v_pk_mul_f32 v[92:93], v[134:135], v[94:95] op_sel_hi:[1,0]
	v_pk_mul_f32 v[98:99], v[138:139], v[132:133]
	v_pk_mul_f32 v[92:93], v[14:15], v[92:93]
	v_pk_mul_f32 v[90:91], v[8:9], v[90:91]
	v_pk_mul_f32 v[92:93], v[98:99], v[92:93]
	v_pk_mul_f32 v[90:91], v[96:97], v[90:91]
	v_pk_mul_f32 v[96:97], v[126:127], v[94:95] op_sel_hi:[1,0]
	v_pk_mul_f32 v[98:99], v[100:101], v[94:95] op_sel_hi:[1,0]
	v_pk_mul_f32 v[100:101], v[120:121], v[94:95] op_sel_hi:[1,0]
	v_mul_f32_e32 v95, 0xbfb8aa3b, v116
	v_exp_f32_e32 v95, v95
	v_mul_f32_e32 v104, 0xbfb8aa3b, v117
	v_exp_f32_e32 v105, v104
	v_pk_mul_f32 v[96:97], v[10:11], v[96:97]
	v_add_f32_e32 v95, 1.0, v95
	v_rcp_f32_e32 v104, v95
	v_add_f32_e32 v95, 1.0, v105
	v_rcp_f32_e32 v105, v95
	v_pk_mul_f32 v[102:103], v[102:103], v[94:95] op_sel_hi:[1,0]
	v_mul_f32_e32 v95, 0xbfb8aa3b, v113
	v_pk_mul_f32 v[102:103], v[0:1], v[102:103]
	v_pk_mul_f32 v[104:105], v[104:105], v[116:117]
	v_exp_f32_e32 v95, v95
	v_pk_mul_f32 v[102:103], v[104:105], v[102:103]
	v_mul_f32_e32 v104, 0xbfb8aa3b, v112
	v_exp_f32_e32 v104, v104
	v_add_f32_e32 v95, 1.0, v95
	v_rcp_f32_e32 v95, v95
	v_mul_f32_e32 v105, v115, v94
	v_add_f32_e32 v104, 1.0, v104
	v_rcp_f32_e32 v156, v104
	v_mul_f32_e32 v106, v95, v113
	v_mul_f32_e32 v113, v114, v94
	v_pk_mul_f32 v[96:97], v[124:125], v[96:97]
	v_pk_mul_f32 v[94:95], v[156:157], v[112:113]
	v_pk_mul_f32 v[98:99], v[4:5], v[98:99]
	v_pk_mul_f32 v[100:101], v[6:7], v[100:101]
	v_mul_f32_e32 v104, v2, v105
	v_mov_b32_e32 v107, v94
	v_mov_b32_e32 v105, v95
	v_cvt_pk_bf16_f32 v88, v88, v89
	v_cvt_pk_bf16_f32 v89, v92, v93
	v_lshlrev_b64 v[92:93], 11, v[164:165]
	v_pk_mul_f32 v[98:99], v[108:109], v[98:99]
	v_pk_mul_f32 v[100:101], v[110:111], v[100:101]
	v_cvt_pk_bf16_f32 v90, v90, v91
	v_cvt_pk_bf16_f32 v91, v96, v97
	v_lshl_add_u64 v[92:93], v[150:151], 0, v[92:93]
	v_pk_mul_f32 v[94:95], v[106:107], v[104:105]
	global_store_dwordx4 v[92:93], v[88:91], off
	s_nop 1
	v_cvt_pk_bf16_f32 v88, v98, v99
	v_cvt_pk_bf16_f32 v89, v100, v101
	v_cvt_pk_bf16_f32 v90, v102, v103
	v_cvt_pk_bf16_f32 v91, v94, v95
	global_store_dwordx4 v[92:93], v[88:91], off offset:16
.LBB0_1433:
	s_or_b64 exec, exec, s[14:15]
	v_add_u32_e32 v3, s33, v3
	v_cmp_gt_i32_e32 vcc, s3, v3
	s_and_saveexec_b64 s[14:15], vcc
	s_cbranch_execz .LBB0_1435
	s_waitcnt vmcnt(17)
	v_lshlrev_b32_e32 v91, 16, v83
	v_lshlrev_b32_e32 v93, 16, v79
	v_and_b32_e32 v90, 0xffff0000, v83
	v_and_b32_e32 v92, 0xffff0000, v79
	s_waitcnt vmcnt(14)
	v_and_b32_e32 v88, 0xffff0000, v87
	v_lshlrev_b32_e32 v89, 16, v87
	v_pk_add_f32 v[90:91], v[90:91], v[92:93]
	v_lshlrev_b32_e32 v92, 16, v86
	v_and_b32_e32 v93, 0xffff0000, v86
	v_lshlrev_b32_e32 v86, 16, v82
	v_and_b32_e32 v87, 0xffff0000, v82
	v_lshlrev_b32_e32 v82, 16, v78
	v_and_b32_e32 v83, 0xffff0000, v78
	v_pk_add_f32 v[78:79], v[82:83], v[86:87]
	v_lshlrev_b32_e32 v86, 16, v85
	v_and_b32_e32 v87, 0xffff0000, v85
	v_lshlrev_b32_e32 v96, 16, v81
	v_and_b32_e32 v97, 0xffff0000, v81
	v_mul_f32_e32 v81, 0xbfb8aa3b, v86
	v_exp_f32_e32 v81, v81
	v_mul_f32_e32 v85, 0xbfb8aa3b, v87
	v_exp_f32_e32 v85, v85
	v_lshlrev_b32_e32 v98, 16, v77
	v_add_f32_e32 v81, 1.0, v81
	v_rcp_f32_e32 v100, v81
	v_add_f32_e32 v81, 1.0, v85
	v_rcp_f32_e32 v101, v81
	v_and_b32_e32 v99, 0xffff0000, v77
	v_and_b32_e32 v85, 0xffff0000, v80
	v_lshlrev_b32_e32 v110, 16, v69
	v_pk_mul_f32 v[86:87], v[100:101], v[86:87]
	v_lshlrev_b32_e32 v100, 16, v84
	v_and_b32_e32 v101, 0xffff0000, v84
	v_mul_f32_e32 v77, 0xbfb8aa3b, v100
	v_lshlrev_b32_e32 v84, 16, v80
	v_exp_f32_e32 v77, v77
	v_mul_f32_e32 v80, 0xbfb8aa3b, v101
	v_exp_f32_e32 v81, v80
	v_lshlrev_b32_e32 v80, 16, v76
	v_add_f32_e32 v77, 1.0, v77
	v_rcp_f32_e32 v102, v77
	v_add_f32_e32 v77, 1.0, v81
	v_rcp_f32_e32 v103, v77
	v_and_b32_e32 v81, 0xffff0000, v76
	v_pk_add_f32 v[76:77], v[80:81], v[84:85]
	v_and_b32_e32 v111, 0xffff0000, v69
	v_pk_mul_f32 v[84:85], v[102:103], v[100:101]
	v_lshlrev_b32_e32 v100, 16, v67
	v_and_b32_e32 v101, 0xffff0000, v67
	v_mul_f32_e32 v67, 0xbfb8aa3b, v100
	v_lshlrev_b32_e32 v102, 16, v71
	v_and_b32_e32 v103, 0xffff0000, v71
	v_exp_f32_e32 v67, v67
	v_mul_f32_e32 v71, 0xbfb8aa3b, v101
	v_exp_f32_e32 v71, v71
	v_lshlrev_b32_e32 v116, 16, v68
	v_add_f32_e32 v67, 1.0, v67
	v_rcp_f32_e32 v106, v67
	v_add_f32_e32 v67, 1.0, v71
	v_rcp_f32_e32 v107, v67
	v_and_b32_e32 v117, 0xffff0000, v68
	v_lshlrev_b32_e32 v68, 16, v72
	v_and_b32_e32 v69, 0xffff0000, v72
	v_lshlrev_b32_e32 v112, 16, v73
	v_and_b32_e32 v113, 0xffff0000, v73
	v_pk_add_f32 v[68:69], v[68:69], v[116:117]
	v_pk_mul_f32 v[100:101], v[106:107], v[100:101]
	v_lshlrev_b32_e32 v106, 16, v66
	v_and_b32_e32 v107, 0xffff0000, v66
	v_lshlrev_b32_e32 v66, 16, v70
	v_and_b32_e32 v67, 0xffff0000, v70
	v_lshlrev_b32_e32 v70, 16, v74
	v_and_b32_e32 v71, 0xffff0000, v74
	v_pk_add_f32 v[110:111], v[112:113], v[110:111]
	v_pk_mul_f32 v[72:73], v[68:69], v[68:69]
	v_pk_add_f32 v[66:67], v[70:71], v[66:67]
	v_mul_f32_e32 v70, 0xbfb8aa3b, v106
	v_pk_mul_f32 v[112:113], v[110:111], v[110:111]
	v_add_f32_e32 v72, v72, v73
	v_exp_f32_e32 v74, v70
	v_mul_f32_e32 v70, 0xbfb8aa3b, v107
	v_add_f32_e32 v72, v112, v72
	v_lshlrev_b32_e32 v104, 16, v75
	v_and_b32_e32 v105, 0xffff0000, v75
	v_exp_f32_e32 v75, v70
	v_pk_mul_f32 v[70:71], v[66:67], v[66:67]
	v_add_f32_e32 v72, v113, v72
	v_pk_add_f32 v[102:103], v[104:105], v[102:103]
	v_add_f32_e32 v70, v70, v72
	v_pk_mul_f32 v[104:105], v[102:103], v[102:103]
	v_add_f32_e32 v70, v71, v70
	v_add_f32_e32 v70, v104, v70
	v_pk_mul_f32 v[80:81], v[76:77], v[76:77]
	v_add_f32_e32 v70, v105, v70
	v_pk_add_f32 v[96:97], v[98:99], v[96:97]
	v_add_f32_e32 v70, v80, v70
	v_pk_mul_f32 v[98:99], v[96:97], v[96:97]
	v_lshlrev_b32_e32 v108, 16, v65
	v_add_f32_e32 v70, v81, v70
	v_and_b32_e32 v109, 0xffff0000, v65
	v_mul_f32_e32 v65, 0xbfb8aa3b, v108
	v_add_f32_e32 v70, v98, v70
	v_pk_mul_f32 v[82:83], v[78:79], v[78:79]
	v_exp_f32_e32 v65, v65
	v_add_f32_e32 v70, v99, v70
	v_add_f32_e32 v70, v82, v70
	v_pk_mul_f32 v[94:95], v[90:91], v[90:91]
	v_add_f32_e32 v70, v83, v70
	v_add_f32_e32 v70, v95, v70
	v_add_f32_e32 v65, 1.0, v65
	v_add_f32_e32 v72, v94, v70
	v_rcp_f32_e32 v114, v65
	v_mul_f32_e32 v65, 0xbfb8aa3b, v109
	v_exp_f32_e32 v65, v65
	v_lshlrev_b32_e32 v70, 16, v64
	v_and_b32_e32 v71, 0xffff0000, v64
	v_add_f32_e32 v74, 1.0, v74
	v_add_f32_e32 v65, 1.0, v65
	s_nop 1
	v_add_f32_dpp v64, v72, v72 quad_perm:[1,0,3,2] row_mask:0xf bank_mask:0xf
	v_rcp_f32_e32 v115, v65
	v_mul_f32_e32 v72, 0xbfb8aa3b, v70
	v_exp_f32_e32 v72, v72
	v_mul_f32_e32 v73, 0xbfb8aa3b, v71
	v_exp_f32_e32 v73, v73
	s_nop 1
	v_add_f32_dpp v80, v64, v64 quad_perm:[2,3,0,1] row_mask:0xf bank_mask:0xf
	v_add_f32_e32 v64, 1.0, v72
	v_add_f32_e32 v65, 1.0, v73
	v_rcp_f32_e32 v64, v64
	v_rcp_f32_e32 v65, v65
	s_nop 1
	v_add_f32_dpp v72, v80, v80 row_half_mirror row_mask:0xf bank_mask:0xf
	v_fmamk_f32 v72, v72, 0x3c000000, v176
	v_mul_f32_e32 v73, 0x4b800000, v72
	v_cmp_gt_f32_e32 vcc, s29, v72
	v_add_f32_e32 v75, 1.0, v75
	v_pk_mul_f32 v[64:65], v[64:65], v[70:71]
	v_cndmask_b32_e32 v72, v72, v73, vcc
	v_rsq_f32_e32 v80, v72
	v_rcp_f32_e32 v74, v74
	v_rcp_f32_e32 v75, v75
	v_ashrrev_i32_e32 v163, 31, v162
	v_mul_f32_e32 v70, 0x45800000, v80
	v_cndmask_b32_e32 v70, v80, v70, vcc
	v_pk_mul_f32 v[68:69], v[68:69], v[70:71] op_sel_hi:[1,0]
	v_pk_mul_f32 v[66:67], v[66:67], v[70:71] op_sel_hi:[1,0]
	v_pk_mul_f32 v[68:69], v[12:13], v[68:69]
	v_pk_mul_f32 v[72:73], v[74:75], v[106:107]
	v_pk_mul_f32 v[64:65], v[64:65], v[68:69]
	v_pk_mul_f32 v[68:69], v[110:111], v[70:71] op_sel_hi:[1,0]
	v_pk_mul_f32 v[74:75], v[114:115], v[108:109]
	v_pk_mul_f32 v[68:69], v[14:15], v[68:69]
	v_pk_mul_f32 v[66:67], v[8:9], v[66:67]
	v_pk_mul_f32 v[68:69], v[74:75], v[68:69]
	v_pk_mul_f32 v[66:67], v[72:73], v[66:67]
	v_pk_mul_f32 v[72:73], v[102:103], v[70:71] op_sel_hi:[1,0]
	v_pk_mul_f32 v[74:75], v[76:77], v[70:71] op_sel_hi:[1,0]
	v_pk_mul_f32 v[76:77], v[96:97], v[70:71] op_sel_hi:[1,0]
	v_mul_f32_e32 v71, 0xbfb8aa3b, v92
	v_exp_f32_e32 v71, v71
	v_mul_f32_e32 v80, 0xbfb8aa3b, v93
	v_exp_f32_e32 v81, v80
	v_pk_mul_f32 v[72:73], v[10:11], v[72:73]
	v_add_f32_e32 v71, 1.0, v71
	v_rcp_f32_e32 v80, v71
	v_add_f32_e32 v71, 1.0, v81
	v_rcp_f32_e32 v81, v71
	v_pk_mul_f32 v[78:79], v[78:79], v[70:71] op_sel_hi:[1,0]
	v_mul_f32_e32 v71, 0xbfb8aa3b, v89
	v_pk_mul_f32 v[78:79], v[0:1], v[78:79]
	v_pk_mul_f32 v[80:81], v[80:81], v[92:93]
	v_exp_f32_e32 v71, v71
	v_pk_mul_f32 v[78:79], v[80:81], v[78:79]
	v_mul_f32_e32 v80, 0xbfb8aa3b, v88
	v_exp_f32_e32 v80, v80
	v_add_f32_e32 v71, 1.0, v71
	v_rcp_f32_e32 v71, v71
	v_mul_f32_e32 v81, v91, v70
	v_add_f32_e32 v80, 1.0, v80
	v_rcp_f32_e32 v156, v80
	v_mul_f32_e32 v82, v71, v89
	v_mul_f32_e32 v89, v90, v70
	v_pk_mul_f32 v[72:73], v[100:101], v[72:73]
	v_pk_mul_f32 v[70:71], v[156:157], v[88:89]
	v_pk_mul_f32 v[74:75], v[4:5], v[74:75]
	v_pk_mul_f32 v[76:77], v[6:7], v[76:77]
	v_mul_f32_e32 v80, v2, v81
	v_mov_b32_e32 v83, v70
	v_mov_b32_e32 v81, v71
	v_cvt_pk_bf16_f32 v64, v64, v65
	v_cvt_pk_bf16_f32 v65, v68, v69
	v_lshlrev_b64 v[68:69], 11, v[162:163]
	v_pk_mul_f32 v[74:75], v[84:85], v[74:75]
	v_pk_mul_f32 v[76:77], v[86:87], v[76:77]
	v_cvt_pk_bf16_f32 v66, v66, v67
	v_cvt_pk_bf16_f32 v67, v72, v73
	v_lshl_add_u64 v[68:69], v[150:151], 0, v[68:69]
	v_pk_mul_f32 v[70:71], v[82:83], v[80:81]
	global_store_dwordx4 v[68:69], v[64:67], off
	s_nop 1
	v_cvt_pk_bf16_f32 v64, v74, v75
	v_cvt_pk_bf16_f32 v65, v76, v77
	v_cvt_pk_bf16_f32 v66, v78, v79
	v_cvt_pk_bf16_f32 v67, v70, v71
	global_store_dwordx4 v[68:69], v[64:67], off offset:16
.LBB0_1435:
	s_or_b64 exec, exec, s[14:15]
	v_add_u32_e32 v3, s33, v3
	v_cmp_gt_i32_e32 vcc, s3, v3
	s_and_saveexec_b64 s[14:15], vcc
	s_cbranch_execz .LBB0_1437
	s_waitcnt vmcnt(11)
	v_and_b32_e32 v69, 0xffff0000, v55
	v_and_b32_e32 v68, 0xffff0000, v59
	s_waitcnt vmcnt(8)
	v_lshlrev_b32_e32 v65, 16, v63
	v_and_b32_e32 v64, 0xffff0000, v63
	v_lshlrev_b32_e32 v63, 16, v59
	v_pk_add_f32 v[68:69], v[68:69], 0 op_sel_hi:[1,0]
	v_add_f32_e32 v67, 0, v63
	v_mov_b32_e32 v66, v68
	v_mov_b32_e32 v70, v69
	v_lshlrev_b32_e32 v68, 16, v62
	v_and_b32_e32 v69, 0xffff0000, v62
	v_lshlrev_b32_e32 v62, 16, v58
	v_and_b32_e32 v63, 0xffff0000, v58
	v_lshlrev_b32_e32 v55, 16, v55
	v_pk_add_f32 v[58:59], v[62:63], 0 op_sel_hi:[1,0]
	v_lshlrev_b32_e32 v62, 16, v54
	v_and_b32_e32 v63, 0xffff0000, v54
	v_add_f32_e32 v71, 0, v55
	v_pk_add_f32 v[54:55], v[62:63], 0 op_sel_hi:[1,0]
	v_lshlrev_b32_e32 v62, 16, v61
	v_and_b32_e32 v63, 0xffff0000, v61
	v_lshlrev_b32_e32 v72, 16, v57
	v_and_b32_e32 v73, 0xffff0000, v57
	v_mul_f32_e32 v57, 0xbfb8aa3b, v62
	v_exp_f32_e32 v57, v57
	v_mul_f32_e32 v61, 0xbfb8aa3b, v63
	v_exp_f32_e32 v61, v61
	v_lshlrev_b32_e32 v74, 16, v53
	v_and_b32_e32 v75, 0xffff0000, v53
	v_add_f32_e32 v53, 1.0, v57
	v_rcp_f32_e32 v76, v53
	v_add_f32_e32 v53, 1.0, v61
	v_rcp_f32_e32 v77, v53
	v_and_b32_e32 v61, 0xffff0000, v56
	v_and_b32_e32 v79, 0xffff0000, v51
	v_lshlrev_b32_e32 v92, 16, v48
	v_pk_mul_f32 v[62:63], v[76:77], v[62:63]
	v_lshlrev_b32_e32 v76, 16, v60
	v_and_b32_e32 v77, 0xffff0000, v60
	v_lshlrev_b32_e32 v60, 16, v56
	v_pk_add_f32 v[56:57], v[60:61], 0 op_sel_hi:[1,0]
	v_mul_f32_e32 v53, 0xbfb8aa3b, v76
	v_mul_f32_e32 v61, 0xbfb8aa3b, v77
	v_exp_f32_e32 v53, v53
	v_exp_f32_e32 v78, v61
	v_lshlrev_b32_e32 v60, 16, v52
	v_and_b32_e32 v61, 0xffff0000, v52
	v_add_f32_e32 v52, 1.0, v53
	v_add_f32_e32 v53, 1.0, v78
	v_rcp_f32_e32 v52, v52
	v_rcp_f32_e32 v53, v53
	v_lshlrev_b32_e32 v78, 16, v51
	v_and_b32_e32 v93, 0xffff0000, v48
	v_lshlrev_b32_e32 v86, 16, v49
	v_pk_mul_f32 v[52:53], v[52:53], v[76:77]
	v_lshlrev_b32_e32 v76, 16, v43
	v_and_b32_e32 v77, 0xffff0000, v43
	v_mul_f32_e32 v43, 0xbfb8aa3b, v76
	v_exp_f32_e32 v43, v43
	v_mul_f32_e32 v51, 0xbfb8aa3b, v77
	v_exp_f32_e32 v51, v51
	v_and_b32_e32 v87, 0xffff0000, v49
	v_add_f32_e32 v43, 1.0, v43
	v_rcp_f32_e32 v82, v43
	v_add_f32_e32 v43, 1.0, v51
	v_rcp_f32_e32 v83, v43
	v_pk_add_f32 v[48:49], v[92:93], 0 op_sel_hi:[1,0]
	v_lshlrev_b32_e32 v92, 16, v44
	v_and_b32_e32 v93, 0xffff0000, v44
	v_lshlrev_b32_e32 v88, 16, v45
	v_and_b32_e32 v89, 0xffff0000, v45
	v_pk_add_f32 v[44:45], v[92:93], 0 op_sel_hi:[1,0]
	v_pk_mul_f32 v[76:77], v[82:83], v[76:77]
	v_lshlrev_b32_e32 v82, 16, v42
	v_and_b32_e32 v83, 0xffff0000, v42
	v_lshlrev_b32_e32 v42, 16, v50
	v_and_b32_e32 v43, 0xffff0000, v50
	v_lshlrev_b32_e32 v50, 16, v46
	v_and_b32_e32 v51, 0xffff0000, v46
	v_pk_add_f32 v[86:87], v[86:87], 0 op_sel_hi:[1,0]
	v_pk_add_f32 v[88:89], v[88:89], 0 op_sel_hi:[1,0]
	v_pk_add_f32 v[44:45], v[48:49], v[44:45]
	v_lshlrev_b32_e32 v80, 16, v47
	v_and_b32_e32 v81, 0xffff0000, v47
	v_pk_add_f32 v[42:43], v[42:43], 0 op_sel_hi:[1,0]
	v_pk_add_f32 v[46:47], v[50:51], 0 op_sel_hi:[1,0]
	v_pk_add_f32 v[86:87], v[86:87], v[88:89]
	v_pk_mul_f32 v[48:49], v[44:45], v[44:45]
	v_pk_add_f32 v[42:43], v[42:43], v[46:47]
	v_mul_f32_e32 v46, 0xbfb8aa3b, v82
	v_pk_mul_f32 v[88:89], v[86:87], v[86:87]
	v_add_f32_e32 v48, v48, v49
	v_exp_f32_e32 v50, v46
	v_mul_f32_e32 v46, 0xbfb8aa3b, v83
	v_add_f32_e32 v48, v88, v48
	v_pk_add_f32 v[78:79], v[78:79], 0 op_sel_hi:[1,0]
	v_pk_add_f32 v[80:81], v[80:81], 0 op_sel_hi:[1,0]
	v_exp_f32_e32 v51, v46
	v_pk_mul_f32 v[46:47], v[42:43], v[42:43]
	v_add_f32_e32 v48, v89, v48
	v_pk_add_f32 v[78:79], v[78:79], v[80:81]
	v_add_f32_e32 v46, v46, v48
	v_pk_add_f32 v[60:61], v[60:61], 0 op_sel_hi:[1,0]
	v_pk_mul_f32 v[80:81], v[78:79], v[78:79]
	v_add_f32_e32 v46, v47, v46
	v_pk_add_f32 v[56:57], v[56:57], v[60:61]
	v_add_f32_e32 v46, v80, v46
	v_pk_add_f32 v[72:73], v[72:73], 0 op_sel_hi:[1,0]
	v_pk_add_f32 v[74:75], v[74:75], 0 op_sel_hi:[1,0]
	v_pk_mul_f32 v[60:61], v[56:57], v[56:57]
	v_add_f32_e32 v46, v81, v46
	v_pk_add_f32 v[72:73], v[72:73], v[74:75]
	v_add_f32_e32 v46, v60, v46
	v_pk_mul_f32 v[74:75], v[72:73], v[72:73]
	v_lshlrev_b32_e32 v84, 16, v41
	v_add_f32_e32 v46, v61, v46
	v_pk_add_f32 v[54:55], v[58:59], v[54:55]
	v_and_b32_e32 v85, 0xffff0000, v41
	v_mul_f32_e32 v41, 0xbfb8aa3b, v84
	v_add_f32_e32 v46, v74, v46
	v_pk_mul_f32 v[58:59], v[54:55], v[54:55]
	v_exp_f32_e32 v41, v41
	v_add_f32_e32 v46, v75, v46
	v_pk_add_f32 v[66:67], v[66:67], v[70:71]
	v_add_f32_e32 v46, v58, v46
	v_pk_mul_f32 v[70:71], v[66:67], v[66:67]
	v_add_f32_e32 v46, v59, v46
	v_add_f32_e32 v46, v71, v46
	v_add_f32_e32 v41, 1.0, v41
	v_add_f32_e32 v48, v70, v46
	v_rcp_f32_e32 v90, v41
	v_mul_f32_e32 v41, 0xbfb8aa3b, v85
	v_exp_f32_e32 v41, v41
	v_lshlrev_b32_e32 v46, 16, v40
	v_and_b32_e32 v47, 0xffff0000, v40
	v_add_f32_e32 v50, 1.0, v50
	v_add_f32_e32 v41, 1.0, v41
	s_nop 1
	v_add_f32_dpp v40, v48, v48 quad_perm:[1,0,3,2] row_mask:0xf bank_mask:0xf
	v_rcp_f32_e32 v91, v41
	v_mul_f32_e32 v48, 0xbfb8aa3b, v46
	v_exp_f32_e32 v48, v48
	v_mul_f32_e32 v49, 0xbfb8aa3b, v47
	v_exp_f32_e32 v49, v49
	s_nop 1
	v_add_f32_dpp v58, v40, v40 quad_perm:[2,3,0,1] row_mask:0xf bank_mask:0xf
	v_add_f32_e32 v40, 1.0, v48
	v_add_f32_e32 v41, 1.0, v49
	v_rcp_f32_e32 v40, v40
	v_rcp_f32_e32 v41, v41
	s_nop 1
	v_add_f32_dpp v48, v58, v58 row_half_mirror row_mask:0xf bank_mask:0xf
	v_fmamk_f32 v48, v48, 0x3c000000, v176
	v_mul_f32_e32 v49, 0x4b800000, v48
	v_cmp_gt_f32_e32 vcc, s29, v48
	v_add_f32_e32 v51, 1.0, v51
	v_pk_mul_f32 v[40:41], v[40:41], v[46:47]
	v_cndmask_b32_e32 v48, v48, v49, vcc
	v_rsq_f32_e32 v58, v48
	v_rcp_f32_e32 v50, v50
	v_rcp_f32_e32 v51, v51
	v_ashrrev_i32_e32 v161, 31, v160
	v_mul_f32_e32 v46, 0x45800000, v58
	v_cndmask_b32_e32 v46, v58, v46, vcc
	v_pk_mul_f32 v[44:45], v[44:45], v[46:47] op_sel_hi:[1,0]
	v_pk_mul_f32 v[48:49], v[50:51], v[82:83]
	v_pk_mul_f32 v[44:45], v[12:13], v[44:45]
	v_pk_mul_f32 v[50:51], v[90:91], v[84:85]
	v_pk_mul_f32 v[40:41], v[40:41], v[44:45]
	v_pk_mul_f32 v[44:45], v[86:87], v[46:47] op_sel_hi:[1,0]
	v_pk_mul_f32 v[42:43], v[42:43], v[46:47] op_sel_hi:[1,0]
	v_pk_mul_f32 v[44:45], v[14:15], v[44:45]
	v_pk_mul_f32 v[42:43], v[8:9], v[42:43]
	v_pk_mul_f32 v[44:45], v[50:51], v[44:45]
	v_pk_mul_f32 v[50:51], v[56:57], v[46:47] op_sel_hi:[1,0]
	v_pk_mul_f32 v[42:43], v[48:49], v[42:43]
	v_pk_mul_f32 v[50:51], v[4:5], v[50:51]
	v_pk_mul_f32 v[48:49], v[78:79], v[46:47] op_sel_hi:[1,0]
	v_pk_mul_f32 v[50:51], v[52:53], v[50:51]
	v_pk_mul_f32 v[52:53], v[72:73], v[46:47] op_sel_hi:[1,0]
	v_mul_f32_e32 v47, 0xbfb8aa3b, v68
	v_exp_f32_e32 v47, v47
	v_mul_f32_e32 v56, 0xbfb8aa3b, v69
	v_exp_f32_e32 v57, v56
	v_pk_mul_f32 v[48:49], v[10:11], v[48:49]
	v_add_f32_e32 v47, 1.0, v47
	v_rcp_f32_e32 v56, v47
	v_add_f32_e32 v47, 1.0, v57
	v_rcp_f32_e32 v57, v47
	v_pk_mul_f32 v[54:55], v[54:55], v[46:47] op_sel_hi:[1,0]
	v_mul_f32_e32 v47, 0xbfb8aa3b, v65
	v_pk_mul_f32 v[54:55], v[0:1], v[54:55]
	v_pk_mul_f32 v[56:57], v[56:57], v[68:69]
	v_exp_f32_e32 v47, v47
	v_pk_mul_f32 v[54:55], v[56:57], v[54:55]
	v_mul_f32_e32 v56, 0xbfb8aa3b, v64
	v_exp_f32_e32 v56, v56
	v_add_f32_e32 v47, 1.0, v47
	v_rcp_f32_e32 v47, v47
	v_mul_f32_e32 v57, v67, v46
	v_add_f32_e32 v56, 1.0, v56
	v_rcp_f32_e32 v156, v56
	v_mul_f32_e32 v58, v47, v65
	v_mul_f32_e32 v65, v66, v46
	v_pk_mul_f32 v[48:49], v[76:77], v[48:49]
	v_pk_mul_f32 v[46:47], v[156:157], v[64:65]
	v_pk_mul_f32 v[52:53], v[6:7], v[52:53]
	v_mul_f32_e32 v56, v2, v57
	v_mov_b32_e32 v59, v46
	v_mov_b32_e32 v57, v47
	v_cvt_pk_bf16_f32 v40, v40, v41
	v_cvt_pk_bf16_f32 v41, v44, v45
	v_lshlrev_b64 v[44:45], 11, v[160:161]
	v_pk_mul_f32 v[52:53], v[62:63], v[52:53]
	v_cvt_pk_bf16_f32 v42, v42, v43
	v_cvt_pk_bf16_f32 v43, v48, v49
	v_lshl_add_u64 v[44:45], v[150:151], 0, v[44:45]
	v_pk_mul_f32 v[46:47], v[58:59], v[56:57]
	global_store_dwordx4 v[44:45], v[40:43], off
	s_nop 1
	v_cvt_pk_bf16_f32 v40, v50, v51
	v_cvt_pk_bf16_f32 v41, v52, v53
	v_cvt_pk_bf16_f32 v42, v54, v55
	v_cvt_pk_bf16_f32 v43, v46, v47
	global_store_dwordx4 v[44:45], v[40:43], off offset:16
.LBB0_1437:
	s_or_b64 exec, exec, s[14:15]
	v_add_u32_e32 v3, s33, v3
	v_cmp_gt_i32_e32 vcc, s3, v3
	s_and_saveexec_b64 s[14:15], vcc
	s_cbranch_execz .LBB0_1428
	s_waitcnt vmcnt(5)
	v_and_b32_e32 v45, 0xffff0000, v31
	v_and_b32_e32 v44, 0xffff0000, v35
	s_waitcnt vmcnt(2)
	v_lshlrev_b32_e32 v41, 16, v39
	v_and_b32_e32 v40, 0xffff0000, v39
	v_lshlrev_b32_e32 v39, 16, v35
	v_pk_add_f32 v[44:45], v[44:45], 0 op_sel_hi:[1,0]
	v_add_f32_e32 v43, 0, v39
	v_mov_b32_e32 v42, v44
	v_mov_b32_e32 v46, v45
	v_lshlrev_b32_e32 v44, 16, v38
	v_and_b32_e32 v45, 0xffff0000, v38
	v_lshlrev_b32_e32 v38, 16, v34
	v_and_b32_e32 v39, 0xffff0000, v34
	v_lshlrev_b32_e32 v31, 16, v31
	v_pk_add_f32 v[34:35], v[38:39], 0 op_sel_hi:[1,0]
	v_lshlrev_b32_e32 v38, 16, v30
	v_and_b32_e32 v39, 0xffff0000, v30
	v_add_f32_e32 v47, 0, v31
	v_pk_add_f32 v[30:31], v[38:39], 0 op_sel_hi:[1,0]
	v_lshlrev_b32_e32 v38, 16, v37
	v_and_b32_e32 v39, 0xffff0000, v37
	v_lshlrev_b32_e32 v48, 16, v33
	v_and_b32_e32 v49, 0xffff0000, v33
	v_mul_f32_e32 v33, 0xbfb8aa3b, v38
	v_exp_f32_e32 v33, v33
	v_mul_f32_e32 v37, 0xbfb8aa3b, v39
	v_exp_f32_e32 v37, v37
	v_lshlrev_b32_e32 v50, 16, v29
	v_and_b32_e32 v51, 0xffff0000, v29
	v_add_f32_e32 v29, 1.0, v33
	v_rcp_f32_e32 v52, v29
	v_add_f32_e32 v29, 1.0, v37
	v_rcp_f32_e32 v53, v29
	v_and_b32_e32 v37, 0xffff0000, v32
	v_and_b32_e32 v55, 0xffff0000, v27
	v_lshlrev_b32_e32 v68, 16, v24
	v_pk_mul_f32 v[38:39], v[52:53], v[38:39]
	v_lshlrev_b32_e32 v52, 16, v36
	v_and_b32_e32 v53, 0xffff0000, v36
	v_lshlrev_b32_e32 v36, 16, v32
	v_pk_add_f32 v[32:33], v[36:37], 0 op_sel_hi:[1,0]
	v_mul_f32_e32 v29, 0xbfb8aa3b, v52
	v_mul_f32_e32 v37, 0xbfb8aa3b, v53
	v_exp_f32_e32 v29, v29
	v_exp_f32_e32 v54, v37
	v_lshlrev_b32_e32 v36, 16, v28
	v_and_b32_e32 v37, 0xffff0000, v28
	v_add_f32_e32 v28, 1.0, v29
	v_add_f32_e32 v29, 1.0, v54
	v_rcp_f32_e32 v28, v28
	v_rcp_f32_e32 v29, v29
	v_lshlrev_b32_e32 v54, 16, v27
	v_and_b32_e32 v69, 0xffff0000, v24
	v_lshlrev_b32_e32 v62, 16, v25
	v_pk_mul_f32 v[28:29], v[28:29], v[52:53]
	v_lshlrev_b32_e32 v52, 16, v19
	v_and_b32_e32 v53, 0xffff0000, v19
	v_mul_f32_e32 v19, 0xbfb8aa3b, v52
	v_exp_f32_e32 v19, v19
	v_mul_f32_e32 v27, 0xbfb8aa3b, v53
	v_exp_f32_e32 v27, v27
	v_and_b32_e32 v63, 0xffff0000, v25
	v_add_f32_e32 v19, 1.0, v19
	v_rcp_f32_e32 v58, v19
	v_add_f32_e32 v19, 1.0, v27
	v_rcp_f32_e32 v59, v19
	v_pk_add_f32 v[24:25], v[68:69], 0 op_sel_hi:[1,0]
	v_lshlrev_b32_e32 v68, 16, v20
	v_and_b32_e32 v69, 0xffff0000, v20
	v_lshlrev_b32_e32 v64, 16, v21
	v_and_b32_e32 v65, 0xffff0000, v21
	v_pk_add_f32 v[20:21], v[68:69], 0 op_sel_hi:[1,0]
	v_pk_mul_f32 v[52:53], v[58:59], v[52:53]
	v_lshlrev_b32_e32 v58, 16, v18
	v_and_b32_e32 v59, 0xffff0000, v18
	v_lshlrev_b32_e32 v18, 16, v26
	v_and_b32_e32 v19, 0xffff0000, v26
	v_lshlrev_b32_e32 v26, 16, v22
	v_and_b32_e32 v27, 0xffff0000, v22
	v_pk_add_f32 v[62:63], v[62:63], 0 op_sel_hi:[1,0]
	v_pk_add_f32 v[64:65], v[64:65], 0 op_sel_hi:[1,0]
	v_pk_add_f32 v[20:21], v[24:25], v[20:21]
	v_lshlrev_b32_e32 v56, 16, v23
	v_and_b32_e32 v57, 0xffff0000, v23
	v_pk_add_f32 v[18:19], v[18:19], 0 op_sel_hi:[1,0]
	v_pk_add_f32 v[22:23], v[26:27], 0 op_sel_hi:[1,0]
	v_pk_add_f32 v[62:63], v[62:63], v[64:65]
	v_pk_mul_f32 v[24:25], v[20:21], v[20:21]
	v_pk_add_f32 v[18:19], v[18:19], v[22:23]
	v_mul_f32_e32 v22, 0xbfb8aa3b, v58
	v_pk_mul_f32 v[64:65], v[62:63], v[62:63]
	v_add_f32_e32 v24, v24, v25
	v_exp_f32_e32 v26, v22
	v_mul_f32_e32 v22, 0xbfb8aa3b, v59
	v_add_f32_e32 v24, v64, v24
	v_pk_add_f32 v[54:55], v[54:55], 0 op_sel_hi:[1,0]
	v_pk_add_f32 v[56:57], v[56:57], 0 op_sel_hi:[1,0]
	v_exp_f32_e32 v27, v22
	v_pk_mul_f32 v[22:23], v[18:19], v[18:19]
	v_add_f32_e32 v24, v65, v24
	v_pk_add_f32 v[54:55], v[54:55], v[56:57]
	v_add_f32_e32 v22, v22, v24
	v_pk_add_f32 v[36:37], v[36:37], 0 op_sel_hi:[1,0]
	v_pk_mul_f32 v[56:57], v[54:55], v[54:55]
	v_add_f32_e32 v22, v23, v22
	v_pk_add_f32 v[32:33], v[32:33], v[36:37]
	v_add_f32_e32 v22, v56, v22
	v_pk_add_f32 v[48:49], v[48:49], 0 op_sel_hi:[1,0]
	v_pk_add_f32 v[50:51], v[50:51], 0 op_sel_hi:[1,0]
	v_pk_mul_f32 v[36:37], v[32:33], v[32:33]
	v_add_f32_e32 v22, v57, v22
	v_pk_add_f32 v[48:49], v[48:49], v[50:51]
	v_add_f32_e32 v22, v36, v22
	v_pk_mul_f32 v[50:51], v[48:49], v[48:49]
	v_lshlrev_b32_e32 v60, 16, v17
	v_add_f32_e32 v22, v37, v22
	v_pk_add_f32 v[30:31], v[34:35], v[30:31]
	v_and_b32_e32 v61, 0xffff0000, v17
	v_mul_f32_e32 v17, 0xbfb8aa3b, v60
	v_add_f32_e32 v22, v50, v22
	v_pk_mul_f32 v[34:35], v[30:31], v[30:31]
	v_exp_f32_e32 v17, v17
	v_add_f32_e32 v22, v51, v22
	v_pk_add_f32 v[42:43], v[42:43], v[46:47]
	v_add_f32_e32 v22, v34, v22
	v_pk_mul_f32 v[46:47], v[42:43], v[42:43]
	v_add_f32_e32 v22, v35, v22
	v_add_f32_e32 v22, v47, v22
	v_add_f32_e32 v17, 1.0, v17
	v_add_f32_e32 v24, v46, v22
	v_rcp_f32_e32 v66, v17
	v_mul_f32_e32 v17, 0xbfb8aa3b, v61
	v_exp_f32_e32 v17, v17
	v_lshlrev_b32_e32 v22, 16, v16
	v_and_b32_e32 v23, 0xffff0000, v16
	v_add_f32_e32 v26, 1.0, v26
	v_add_f32_e32 v17, 1.0, v17
	s_nop 1
	v_add_f32_dpp v16, v24, v24 quad_perm:[1,0,3,2] row_mask:0xf bank_mask:0xf
	v_rcp_f32_e32 v67, v17
	v_mul_f32_e32 v24, 0xbfb8aa3b, v22
	v_exp_f32_e32 v24, v24
	v_mul_f32_e32 v25, 0xbfb8aa3b, v23
	v_exp_f32_e32 v25, v25
	s_nop 1
	v_add_f32_dpp v34, v16, v16 quad_perm:[2,3,0,1] row_mask:0xf bank_mask:0xf
	v_add_f32_e32 v16, 1.0, v24
	v_add_f32_e32 v17, 1.0, v25
	v_rcp_f32_e32 v16, v16
	v_rcp_f32_e32 v17, v17
	s_nop 1
	v_add_f32_dpp v24, v34, v34 row_half_mirror row_mask:0xf bank_mask:0xf
	v_fmamk_f32 v24, v24, 0x3c000000, v176
	v_mul_f32_e32 v25, 0x4b800000, v24
	v_cmp_gt_f32_e32 vcc, s29, v24
	v_add_f32_e32 v27, 1.0, v27
	v_pk_mul_f32 v[16:17], v[16:17], v[22:23]
	v_cndmask_b32_e32 v24, v24, v25, vcc
	v_rsq_f32_e32 v34, v24
	v_rcp_f32_e32 v26, v26
	v_rcp_f32_e32 v27, v27
	v_ashrrev_i32_e32 v159, 31, v158
	v_mul_f32_e32 v22, 0x45800000, v34
	v_cndmask_b32_e32 v22, v34, v22, vcc
	v_pk_mul_f32 v[20:21], v[20:21], v[22:23] op_sel_hi:[1,0]
	v_pk_mul_f32 v[24:25], v[26:27], v[58:59]
	v_pk_mul_f32 v[20:21], v[12:13], v[20:21]
	v_pk_mul_f32 v[26:27], v[66:67], v[60:61]
	v_pk_mul_f32 v[16:17], v[16:17], v[20:21]
	v_pk_mul_f32 v[20:21], v[62:63], v[22:23] op_sel_hi:[1,0]
	v_pk_mul_f32 v[18:19], v[18:19], v[22:23] op_sel_hi:[1,0]
	v_pk_mul_f32 v[20:21], v[14:15], v[20:21]
	v_pk_mul_f32 v[18:19], v[8:9], v[18:19]
	v_pk_mul_f32 v[20:21], v[26:27], v[20:21]
	v_pk_mul_f32 v[26:27], v[32:33], v[22:23] op_sel_hi:[1,0]
	v_pk_mul_f32 v[18:19], v[24:25], v[18:19]
	v_pk_mul_f32 v[26:27], v[4:5], v[26:27]
	v_pk_mul_f32 v[24:25], v[54:55], v[22:23] op_sel_hi:[1,0]
	v_pk_mul_f32 v[26:27], v[28:29], v[26:27]
	v_pk_mul_f32 v[28:29], v[48:49], v[22:23] op_sel_hi:[1,0]
	v_mul_f32_e32 v23, 0xbfb8aa3b, v44
	v_exp_f32_e32 v23, v23
	v_mul_f32_e32 v32, 0xbfb8aa3b, v45
	v_exp_f32_e32 v33, v32
	v_pk_mul_f32 v[24:25], v[10:11], v[24:25]
	v_add_f32_e32 v23, 1.0, v23
	v_rcp_f32_e32 v32, v23
	v_add_f32_e32 v23, 1.0, v33
	v_rcp_f32_e32 v33, v23
	v_pk_mul_f32 v[30:31], v[30:31], v[22:23] op_sel_hi:[1,0]
	v_mul_f32_e32 v23, 0xbfb8aa3b, v41
	v_pk_mul_f32 v[30:31], v[0:1], v[30:31]
	v_pk_mul_f32 v[32:33], v[32:33], v[44:45]
	v_exp_f32_e32 v23, v23
	v_pk_mul_f32 v[30:31], v[32:33], v[30:31]
	v_mul_f32_e32 v32, 0xbfb8aa3b, v40
	v_exp_f32_e32 v32, v32
	v_add_f32_e32 v23, 1.0, v23
	v_rcp_f32_e32 v23, v23
	v_mul_f32_e32 v33, v43, v22
	v_add_f32_e32 v32, 1.0, v32
	v_rcp_f32_e32 v156, v32
	v_mul_f32_e32 v34, v23, v41
	v_mul_f32_e32 v41, v42, v22
	v_pk_mul_f32 v[24:25], v[52:53], v[24:25]
	v_pk_mul_f32 v[22:23], v[156:157], v[40:41]
	v_pk_mul_f32 v[28:29], v[6:7], v[28:29]
	v_mul_f32_e32 v32, v2, v33
	v_mov_b32_e32 v35, v22
	v_mov_b32_e32 v33, v23
	v_cvt_pk_bf16_f32 v16, v16, v17
	v_cvt_pk_bf16_f32 v17, v20, v21
	v_lshlrev_b64 v[20:21], 11, v[158:159]
	v_pk_mul_f32 v[28:29], v[38:39], v[28:29]
	v_cvt_pk_bf16_f32 v18, v18, v19
	v_cvt_pk_bf16_f32 v19, v24, v25
	v_lshl_add_u64 v[20:21], v[150:151], 0, v[20:21]
	v_pk_mul_f32 v[22:23], v[34:35], v[32:33]
	global_store_dwordx4 v[20:21], v[16:19], off
	s_nop 1
	v_cvt_pk_bf16_f32 v16, v26, v27
	v_cvt_pk_bf16_f32 v17, v28, v29
	v_cvt_pk_bf16_f32 v18, v30, v31
	v_cvt_pk_bf16_f32 v19, v22, v23
	global_store_dwordx4 v[20:21], v[16:19], off offset:16
	s_branch .LBB0_1428

.LBB0_1559:
	v_add_u32_e32 v35, s90, v128
	s_waitcnt vmcnt(6)
	v_add_co_u32_e32 v36, vcc, s10, v24
	s_waitcnt vmcnt(4)
	v_min_i32_e32 v38, 0x2fff, v35
	v_addc_co_u32_e32 v37, vcc, -1, v25, vcc
	global_load_dwordx2 v[130:131], v[24:25], off
	global_load_dwordx2 v[132:133], v[36:37], off
	v_ashrrev_i32_e32 v39, 31, v38
	v_lshlrev_b64 v[38:39], 11, v[38:39]
	v_lshl_add_u64 v[40:41], v[16:17], 0, v[38:39]
	v_lshl_add_u64 v[38:39], v[18:19], 0, v[38:39]
	global_load_dwordx2 v[134:135], v[24:25], off offset:-512
	global_load_dwordx2 v[136:137], v[36:37], off offset:-512
	global_load_dwordx2 v[106:107], v[40:41], off
	global_load_dwordx2 v[110:111], v[40:41], off offset:512
	global_load_dwordx2 v[114:115], v[40:41], off offset:1024
	global_load_dwordx2 v[118:119], v[40:41], off offset:1536
	global_load_dwordx2 v[108:109], v[38:39], off
	global_load_dwordx2 v[112:113], v[38:39], off offset:512
	global_load_dwordx2 v[116:117], v[38:39], off offset:1024
	global_load_dwordx2 v[120:121], v[38:39], off offset:1536
	global_load_dwordx2 v[138:139], v[24:25], off offset:-1024
	global_load_dwordx2 v[140:141], v[36:37], off offset:-1024
	v_add_u32_e32 v88, s90, v129
	v_min_i32_e32 v38, 0x2fff, v88
	v_ashrrev_i32_e32 v39, 31, v38
	v_lshlrev_b64 v[38:39], 11, v[38:39]
	v_lshl_add_u64 v[40:41], v[16:17], 0, v[38:39]
	v_lshl_add_u64 v[38:39], v[18:19], 0, v[38:39]
	global_load_dwordx2 v[142:143], v[24:25], off offset:-1536
	global_load_dwordx2 v[102:103], v[40:41], off
	global_load_dwordx2 v[98:99], v[40:41], off offset:512
	global_load_dwordx2 v[94:95], v[40:41], off offset:1024
	global_load_dwordx2 v[90:91], v[40:41], off offset:1536
	global_load_dwordx2 v[144:145], v[36:37], off offset:-1536
	global_load_dwordx2 v[104:105], v[38:39], off
	global_load_dwordx2 v[100:101], v[38:39], off offset:512
	global_load_dwordx2 v[96:97], v[38:39], off offset:1024
	global_load_dwordx2 v[92:93], v[38:39], off offset:1536
	v_add_u32_e32 v70, s90, v30
	v_min_i32_e32 v36, 0x2fff, v70
	v_ashrrev_i32_e32 v37, 31, v36
	v_lshlrev_b64 v[36:37], 11, v[36:37]
	v_lshl_add_u64 v[38:39], v[16:17], 0, v[36:37]
	v_lshl_add_u64 v[36:37], v[18:19], 0, v[36:37]
	v_add_u32_e32 v52, s90, v29
	global_load_dwordx2 v[84:85], v[38:39], off
	global_load_dwordx2 v[80:81], v[38:39], off offset:512
	global_load_dwordx2 v[76:77], v[38:39], off offset:1024
	global_load_dwordx2 v[72:73], v[38:39], off offset:1536
	global_load_dwordx2 v[86:87], v[36:37], off
	global_load_dwordx2 v[82:83], v[36:37], off offset:512
	global_load_dwordx2 v[78:79], v[36:37], off offset:1024
	global_load_dwordx2 v[74:75], v[36:37], off offset:1536
	v_min_i32_e32 v36, 0x2fff, v52
	v_ashrrev_i32_e32 v37, 31, v36
	v_lshlrev_b64 v[36:37], 11, v[36:37]
	v_lshl_add_u64 v[38:39], v[16:17], 0, v[36:37]
	v_lshl_add_u64 v[36:37], v[18:19], 0, v[36:37]
	v_add_u32_e32 v34, s90, v28
	global_load_dwordx2 v[66:67], v[38:39], off
	global_load_dwordx2 v[62:63], v[38:39], off offset:512
	global_load_dwordx2 v[58:59], v[38:39], off offset:1024
	global_load_dwordx2 v[54:55], v[38:39], off offset:1536
	global_load_dwordx2 v[68:69], v[36:37], off
	global_load_dwordx2 v[64:65], v[36:37], off offset:512
	global_load_dwordx2 v[60:61], v[36:37], off offset:1024
	global_load_dwordx2 v[56:57], v[36:37], off offset:1536
	v_min_i32_e32 v36, 0x2fff, v34
	v_ashrrev_i32_e32 v37, 31, v36
	v_lshlrev_b64 v[36:37], 11, v[36:37]
	v_lshl_add_u64 v[38:39], v[16:17], 0, v[36:37]
	v_lshl_add_u64 v[146:147], v[18:19], 0, v[36:37]
	global_load_dwordx2 v[48:49], v[38:39], off
	global_load_dwordx2 v[44:45], v[38:39], off offset:512
	global_load_dwordx2 v[40:41], v[38:39], off offset:1024
	global_load_dwordx2 v[36:37], v[38:39], off offset:1536
	global_load_dwordx2 v[50:51], v[146:147], off
	global_load_dwordx2 v[46:47], v[146:147], off offset:512
	global_load_dwordx2 v[42:43], v[146:147], off offset:1024
	s_nop 0
	global_load_dwordx2 v[38:39], v[146:147], off offset:1536
	s_waitcnt vmcnt(47)
	v_lshlrev_b32_e32 v146, 16, v130
	v_and_b32_e32 v147, 0xffff0000, v130
	v_lshlrev_b32_e32 v130, 16, v131
	v_and_b32_e32 v131, 0xffff0000, v131
	s_waitcnt vmcnt(46)
	v_lshlrev_b32_e32 v148, 16, v132
	v_and_b32_e32 v149, 0xffff0000, v132
	v_lshlrev_b32_e32 v132, 16, v133
	v_and_b32_e32 v133, 0xffff0000, v133
	v_pk_add_f32 v[150:151], v[130:131], v[132:133]
	s_waitcnt vmcnt(45)
	v_lshlrev_b32_e32 v130, 16, v134
	v_and_b32_e32 v131, 0xffff0000, v134
	v_lshlrev_b32_e32 v132, 16, v135
	v_and_b32_e32 v133, 0xffff0000, v135
	s_waitcnt vmcnt(44)
	v_lshlrev_b32_e32 v134, 16, v136
	v_and_b32_e32 v135, 0xffff0000, v136
	v_lshlrev_b32_e32 v136, 16, v137
	v_and_b32_e32 v137, 0xffff0000, v137
	v_pk_add_f32 v[136:137], v[132:133], v[136:137]
	v_pk_add_f32 v[134:135], v[130:131], v[134:135]
	s_waitcnt vmcnt(35)
	v_lshlrev_b32_e32 v130, 16, v138
	v_and_b32_e32 v131, 0xffff0000, v138
	v_lshlrev_b32_e32 v132, 16, v139
	v_and_b32_e32 v133, 0xffff0000, v139
	s_waitcnt vmcnt(34)
	v_lshlrev_b32_e32 v138, 16, v140
	v_and_b32_e32 v139, 0xffff0000, v140
	v_lshlrev_b32_e32 v140, 16, v141
	v_and_b32_e32 v141, 0xffff0000, v141
	v_pk_add_f32 v[140:141], v[132:133], v[140:141]
	v_pk_add_f32 v[138:139], v[130:131], v[138:139]
	s_waitcnt vmcnt(33)
	v_lshlrev_b32_e32 v130, 16, v142
	v_and_b32_e32 v131, 0xffff0000, v142
	v_lshlrev_b32_e32 v132, 16, v143
	v_and_b32_e32 v133, 0xffff0000, v143
	s_waitcnt vmcnt(28)
	v_lshlrev_b32_e32 v142, 16, v144
	v_and_b32_e32 v143, 0xffff0000, v144
	v_lshlrev_b32_e32 v144, 16, v145
	v_and_b32_e32 v145, 0xffff0000, v145
	v_pk_add_f32 v[130:131], v[130:131], v[142:143]
	v_pk_add_f32 v[132:133], v[132:133], v[144:145]
	v_mov_b32_e32 v144, v139
	v_mov_b32_e32 v145, v131
	v_mov_b32_e32 v142, v138
	v_mov_b32_e32 v143, v130
	v_pk_mul_f32 v[144:145], v[144:145], v[144:145]
	v_pk_add_f32 v[146:147], v[146:147], v[148:149]
	v_pk_fma_f32 v[142:143], v[142:143], v[142:143], v[144:145]
	v_mov_b32_e32 v144, v140
	v_mov_b32_e32 v145, v132
	v_pk_fma_f32 v[142:143], v[144:145], v[144:145], v[142:143]
	v_mov_b32_e32 v144, v141
	v_mov_b32_e32 v145, v133
	v_mov_b32_e32 v148, v147
	v_mov_b32_e32 v149, v135
	v_pk_fma_f32 v[142:143], v[144:145], v[144:145], v[142:143]
	v_mov_b32_e32 v144, v146
	v_mov_b32_e32 v145, v134
	v_pk_mul_f32 v[148:149], v[148:149], v[148:149]
	v_add_f32_e32 v53, v142, v143
	v_pk_fma_f32 v[144:145], v[144:145], v[144:145], v[148:149]
	v_mov_b32_e32 v148, v150
	v_mov_b32_e32 v149, v136
	v_pk_fma_f32 v[144:145], v[148:149], v[148:149], v[144:145]
	v_mov_b32_e32 v148, v151
	v_mov_b32_e32 v149, v137
	v_pk_fma_f32 v[144:145], v[148:149], v[148:149], v[144:145]
	s_nop 0
	v_add_f32_e32 v53, v145, v53
	v_add_f32_e32 v53, v144, v53
	v_mov_b32_e32 v71, v53
	v_lshl_add_u64 v[144:145], v[32:33], 0, v[22:23]
	s_nop 1
	v_permlane32_swap_b32_e32 v71, v53
	s_nop 1
	v_add_f32_e32 v53, v53, v71
	v_mov_b32_e32 v71, v53
	s_nop 1
	v_permlane16_swap_b32_e32 v71, v53
	s_nop 1
	v_add_f32_e32 v53, v53, v71
	s_nop 1
	v_add_f32_dpp v53, v53, v53 row_ror:8 row_mask:0xf bank_mask:0xf
	s_nop 1
	v_add_f32_dpp v53, v53, v53 row_ror:4 row_mask:0xf bank_mask:0xf
	s_nop 1
	v_add_f32_dpp v53, v53, v53 quad_perm:[2,3,0,1] row_mask:0xf bank_mask:0xf
	s_nop 1
	v_add_f32_dpp v53, v53, v53 quad_perm:[1,0,3,2] row_mask:0xf bank_mask:0xf
	v_fmamk_f32 v53, v53, 0x3a800000, v31
	v_mul_f32_e32 v71, 0x4b800000, v53
	v_cmp_gt_f32_e32 vcc, s11, v53
	s_nop 1
	v_cndmask_b32_e32 v53, v53, v71, vcc
	v_rsq_f32_e32 v53, v53
	s_nop 0
	v_mul_f32_e32 v71, 0x45800000, v53
	v_cndmask_b32_e32 v142, v53, v71, vcc
	v_pk_mul_f32 v[130:131], v[130:131], v[142:143] op_sel_hi:[1,0]
	v_pk_mul_f32 v[132:133], v[132:133], v[142:143] op_sel_hi:[1,0]
	v_pk_mul_f32 v[130:131], v[0:1], v[130:131]
	v_pk_mul_f32 v[132:133], v[2:3], v[132:133]
	global_store_dwordx4 v[144:145], v[130:133], off nt
	v_cmp_gt_i32_e32 vcc, s8, v35
	s_nop 0
	v_pk_mul_f32 v[130:131], v[138:139], v[142:143] op_sel_hi:[1,0]
	v_pk_mul_f32 v[132:133], v[140:141], v[142:143] op_sel_hi:[1,0]
	v_pk_mul_f32 v[130:131], v[4:5], v[130:131]
	v_pk_mul_f32 v[132:133], v[6:7], v[132:133]
	global_store_dwordx4 v[144:145], v[130:133], off offset:1024 nt
	s_nop 1
	v_pk_mul_f32 v[130:131], v[134:135], v[142:143] op_sel_hi:[1,0]
	v_pk_mul_f32 v[132:133], v[136:137], v[142:143] op_sel_hi:[1,0]
	v_pk_mul_f32 v[130:131], v[8:9], v[130:131]
	v_pk_mul_f32 v[132:133], v[10:11], v[132:133]
	global_store_dwordx4 v[144:145], v[130:133], off offset:2048 nt
	s_nop 1
	v_pk_mul_f32 v[130:131], v[146:147], v[142:143] op_sel_hi:[1,0]
	v_pk_mul_f32 v[132:133], v[150:151], v[142:143] op_sel_hi:[1,0]
	v_pk_mul_f32 v[130:131], v[12:13], v[130:131]
	v_pk_mul_f32 v[132:133], v[14:15], v[132:133]
	global_store_dwordx4 v[144:145], v[130:133], off offset:3072 nt
	s_and_saveexec_b64 s[6:7], vcc
	s_cbranch_execz .LBB0_1561
	v_lshlrev_b32_e32 v130, 16, v118
	v_and_b32_e32 v131, 0xffff0000, v118
	v_lshlrev_b32_e32 v118, 16, v119
	v_and_b32_e32 v119, 0xffff0000, v119
	v_lshlrev_b32_e32 v132, 16, v120
	v_and_b32_e32 v133, 0xffff0000, v120
	v_lshlrev_b32_e32 v120, 16, v121
	v_and_b32_e32 v121, 0xffff0000, v121
	v_pk_add_f32 v[118:119], v[118:119], v[120:121]
	v_pk_add_f32 v[120:121], v[130:131], v[132:133]
	v_lshlrev_b32_e32 v130, 16, v114
	v_and_b32_e32 v131, 0xffff0000, v114
	v_lshlrev_b32_e32 v114, 16, v115
	v_and_b32_e32 v115, 0xffff0000, v115
	v_lshlrev_b32_e32 v132, 16, v116
	v_and_b32_e32 v133, 0xffff0000, v116
	v_lshlrev_b32_e32 v116, 16, v117
	v_and_b32_e32 v117, 0xffff0000, v117
	v_pk_add_f32 v[114:115], v[114:115], v[116:117]
	v_pk_add_f32 v[116:117], v[130:131], v[132:133]
	v_lshlrev_b32_e32 v130, 16, v110
	v_and_b32_e32 v131, 0xffff0000, v110
	v_lshlrev_b32_e32 v110, 16, v111
	v_and_b32_e32 v111, 0xffff0000, v111
	v_lshlrev_b32_e32 v132, 16, v112
	v_and_b32_e32 v133, 0xffff0000, v112
	v_lshlrev_b32_e32 v112, 16, v113
	v_and_b32_e32 v113, 0xffff0000, v113
	v_pk_add_f32 v[110:111], v[110:111], v[112:113]
	v_pk_add_f32 v[112:113], v[130:131], v[132:133]
	v_lshlrev_b32_e32 v130, 16, v106
	v_and_b32_e32 v131, 0xffff0000, v106
	v_lshlrev_b32_e32 v106, 16, v107
	v_and_b32_e32 v107, 0xffff0000, v107
	v_lshlrev_b32_e32 v132, 16, v108
	v_and_b32_e32 v133, 0xffff0000, v108
	v_lshlrev_b32_e32 v108, 16, v109
	v_and_b32_e32 v109, 0xffff0000, v109
	v_pk_add_f32 v[106:107], v[106:107], v[108:109]
	v_pk_add_f32 v[108:109], v[130:131], v[132:133]
	v_mov_b32_e32 v133, v113
	v_mov_b32_e32 v132, v109
	v_mov_b32_e32 v130, v108
	v_mov_b32_e32 v131, v112
	v_pk_mul_f32 v[132:133], v[132:133], v[132:133]
	v_mov_b32_e32 v134, v117
	v_pk_fma_f32 v[130:131], v[130:131], v[130:131], v[132:133]
	v_mov_b32_e32 v132, v106
	v_mov_b32_e32 v133, v110
	v_pk_fma_f32 v[130:131], v[132:133], v[132:133], v[130:131]
	v_mov_b32_e32 v132, v107
	v_mov_b32_e32 v133, v111
	v_mov_b32_e32 v135, v121
	v_pk_fma_f32 v[130:131], v[132:133], v[132:133], v[130:131]
	v_mov_b32_e32 v132, v116
	v_mov_b32_e32 v133, v120
	v_pk_mul_f32 v[134:135], v[134:135], v[134:135]
	v_add_f32_e32 v53, v130, v131
	v_pk_fma_f32 v[132:133], v[132:133], v[132:133], v[134:135]
	v_mov_b32_e32 v134, v114
	v_mov_b32_e32 v135, v118
	v_pk_fma_f32 v[132:133], v[134:135], v[134:135], v[132:133]
	v_mov_b32_e32 v134, v115
	v_mov_b32_e32 v135, v119
	v_pk_fma_f32 v[132:133], v[134:135], v[134:135], v[132:133]
	s_nop 0
	v_add_f32_e32 v53, v53, v132
	v_add_f32_e32 v53, v53, v133
	v_mov_b32_e32 v71, v53
	v_lshl_add_u64 v[132:133], v[32:33], 0, v[26:27]
	s_nop 1
	v_permlane32_swap_b32_e32 v71, v53
	s_nop 1
	v_add_f32_e32 v53, v53, v71
	v_mov_b32_e32 v71, v53
	s_nop 1
	v_permlane16_swap_b32_e32 v71, v53
	s_nop 1
	v_add_f32_e32 v53, v53, v71
	s_nop 1
	v_add_f32_dpp v53, v53, v53 row_ror:8 row_mask:0xf bank_mask:0xf
	s_nop 1
	v_add_f32_dpp v53, v53, v53 row_ror:4 row_mask:0xf bank_mask:0xf
	s_nop 1
	v_add_f32_dpp v53, v53, v53 quad_perm:[2,3,0,1] row_mask:0xf bank_mask:0xf
	s_nop 1
	v_add_f32_dpp v53, v53, v53 quad_perm:[1,0,3,2] row_mask:0xf bank_mask:0xf
	v_fmamk_f32 v53, v53, 0x3a800000, v31
	v_mul_f32_e32 v71, 0x4b800000, v53
	v_cmp_gt_f32_e32 vcc, s11, v53
	s_nop 1
	v_cndmask_b32_e32 v53, v53, v71, vcc
	v_rsq_f32_e32 v53, v53
	s_nop 0
	v_mul_f32_e32 v71, 0x45800000, v53
	v_cndmask_b32_e32 v130, v53, v71, vcc
	v_pk_mul_f32 v[134:135], v[108:109], v[130:131] op_sel_hi:[1,0]
	v_pk_mul_f32 v[106:107], v[106:107], v[130:131] op_sel_hi:[1,0]
	s_nop 0
	v_pk_mul_f32 v[108:109], v[2:3], v[106:107]
	v_pk_mul_f32 v[106:107], v[0:1], v[134:135]
	global_store_dwordx4 v[132:133], v[106:109], off nt
	s_nop 1
	v_pk_mul_f32 v[106:107], v[112:113], v[130:131] op_sel_hi:[1,0]
	v_pk_mul_f32 v[108:109], v[110:111], v[130:131] op_sel_hi:[1,0]
	v_pk_mul_f32 v[106:107], v[4:5], v[106:107]
	v_pk_mul_f32 v[108:109], v[6:7], v[108:109]
	global_store_dwordx4 v[132:133], v[106:109], off offset:1024 nt
	s_nop 1
	v_pk_mul_f32 v[106:107], v[116:117], v[130:131] op_sel_hi:[1,0]
	v_pk_mul_f32 v[108:109], v[114:115], v[130:131] op_sel_hi:[1,0]
	v_pk_mul_f32 v[106:107], v[8:9], v[106:107]
	v_pk_mul_f32 v[108:109], v[10:11], v[108:109]
	global_store_dwordx4 v[132:133], v[106:109], off offset:2048 nt
	s_nop 1
	v_pk_mul_f32 v[106:107], v[120:121], v[130:131] op_sel_hi:[1,0]
	v_pk_mul_f32 v[108:109], v[118:119], v[130:131] op_sel_hi:[1,0]
	v_pk_mul_f32 v[106:107], v[12:13], v[106:107]
	v_pk_mul_f32 v[108:109], v[14:15], v[108:109]
	global_store_dwordx4 v[132:133], v[106:109], off offset:3072 nt
.LBB0_1561:
	s_or_b64 exec, exec, s[6:7]
	v_add_u32_e32 v35, s33, v35
	v_cmp_gt_i32_e32 vcc, s8, v35
	s_and_saveexec_b64 s[6:7], vcc
	s_cbranch_execz .LBB0_1563
	s_waitcnt vmcnt(31)
	v_lshlrev_b32_e32 v106, 16, v104
	v_and_b32_e32 v107, 0xffff0000, v104
	v_lshlrev_b32_e32 v104, 16, v105
	v_and_b32_e32 v105, 0xffff0000, v105
	v_lshlrev_b32_e32 v108, 16, v102
	v_and_b32_e32 v109, 0xffff0000, v102
	v_lshlrev_b32_e32 v102, 16, v103
	v_and_b32_e32 v103, 0xffff0000, v103
	v_pk_add_f32 v[102:103], v[102:103], v[104:105]
	v_pk_add_f32 v[104:105], v[108:109], v[106:107]
	s_waitcnt vmcnt(30)
	v_lshlrev_b32_e32 v106, 16, v100
	v_and_b32_e32 v107, 0xffff0000, v100
	v_lshlrev_b32_e32 v100, 16, v101
	v_and_b32_e32 v101, 0xffff0000, v101
	v_lshlrev_b32_e32 v108, 16, v98
	v_and_b32_e32 v109, 0xffff0000, v98
	v_lshlrev_b32_e32 v98, 16, v99
	v_and_b32_e32 v99, 0xffff0000, v99
	v_pk_add_f32 v[98:99], v[98:99], v[100:101]
	v_pk_add_f32 v[100:101], v[108:109], v[106:107]
	s_waitcnt vmcnt(29)
	v_lshlrev_b32_e32 v106, 16, v96
	v_and_b32_e32 v107, 0xffff0000, v96
	v_lshlrev_b32_e32 v96, 16, v97
	v_and_b32_e32 v97, 0xffff0000, v97
	v_lshlrev_b32_e32 v108, 16, v94
	v_and_b32_e32 v109, 0xffff0000, v94
	v_lshlrev_b32_e32 v94, 16, v95
	v_and_b32_e32 v95, 0xffff0000, v95
	v_pk_add_f32 v[94:95], v[94:95], v[96:97]
	v_pk_add_f32 v[96:97], v[108:109], v[106:107]
	s_waitcnt vmcnt(28)
	v_lshlrev_b32_e32 v106, 16, v92
	v_and_b32_e32 v107, 0xffff0000, v92
	v_lshlrev_b32_e32 v108, 16, v90
	v_and_b32_e32 v109, 0xffff0000, v90
	v_lshlrev_b32_e32 v92, 16, v93
	v_and_b32_e32 v93, 0xffff0000, v93
	v_lshlrev_b32_e32 v90, 16, v91
	v_and_b32_e32 v91, 0xffff0000, v91
	v_pk_add_f32 v[106:107], v[108:109], v[106:107]
	v_mov_b32_e32 v108, v105
	v_mov_b32_e32 v109, v101
	v_pk_add_f32 v[92:93], v[90:91], v[92:93]
	v_mov_b32_e32 v90, v104
	v_mov_b32_e32 v91, v100
	v_pk_mul_f32 v[108:109], v[108:109], v[108:109]
	v_mov_b32_e32 v110, v97
	v_pk_fma_f32 v[90:91], v[90:91], v[90:91], v[108:109]
	v_mov_b32_e32 v108, v102
	v_mov_b32_e32 v109, v98
	v_pk_fma_f32 v[90:91], v[108:109], v[108:109], v[90:91]
	v_mov_b32_e32 v108, v103
	v_mov_b32_e32 v109, v99
	v_mov_b32_e32 v111, v107
	v_pk_fma_f32 v[90:91], v[108:109], v[108:109], v[90:91]
	v_mov_b32_e32 v108, v96
	v_mov_b32_e32 v109, v106
	v_pk_mul_f32 v[110:111], v[110:111], v[110:111]
	v_add_f32_e32 v53, v90, v91
	v_pk_fma_f32 v[108:109], v[108:109], v[108:109], v[110:111]
	v_mov_b32_e32 v110, v94
	v_mov_b32_e32 v111, v92
	v_pk_fma_f32 v[108:109], v[110:111], v[110:111], v[108:109]
	v_mov_b32_e32 v110, v95
	v_mov_b32_e32 v111, v93
	v_pk_fma_f32 v[108:109], v[110:111], v[110:111], v[108:109]
	v_ashrrev_i32_e32 v89, 31, v88
	v_add_f32_e32 v53, v53, v108
	v_add_f32_e32 v53, v53, v109
	v_mov_b32_e32 v71, v53
	v_lshlrev_b64 v[88:89], 12, v[88:89]
	v_lshl_add_u64 v[110:111], v[20:21], 0, v[88:89]
	s_nop 1
	v_permlane32_swap_b32_e32 v71, v53
	s_nop 1
	v_add_f32_e32 v53, v53, v71
	v_mov_b32_e32 v71, v53
	s_nop 1
	v_permlane16_swap_b32_e32 v71, v53
	s_nop 1
	v_add_f32_e32 v53, v53, v71
	s_nop 1
	v_add_f32_dpp v53, v53, v53 row_ror:8 row_mask:0xf bank_mask:0xf
	s_nop 1
	v_add_f32_dpp v53, v53, v53 row_ror:4 row_mask:0xf bank_mask:0xf
	s_nop 1
	v_add_f32_dpp v53, v53, v53 quad_perm:[2,3,0,1] row_mask:0xf bank_mask:0xf
	s_nop 1
	v_add_f32_dpp v53, v53, v53 quad_perm:[1,0,3,2] row_mask:0xf bank_mask:0xf
	v_fmamk_f32 v53, v53, 0x3a800000, v31
	v_mul_f32_e32 v71, 0x4b800000, v53
	v_cmp_gt_f32_e32 vcc, s11, v53
	s_nop 1
	v_cndmask_b32_e32 v53, v53, v71, vcc
	v_rsq_f32_e32 v53, v53
	s_nop 0
	v_mul_f32_e32 v71, 0x45800000, v53
	v_cndmask_b32_e32 v108, v53, v71, vcc
	v_pk_mul_f32 v[88:89], v[104:105], v[108:109] op_sel_hi:[1,0]
	v_pk_mul_f32 v[90:91], v[102:103], v[108:109] op_sel_hi:[1,0]
	v_pk_mul_f32 v[88:89], v[0:1], v[88:89]
	v_pk_mul_f32 v[90:91], v[2:3], v[90:91]
	global_store_dwordx4 v[110:111], v[88:91], off nt
	s_nop 1
	v_pk_mul_f32 v[88:89], v[100:101], v[108:109] op_sel_hi:[1,0]
	v_pk_mul_f32 v[90:91], v[98:99], v[108:109] op_sel_hi:[1,0]
	v_pk_mul_f32 v[88:89], v[4:5], v[88:89]
	v_pk_mul_f32 v[90:91], v[6:7], v[90:91]
	global_store_dwordx4 v[110:111], v[88:91], off offset:1024 nt
	s_nop 1
	v_pk_mul_f32 v[88:89], v[96:97], v[108:109] op_sel_hi:[1,0]
	v_pk_mul_f32 v[90:91], v[94:95], v[108:109] op_sel_hi:[1,0]
	v_pk_mul_f32 v[88:89], v[8:9], v[88:89]
	v_pk_mul_f32 v[90:91], v[10:11], v[90:91]
	global_store_dwordx4 v[110:111], v[88:91], off offset:2048 nt
	s_nop 1
	v_pk_mul_f32 v[88:89], v[106:107], v[108:109] op_sel_hi:[1,0]
	v_pk_mul_f32 v[90:91], v[92:93], v[108:109] op_sel_hi:[1,0]
	v_pk_mul_f32 v[88:89], v[12:13], v[88:89]
	v_pk_mul_f32 v[90:91], v[14:15], v[90:91]
	global_store_dwordx4 v[110:111], v[88:91], off offset:3072 nt
.LBB0_1563:
	s_or_b64 exec, exec, s[6:7]
	v_add_u32_e32 v35, s33, v35
	v_cmp_gt_i32_e32 vcc, s8, v35
	s_and_saveexec_b64 s[6:7], vcc
	s_cbranch_execz .LBB0_1565
	s_waitcnt vmcnt(23)
	v_lshlrev_b32_e32 v88, 16, v86
	v_and_b32_e32 v89, 0xffff0000, v86
	v_lshlrev_b32_e32 v86, 16, v87
	v_and_b32_e32 v87, 0xffff0000, v87
	v_lshlrev_b32_e32 v90, 16, v84
	v_and_b32_e32 v91, 0xffff0000, v84
	v_lshlrev_b32_e32 v84, 16, v85
	v_and_b32_e32 v85, 0xffff0000, v85
	v_pk_add_f32 v[84:85], v[84:85], v[86:87]
	v_pk_add_f32 v[86:87], v[90:91], v[88:89]
	s_waitcnt vmcnt(22)
	v_lshlrev_b32_e32 v88, 16, v82
	v_and_b32_e32 v89, 0xffff0000, v82
	v_lshlrev_b32_e32 v82, 16, v83
	v_and_b32_e32 v83, 0xffff0000, v83
	v_lshlrev_b32_e32 v90, 16, v80
	v_and_b32_e32 v91, 0xffff0000, v80
	v_lshlrev_b32_e32 v80, 16, v81
	v_and_b32_e32 v81, 0xffff0000, v81
	v_pk_add_f32 v[80:81], v[80:81], v[82:83]
	v_pk_add_f32 v[82:83], v[90:91], v[88:89]
	s_waitcnt vmcnt(21)
	v_lshlrev_b32_e32 v88, 16, v78
	v_and_b32_e32 v89, 0xffff0000, v78
	v_lshlrev_b32_e32 v78, 16, v79
	v_and_b32_e32 v79, 0xffff0000, v79
	v_lshlrev_b32_e32 v90, 16, v76
	v_and_b32_e32 v91, 0xffff0000, v76
	v_lshlrev_b32_e32 v76, 16, v77
	v_and_b32_e32 v77, 0xffff0000, v77
	v_pk_add_f32 v[76:77], v[76:77], v[78:79]
	v_pk_add_f32 v[78:79], v[90:91], v[88:89]
	s_waitcnt vmcnt(20)
	v_lshlrev_b32_e32 v88, 16, v74
	v_and_b32_e32 v89, 0xffff0000, v74
	v_lshlrev_b32_e32 v90, 16, v72
	v_and_b32_e32 v91, 0xffff0000, v72
	v_lshlrev_b32_e32 v74, 16, v75
	v_and_b32_e32 v75, 0xffff0000, v75
	v_lshlrev_b32_e32 v72, 16, v73
	v_and_b32_e32 v73, 0xffff0000, v73
	v_pk_add_f32 v[88:89], v[90:91], v[88:89]
	v_mov_b32_e32 v90, v87
	v_mov_b32_e32 v91, v83
	v_pk_add_f32 v[74:75], v[72:73], v[74:75]
	v_mov_b32_e32 v72, v86
	v_mov_b32_e32 v73, v82
	v_pk_mul_f32 v[90:91], v[90:91], v[90:91]
	v_mov_b32_e32 v92, v79
	v_pk_fma_f32 v[72:73], v[72:73], v[72:73], v[90:91]
	v_mov_b32_e32 v90, v84
	v_mov_b32_e32 v91, v80
	v_pk_fma_f32 v[72:73], v[90:91], v[90:91], v[72:73]
	v_mov_b32_e32 v90, v85
	v_mov_b32_e32 v91, v81
	v_mov_b32_e32 v93, v89
	v_pk_fma_f32 v[72:73], v[90:91], v[90:91], v[72:73]
	v_mov_b32_e32 v90, v78
	v_mov_b32_e32 v91, v88
	v_pk_mul_f32 v[92:93], v[92:93], v[92:93]
	v_add_f32_e32 v53, v72, v73
	v_pk_fma_f32 v[90:91], v[90:91], v[90:91], v[92:93]
	v_mov_b32_e32 v92, v76
	v_mov_b32_e32 v93, v74
	v_pk_fma_f32 v[90:91], v[92:93], v[92:93], v[90:91]
	v_mov_b32_e32 v92, v77
	v_mov_b32_e32 v93, v75
	v_pk_fma_f32 v[90:91], v[92:93], v[92:93], v[90:91]
	s_nop 0
	v_add_f32_e32 v53, v53, v90
	v_add_f32_e32 v53, v53, v91
	v_mov_b32_e32 v71, v53
	s_nop 1
	v_permlane32_swap_b32_e32 v71, v53
	s_nop 1
	v_add_f32_e32 v53, v53, v71
	v_mov_b32_e32 v71, v53
	s_nop 1
	v_permlane16_swap_b32_e32 v71, v53
	s_nop 1
	v_add_f32_e32 v53, v53, v71
	s_nop 1
	v_add_f32_dpp v53, v53, v53 row_ror:8 row_mask:0xf bank_mask:0xf
	s_nop 1
	v_add_f32_dpp v53, v53, v53 row_ror:4 row_mask:0xf bank_mask:0xf
	s_nop 1
	v_add_f32_dpp v53, v53, v53 quad_perm:[2,3,0,1] row_mask:0xf bank_mask:0xf
	s_nop 1
	v_add_f32_dpp v53, v53, v53 quad_perm:[1,0,3,2] row_mask:0xf bank_mask:0xf
	v_fmamk_f32 v53, v53, 0x3a800000, v31
	v_mul_f32_e32 v71, 0x4b800000, v53
	v_cmp_gt_f32_e32 vcc, s11, v53
	s_nop 1
	v_cndmask_b32_e32 v53, v53, v71, vcc
	v_rsq_f32_e32 v53, v53
	v_ashrrev_i32_e32 v71, 31, v70
	v_lshlrev_b64 v[70:71], 12, v[70:71]
	v_lshl_add_u64 v[92:93], v[20:21], 0, v[70:71]
	v_mul_f32_e32 v72, 0x45800000, v53
	v_cndmask_b32_e32 v90, v53, v72, vcc
	v_pk_mul_f32 v[70:71], v[86:87], v[90:91] op_sel_hi:[1,0]
	v_pk_mul_f32 v[72:73], v[84:85], v[90:91] op_sel_hi:[1,0]
	v_pk_mul_f32 v[70:71], v[0:1], v[70:71]
	v_pk_mul_f32 v[72:73], v[2:3], v[72:73]
	global_store_dwordx4 v[92:93], v[70:73], off nt
	s_nop 1
	v_pk_mul_f32 v[70:71], v[82:83], v[90:91] op_sel_hi:[1,0]
	v_pk_mul_f32 v[72:73], v[80:81], v[90:91] op_sel_hi:[1,0]
	v_pk_mul_f32 v[70:71], v[4:5], v[70:71]
	v_pk_mul_f32 v[72:73], v[6:7], v[72:73]
	global_store_dwordx4 v[92:93], v[70:73], off offset:1024 nt
	s_nop 1
	v_pk_mul_f32 v[70:71], v[78:79], v[90:91] op_sel_hi:[1,0]
	v_pk_mul_f32 v[72:73], v[76:77], v[90:91] op_sel_hi:[1,0]
	v_pk_mul_f32 v[70:71], v[8:9], v[70:71]
	v_pk_mul_f32 v[72:73], v[10:11], v[72:73]
	global_store_dwordx4 v[92:93], v[70:73], off offset:2048 nt
	s_nop 1
	v_pk_mul_f32 v[70:71], v[88:89], v[90:91] op_sel_hi:[1,0]
	v_pk_mul_f32 v[72:73], v[74:75], v[90:91] op_sel_hi:[1,0]
	v_pk_mul_f32 v[70:71], v[12:13], v[70:71]
	v_pk_mul_f32 v[72:73], v[14:15], v[72:73]
	global_store_dwordx4 v[92:93], v[70:73], off offset:3072 nt
.LBB0_1565:
	s_or_b64 exec, exec, s[6:7]
	v_add_u32_e32 v35, s33, v35
	v_cmp_gt_i32_e32 vcc, s8, v35
	s_and_saveexec_b64 s[6:7], vcc
	s_cbranch_execz .LBB0_1567
	s_waitcnt vmcnt(15)
	v_lshlrev_b32_e32 v70, 16, v68
	v_and_b32_e32 v71, 0xffff0000, v68
	v_lshlrev_b32_e32 v68, 16, v69
	v_and_b32_e32 v69, 0xffff0000, v69
	v_lshlrev_b32_e32 v72, 16, v66
	v_and_b32_e32 v73, 0xffff0000, v66
	v_lshlrev_b32_e32 v66, 16, v67
	v_and_b32_e32 v67, 0xffff0000, v67
	v_pk_add_f32 v[66:67], v[66:67], v[68:69]
	v_pk_add_f32 v[68:69], v[72:73], v[70:71]
	s_waitcnt vmcnt(14)
	v_lshlrev_b32_e32 v70, 16, v64
	v_and_b32_e32 v71, 0xffff0000, v64
	v_lshlrev_b32_e32 v64, 16, v65
	v_and_b32_e32 v65, 0xffff0000, v65
	v_lshlrev_b32_e32 v72, 16, v62
	v_and_b32_e32 v73, 0xffff0000, v62
	v_lshlrev_b32_e32 v62, 16, v63
	v_and_b32_e32 v63, 0xffff0000, v63
	v_pk_add_f32 v[62:63], v[62:63], v[64:65]
	v_pk_add_f32 v[64:65], v[72:73], v[70:71]
	s_waitcnt vmcnt(13)
	v_lshlrev_b32_e32 v70, 16, v60
	v_and_b32_e32 v71, 0xffff0000, v60
	v_lshlrev_b32_e32 v60, 16, v61
	v_and_b32_e32 v61, 0xffff0000, v61
	v_lshlrev_b32_e32 v72, 16, v58
	v_and_b32_e32 v73, 0xffff0000, v58
	v_lshlrev_b32_e32 v58, 16, v59
	v_and_b32_e32 v59, 0xffff0000, v59
	v_pk_add_f32 v[58:59], v[58:59], v[60:61]
	v_pk_add_f32 v[60:61], v[72:73], v[70:71]
	s_waitcnt vmcnt(12)
	v_lshlrev_b32_e32 v70, 16, v56
	v_and_b32_e32 v71, 0xffff0000, v56
	v_lshlrev_b32_e32 v72, 16, v54
	v_and_b32_e32 v73, 0xffff0000, v54
	v_lshlrev_b32_e32 v56, 16, v57
	v_and_b32_e32 v57, 0xffff0000, v57
	v_lshlrev_b32_e32 v54, 16, v55
	v_and_b32_e32 v55, 0xffff0000, v55
	v_pk_add_f32 v[70:71], v[72:73], v[70:71]
	v_mov_b32_e32 v72, v69
	v_mov_b32_e32 v73, v65
	v_pk_add_f32 v[56:57], v[54:55], v[56:57]
	v_mov_b32_e32 v54, v68
	v_mov_b32_e32 v55, v64
	v_pk_mul_f32 v[72:73], v[72:73], v[72:73]
	v_mov_b32_e32 v74, v61
	v_pk_fma_f32 v[54:55], v[54:55], v[54:55], v[72:73]
	v_mov_b32_e32 v72, v66
	v_mov_b32_e32 v73, v62
	v_pk_fma_f32 v[54:55], v[72:73], v[72:73], v[54:55]
	v_mov_b32_e32 v72, v67
	v_mov_b32_e32 v73, v63
	v_mov_b32_e32 v75, v71
	v_pk_fma_f32 v[54:55], v[72:73], v[72:73], v[54:55]
	v_mov_b32_e32 v72, v60
	v_mov_b32_e32 v73, v70
	v_pk_mul_f32 v[74:75], v[74:75], v[74:75]
	v_add_f32_e32 v53, v54, v55
	v_pk_fma_f32 v[72:73], v[72:73], v[72:73], v[74:75]
	v_mov_b32_e32 v74, v58
	v_mov_b32_e32 v75, v56
	v_pk_fma_f32 v[72:73], v[74:75], v[74:75], v[72:73]
	v_mov_b32_e32 v74, v59
	v_mov_b32_e32 v75, v57
	v_pk_fma_f32 v[72:73], v[74:75], v[74:75], v[72:73]
	s_nop 0
	v_add_f32_e32 v53, v53, v72
	v_add_f32_e32 v53, v53, v73
	v_mov_b32_e32 v54, v53
	s_nop 1
	v_permlane32_swap_b32_e32 v54, v53
	s_nop 1
	v_add_f32_e32 v53, v53, v54
	v_mov_b32_e32 v54, v53
	s_nop 1
	v_permlane16_swap_b32_e32 v54, v53
	s_nop 1
	v_add_f32_e32 v53, v53, v54
	s_nop 1
	v_add_f32_dpp v53, v53, v53 row_ror:8 row_mask:0xf bank_mask:0xf
	s_nop 1
	v_add_f32_dpp v53, v53, v53 row_ror:4 row_mask:0xf bank_mask:0xf
	s_nop 1
	v_add_f32_dpp v53, v53, v53 quad_perm:[2,3,0,1] row_mask:0xf bank_mask:0xf
	s_nop 1
	v_add_f32_dpp v53, v53, v53 quad_perm:[1,0,3,2] row_mask:0xf bank_mask:0xf
	v_fmamk_f32 v53, v53, 0x3a800000, v31
	v_mul_f32_e32 v54, 0x4b800000, v53
	v_cmp_gt_f32_e32 vcc, s11, v53
	s_nop 1
	v_cndmask_b32_e32 v53, v53, v54, vcc
	v_rsq_f32_e32 v54, v53
	v_ashrrev_i32_e32 v53, 31, v52
	v_lshlrev_b64 v[52:53], 12, v[52:53]
	v_lshl_add_u64 v[74:75], v[20:21], 0, v[52:53]
	v_mul_f32_e32 v55, 0x45800000, v54
	v_cndmask_b32_e32 v72, v54, v55, vcc
	v_pk_mul_f32 v[52:53], v[68:69], v[72:73] op_sel_hi:[1,0]
	v_pk_mul_f32 v[54:55], v[66:67], v[72:73] op_sel_hi:[1,0]
	v_pk_mul_f32 v[52:53], v[0:1], v[52:53]
	v_pk_mul_f32 v[54:55], v[2:3], v[54:55]
	global_store_dwordx4 v[74:75], v[52:55], off nt
	s_nop 1
	v_pk_mul_f32 v[52:53], v[64:65], v[72:73] op_sel_hi:[1,0]
	v_pk_mul_f32 v[54:55], v[62:63], v[72:73] op_sel_hi:[1,0]
	v_pk_mul_f32 v[52:53], v[4:5], v[52:53]
	v_pk_mul_f32 v[54:55], v[6:7], v[54:55]
	global_store_dwordx4 v[74:75], v[52:55], off offset:1024 nt
	s_nop 1
	v_pk_mul_f32 v[52:53], v[60:61], v[72:73] op_sel_hi:[1,0]
	v_pk_mul_f32 v[54:55], v[58:59], v[72:73] op_sel_hi:[1,0]
	v_pk_mul_f32 v[52:53], v[8:9], v[52:53]
	v_pk_mul_f32 v[54:55], v[10:11], v[54:55]
	global_store_dwordx4 v[74:75], v[52:55], off offset:2048 nt
	s_nop 1
	v_pk_mul_f32 v[52:53], v[70:71], v[72:73] op_sel_hi:[1,0]
	v_pk_mul_f32 v[54:55], v[56:57], v[72:73] op_sel_hi:[1,0]
	v_pk_mul_f32 v[52:53], v[12:13], v[52:53]
	v_pk_mul_f32 v[54:55], v[14:15], v[54:55]
	global_store_dwordx4 v[74:75], v[52:55], off offset:3072 nt
.LBB0_1567:
	s_or_b64 exec, exec, s[6:7]
	s_nop 0
	v_add_u32_e32 v52, s33, v35
	v_cmp_gt_i32_e32 vcc, s8, v52
	s_and_saveexec_b64 s[6:7], vcc
	s_cbranch_execz .LBB0_1558
	s_waitcnt vmcnt(7)
	v_lshlrev_b32_e32 v54, 16, v50
	v_and_b32_e32 v55, 0xffff0000, v50
	v_lshlrev_b32_e32 v50, 16, v51
	v_and_b32_e32 v51, 0xffff0000, v51
	v_lshlrev_b32_e32 v56, 16, v48
	v_and_b32_e32 v57, 0xffff0000, v48
	v_lshlrev_b32_e32 v48, 16, v49
	v_and_b32_e32 v49, 0xffff0000, v49
	v_pk_add_f32 v[48:49], v[48:49], v[50:51]
	v_pk_add_f32 v[50:51], v[56:57], v[54:55]
	s_waitcnt vmcnt(6)
	v_lshlrev_b32_e32 v54, 16, v46
	v_and_b32_e32 v55, 0xffff0000, v46
	v_lshlrev_b32_e32 v46, 16, v47
	v_and_b32_e32 v47, 0xffff0000, v47
	v_lshlrev_b32_e32 v56, 16, v44
	v_and_b32_e32 v57, 0xffff0000, v44
	v_lshlrev_b32_e32 v44, 16, v45
	v_and_b32_e32 v45, 0xffff0000, v45
	v_pk_add_f32 v[44:45], v[44:45], v[46:47]
	v_pk_add_f32 v[46:47], v[56:57], v[54:55]
	s_waitcnt vmcnt(5)
	v_lshlrev_b32_e32 v54, 16, v42
	v_and_b32_e32 v55, 0xffff0000, v42
	v_lshlrev_b32_e32 v42, 16, v43
	v_and_b32_e32 v43, 0xffff0000, v43
	v_lshlrev_b32_e32 v56, 16, v40
	v_and_b32_e32 v57, 0xffff0000, v40
	v_lshlrev_b32_e32 v40, 16, v41
	v_and_b32_e32 v41, 0xffff0000, v41
	v_pk_add_f32 v[40:41], v[40:41], v[42:43]
	v_pk_add_f32 v[42:43], v[56:57], v[54:55]
	s_waitcnt vmcnt(4)
	v_lshlrev_b32_e32 v54, 16, v38
	v_and_b32_e32 v55, 0xffff0000, v38
	v_lshlrev_b32_e32 v56, 16, v36
	v_and_b32_e32 v57, 0xffff0000, v36
	v_lshlrev_b32_e32 v38, 16, v39
	v_and_b32_e32 v39, 0xffff0000, v39
	v_lshlrev_b32_e32 v36, 16, v37
	v_and_b32_e32 v37, 0xffff0000, v37
	v_pk_add_f32 v[54:55], v[56:57], v[54:55]
	v_mov_b32_e32 v56, v51
	v_mov_b32_e32 v57, v47
	v_pk_add_f32 v[38:39], v[36:37], v[38:39]
	v_mov_b32_e32 v36, v50
	v_mov_b32_e32 v37, v46
	v_pk_mul_f32 v[56:57], v[56:57], v[56:57]
	v_mov_b32_e32 v58, v43
	v_pk_fma_f32 v[36:37], v[36:37], v[36:37], v[56:57]
	v_mov_b32_e32 v56, v48
	v_mov_b32_e32 v57, v44
	v_pk_fma_f32 v[36:37], v[56:57], v[56:57], v[36:37]
	v_mov_b32_e32 v56, v49
	v_mov_b32_e32 v57, v45
	v_mov_b32_e32 v59, v55
	v_pk_fma_f32 v[36:37], v[56:57], v[56:57], v[36:37]
	v_mov_b32_e32 v56, v42
	v_mov_b32_e32 v57, v54
	v_pk_mul_f32 v[58:59], v[58:59], v[58:59]
	v_add_f32_e32 v35, v36, v37
	v_pk_fma_f32 v[56:57], v[56:57], v[56:57], v[58:59]
	v_mov_b32_e32 v58, v40
	v_mov_b32_e32 v59, v38
	v_pk_fma_f32 v[56:57], v[58:59], v[58:59], v[56:57]
	v_mov_b32_e32 v58, v41
	v_mov_b32_e32 v59, v39
	v_pk_fma_f32 v[56:57], v[58:59], v[58:59], v[56:57]
	s_nop 0
	v_add_f32_e32 v35, v35, v56
	v_add_f32_e32 v35, v35, v57
	v_mov_b32_e32 v36, v35
	s_nop 1
	v_permlane32_swap_b32_e32 v36, v35
	s_nop 1
	v_add_f32_e32 v35, v35, v36
	v_mov_b32_e32 v36, v35
	s_nop 1
	v_permlane16_swap_b32_e32 v36, v35
	s_nop 1
	v_add_f32_e32 v35, v35, v36
	s_nop 1
	v_add_f32_dpp v35, v35, v35 row_ror:8 row_mask:0xf bank_mask:0xf
	s_nop 1
	v_add_f32_dpp v35, v35, v35 row_ror:4 row_mask:0xf bank_mask:0xf
	s_nop 1
	v_add_f32_dpp v35, v35, v35 quad_perm:[2,3,0,1] row_mask:0xf bank_mask:0xf
	s_nop 1
	v_add_f32_dpp v35, v35, v35 quad_perm:[1,0,3,2] row_mask:0xf bank_mask:0xf
	v_fmamk_f32 v35, v35, 0x3a800000, v31
	v_mul_f32_e32 v36, 0x4b800000, v35
	v_cmp_gt_f32_e32 vcc, s11, v35
	s_nop 1
	v_cndmask_b32_e32 v35, v35, v36, vcc
	v_rsq_f32_e32 v36, v35
	v_ashrrev_i32_e32 v35, 31, v34
	v_lshlrev_b64 v[34:35], 12, v[34:35]
	v_lshl_add_u64 v[58:59], v[20:21], 0, v[34:35]
	v_mul_f32_e32 v37, 0x45800000, v36
	v_cndmask_b32_e32 v56, v36, v37, vcc
	v_pk_mul_f32 v[34:35], v[50:51], v[56:57] op_sel_hi:[1,0]
	v_pk_mul_f32 v[36:37], v[48:49], v[56:57] op_sel_hi:[1,0]
	v_pk_mul_f32 v[34:35], v[0:1], v[34:35]
	v_pk_mul_f32 v[36:37], v[2:3], v[36:37]
	global_store_dwordx4 v[58:59], v[34:37], off nt
	s_nop 1
	v_pk_mul_f32 v[34:35], v[46:47], v[56:57] op_sel_hi:[1,0]
	v_pk_mul_f32 v[36:37], v[44:45], v[56:57] op_sel_hi:[1,0]
	v_pk_mul_f32 v[34:35], v[4:5], v[34:35]
	v_pk_mul_f32 v[36:37], v[6:7], v[36:37]
	global_store_dwordx4 v[58:59], v[34:37], off offset:1024 nt
	s_nop 1
	v_pk_mul_f32 v[34:35], v[42:43], v[56:57] op_sel_hi:[1,0]
	v_pk_mul_f32 v[36:37], v[40:41], v[56:57] op_sel_hi:[1,0]
	v_pk_mul_f32 v[34:35], v[8:9], v[34:35]
	v_pk_mul_f32 v[36:37], v[10:11], v[36:37]
	global_store_dwordx4 v[58:59], v[34:37], off offset:2048 nt
	s_nop 1
	v_pk_mul_f32 v[34:35], v[54:55], v[56:57] op_sel_hi:[1,0]
	v_pk_mul_f32 v[36:37], v[38:39], v[56:57] op_sel_hi:[1,0]
	v_pk_mul_f32 v[34:35], v[12:13], v[34:35]
	v_pk_mul_f32 v[36:37], v[14:15], v[36:37]
	global_store_dwordx4 v[58:59], v[34:37], off offset:3072 nt
	s_branch .LBB0_1558
